# GEMM phases: scalar/address instructions between the last MFMA of a block and the hand-off s_barrier moved into the block's MFMA shadow (barrier directly follows the last MFMA)
# speedup vs baseline: 1.0079x; 1.0038x over previous
; #define STG(P, GB) do { const char* _gb = (GB); \
;     _Pragma("unroll") for (int _i = 0; _i < 2; ++_i) { \
;       __builtin_amdgcn_global_load_lds((const unsigned*)(_gb + voff[_i]), \
;         (LAS unsigned*)((LAS char*)(P) + ldsw + _i * 8192), 16, 0, 0); } } while (0)
; #define LDA(dst, b, h) _Pragma("unroll") for (int m = 0; m < 4; ++m) _Pragma("unroll") for (int k = 0; k < 2; ++k) \
;     dst[m][k] = *(const LAS bf16x8*)((LAS char*)SA(b, h) + aoff + m * 2048 + k * 1024)
; #define LDB(dst, b, h) _Pragma("unroll") for (int n = 0; n < 2; ++n) _Pragma("unroll") for (int k = 0; k < 2; ++k) \
;     dst[n][k] = *(const LAS bf16x8*)((LAS char*)SB(b, h) + boff + n * 2048 + k * 1024)
; #define MMA(ai, bj, At_, Bt_) do { __builtin_amdgcn_s_setprio(1); \
;     _Pragma("unroll") for (int m = 0; m < 4; ++m) _Pragma("unroll") for (int n = 0; n < 2; ++n) _Pragma("unroll") for (int k = 0; k < 2; ++k) \
;       acc[ai][bj][m][n] = __builtin_amdgcn_mfma_f32_16x16x32_bf16(Bt_[n][k], At_[m][k], acc[ai][bj][m][n], 0, 0, 0); \
;     __builtin_amdgcn_s_setprio(0); } while (0)
; #define WAIT_L(n) asm volatile("s_waitcnt lgkmcnt(" #n ")" ::: "memory")
; #define BAR __builtin_amdgcn_s_barrier()
; #define SCHED __builtin_amdgcn_sched_barrier(0)
; __device__ __forceinline__ void gemm_phase(const bf16_t* __restrict__ A, const bf16_t* __restrict__ Bt, bf16_t* __restrict__ C, int M, int N, int K,
;                                            int ldc, const int EPI, char* smem, const int wid_u) {
;     ...
;       LDB(B0, 0, 0); SCHED; LDA(At, 0, 0); STG(SA(1, 1), a1 + hstep);
;       WAIT_L(8); BAR; WAIT_L(0); MMA(0, 0, At, B0); BAR; SCHED;
;       LDB(B1, 0, 1); STG(SB(0, 0), b2);
;       BAR; WAIT_L(0); MMA(0, 1, At, B1); BAR;
;       LDA(At, 0, 1); STG(SA(0, 0), a2);
;       BAR; WAIT_L(0); MMA(1, 0, At, B0); BAR; SCHED;
.LBB0_145:
	ds_read_b128 v[150:153], v146
	ds_read_b128 v[154:157], v146 offset:1024
	ds_read_b128 v[158:161], v146 offset:2048
	ds_read_b128 v[162:165], v146 offset:3072
	s_add_u32 s18, s16, 0x100
	s_addc_u32 s19, s17, 0
	s_cmp_eq_u32 s49, 12
	s_cselect_b32 s23, s44, s19
	s_cselect_b32 s22, s45, s18
	s_cselect_b32 s21, s11, s48
	s_cselect_b32 s20, s46, s47
	v_lshl_add_u64 v[142:143], s[16:17], 0, v[136:137]
	s_add_i32 m0, s28, 0xc000
	ds_read_b128 v[166:169], v147
	ds_read_b128 v[170:173], v147 offset:1024
	ds_read_b128 v[174:177], v147 offset:2048
	ds_read_b128 v[178:181], v147 offset:3072
	ds_read_b128 v[182:185], v147 offset:4096
	ds_read_b128 v[186:189], v147 offset:5120
	ds_read_b128 v[190:193], v147 offset:6144
	ds_read_b128 v[194:197], v147 offset:7168
	global_load_lds_dwordx4 v[142:143], off
	v_lshl_add_u64 v[142:143], s[16:17], 0, v[134:135]
	s_add_i32 m0, s28, 0xe000
	s_nop 0
	global_load_lds_dwordx4 v[142:143], off
	s_waitcnt lgkmcnt(8)
	s_barrier
	s_waitcnt lgkmcnt(0)
	s_waitcnt lgkmcnt(0)
	v_mfma_f32_16x16x32_bf16 v[124:127], v[150:153], v[166:169], v[124:127]
	v_mfma_f32_16x16x32_bf16 v[120:123], v[158:161], v[166:169], v[120:123]
	v_mfma_f32_16x16x32_bf16 v[108:111], v[150:153], v[174:177], v[108:111]
	v_mfma_f32_16x16x32_bf16 v[104:107], v[158:161], v[174:177], v[104:107]
	v_mfma_f32_16x16x32_bf16 v[92:95], v[150:153], v[182:185], v[92:95]
	v_mfma_f32_16x16x32_bf16 v[88:91], v[158:161], v[182:185], v[88:91]
	v_mfma_f32_16x16x32_bf16 v[76:79], v[150:153], v[190:193], v[76:79]
	v_mfma_f32_16x16x32_bf16 v[72:75], v[158:161], v[190:193], v[72:75]
	v_mfma_f32_16x16x32_bf16 v[124:127], v[154:157], v[170:173], v[124:127]
	v_mfma_f32_16x16x32_bf16 v[120:123], v[162:165], v[170:173], v[120:123]
	v_mfma_f32_16x16x32_bf16 v[108:111], v[154:157], v[178:181], v[108:111]
	v_mfma_f32_16x16x32_bf16 v[104:107], v[162:165], v[178:181], v[104:107]
	v_mfma_f32_16x16x32_bf16 v[92:95], v[154:157], v[186:189], v[92:95]
	v_mfma_f32_16x16x32_bf16 v[88:91], v[162:165], v[186:189], v[88:91]
	v_mfma_f32_16x16x32_bf16 v[76:79], v[154:157], v[194:197], v[76:79]
	v_mfma_f32_16x16x32_bf16 v[72:75], v[162:165], v[194:197], v[72:75]
	s_barrier
	s_add_i32 s16, s36, s27
	v_lshl_add_u64 v[142:143], s[20:21], 0, v[130:131]
	s_mov_b32 m0, s16
	ds_read_b128 v[198:201], v148
	ds_read_b128 v[202:205], v148 offset:1024
	ds_read_b128 v[206:209], v148 offset:2048
	ds_read_b128 v[210:213], v148 offset:3072
	global_load_lds_dwordx4 v[142:143], off
	v_lshl_add_u64 v[214:215], s[20:21], 0, v[128:129]
	s_add_i32 m0, s16, 0x2000
	s_nop 0
	global_load_lds_dwordx4 v[214:215], off
	s_barrier
	s_waitcnt lgkmcnt(0)
	s_waitcnt lgkmcnt(0)
	v_mfma_f32_16x16x32_bf16 v[116:119], v[198:201], v[166:169], v[116:119]
	v_mfma_f32_16x16x32_bf16 v[112:115], v[206:209], v[166:169], v[112:115]
	v_mfma_f32_16x16x32_bf16 v[100:103], v[198:201], v[174:177], v[100:103]
	v_mfma_f32_16x16x32_bf16 v[96:99], v[206:209], v[174:177], v[96:99]
	v_mfma_f32_16x16x32_bf16 v[84:87], v[198:201], v[182:185], v[84:87]
	v_mfma_f32_16x16x32_bf16 v[80:83], v[206:209], v[182:185], v[80:83]
	v_mfma_f32_16x16x32_bf16 v[68:71], v[198:201], v[190:193], v[68:71]
	v_mfma_f32_16x16x32_bf16 v[64:67], v[206:209], v[190:193], v[64:67]
	v_mfma_f32_16x16x32_bf16 v[116:119], v[202:205], v[170:173], v[116:119]
	v_mfma_f32_16x16x32_bf16 v[112:115], v[210:213], v[170:173], v[112:115]
	v_mfma_f32_16x16x32_bf16 v[100:103], v[202:205], v[178:181], v[100:103]
	v_mfma_f32_16x16x32_bf16 v[96:99], v[210:213], v[178:181], v[96:99]
	v_mfma_f32_16x16x32_bf16 v[84:87], v[202:205], v[186:189], v[84:87]
	v_mfma_f32_16x16x32_bf16 v[80:83], v[210:213], v[186:189], v[80:83]
	s_mov_b32 m0, s28
	v_lshl_add_u64 v[216:217], s[22:23], 0, v[130:131]
	v_mfma_f32_16x16x32_bf16 v[68:71], v[202:205], v[194:197], v[68:71]
	v_mfma_f32_16x16x32_bf16 v[64:67], v[210:213], v[194:197], v[64:67]
	s_barrier
	ds_read_b128 v[166:169], v147 offset:16384
	ds_read_b128 v[170:173], v147 offset:17408
	ds_read_b128 v[174:177], v147 offset:18432
	ds_read_b128 v[178:181], v147 offset:19456
	ds_read_b128 v[182:185], v147 offset:20480
	ds_read_b128 v[186:189], v147 offset:21504
	ds_read_b128 v[190:193], v147 offset:22528
	ds_read_b128 v[194:197], v147 offset:23552
	global_load_lds_dwordx4 v[216:217], off
	v_lshl_add_u64 v[218:219], s[22:23], 0, v[128:129]
	s_mov_b32 m0, s29
	s_nop 0
	global_load_lds_dwordx4 v[218:219], off
	s_barrier
	s_waitcnt lgkmcnt(0)
	s_waitcnt lgkmcnt(0)
	v_mfma_f32_16x16x32_bf16 v[60:63], v[150:153], v[166:169], v[60:63]
	v_mfma_f32_16x16x32_bf16 v[56:59], v[158:161], v[166:169], v[56:59]
	v_mfma_f32_16x16x32_bf16 v[44:47], v[150:153], v[174:177], v[44:47]
	v_mfma_f32_16x16x32_bf16 v[40:43], v[158:161], v[174:177], v[40:43]
	v_mfma_f32_16x16x32_bf16 v[28:31], v[150:153], v[182:185], v[28:31]
	v_mfma_f32_16x16x32_bf16 v[24:27], v[158:161], v[182:185], v[24:27]
	v_mfma_f32_16x16x32_bf16 v[12:15], v[150:153], v[190:193], v[12:15]
	v_mfma_f32_16x16x32_bf16 v[8:11], v[158:161], v[190:193], v[8:11]
	v_mfma_f32_16x16x32_bf16 v[60:63], v[154:157], v[170:173], v[60:63]
	v_mfma_f32_16x16x32_bf16 v[56:59], v[162:165], v[170:173], v[56:59]
	v_mfma_f32_16x16x32_bf16 v[44:47], v[154:157], v[178:181], v[44:47]
	v_mfma_f32_16x16x32_bf16 v[40:43], v[162:165], v[178:181], v[40:43]
	v_mfma_f32_16x16x32_bf16 v[28:31], v[154:157], v[186:189], v[28:31]
	v_mfma_f32_16x16x32_bf16 v[24:27], v[162:165], v[186:189], v[24:27]
	v_mfma_f32_16x16x32_bf16 v[12:15], v[154:157], v[194:197], v[12:15]
	v_mfma_f32_16x16x32_bf16 v[8:11], v[162:165], v[194:197], v[8:11]
	s_barrier
; #define STG(P, GB) do { const char* _gb = (GB); \
;     _Pragma("unroll") for (int _i = 0; _i < 2; ++_i) { \
;       __builtin_amdgcn_global_load_lds((const unsigned*)(_gb + voff[_i]), \
;         (LAS unsigned*)((LAS char*)(P) + ldsw + _i * 8192), 16, 0, 0); } } while (0)
; #define LDA(dst, b, h) _Pragma("unroll") for (int m = 0; m < 4; ++m) _Pragma("unroll") for (int k = 0; k < 2; ++k) \
;     dst[m][k] = *(const LAS bf16x8*)((LAS char*)SA(b, h) + aoff + m * 2048 + k * 1024)
; #define LDB(dst, b, h) _Pragma("unroll") for (int n = 0; n < 2; ++n) _Pragma("unroll") for (int k = 0; k < 2; ++k) \
;     dst[n][k] = *(const LAS bf16x8*)((LAS char*)SB(b, h) + boff + n * 2048 + k * 1024)
; #define MMA(ai, bj, At_, Bt_) do { __builtin_amdgcn_s_setprio(1); \
;     _Pragma("unroll") for (int m = 0; m < 4; ++m) _Pragma("unroll") for (int n = 0; n < 2; ++n) _Pragma("unroll") for (int k = 0; k < 2; ++k) \
;       acc[ai][bj][m][n] = __builtin_amdgcn_mfma_f32_16x16x32_bf16(Bt_[n][k], At_[m][k], acc[ai][bj][m][n], 0, 0, 0); \
;     __builtin_amdgcn_s_setprio(0); } while (0)
; #define WAIT_V(n) asm volatile("s_waitcnt vmcnt(" #n ")" ::: "memory")
; #define WAIT_L(n) asm volatile("s_waitcnt lgkmcnt(" #n ")" ::: "memory")
; #define BAR __builtin_amdgcn_s_barrier()
; #define SCHED __builtin_amdgcn_sched_barrier(0)
; __device__ __forceinline__ void gemm_phase(const bf16_t* __restrict__ A, const bf16_t* __restrict__ Bt, bf16_t* __restrict__ C, int M, int N, int K,
;                                            int ldc, const int EPI, char* smem, const int wid_u) {
;     ...
;       STG(SB(0, 1), b2 + hstep);
;       WAIT_V(6); BAR; MMA(1, 1, At, B1); BAR;
;       LDB(B0, 1, 0); SCHED; LDA(At, 1, 0); STG(SA(0, 1), a2 + hstep);
;       WAIT_L(8); BAR; WAIT_L(0); MMA(0, 0, At, B0); BAR; SCHED;
;       LDB(B1, 1, 1); STG(SB(1, 0), b3);
;       BAR; WAIT_L(0); MMA(0, 1, At, B1); BAR;
;       LDA(At, 1, 1); STG(SA(1, 0), a3);
	s_add_u32 s16, s20, 0x40000
	s_addc_u32 s17, s21, 0
	s_add_i32 s50, s37, s27
	v_lshl_add_u64 v[150:151], s[16:17], 0, v[130:131]
	s_mov_b32 m0, s50
	s_nop 0
	global_load_lds_dwordx4 v[150:151], off
	v_lshl_add_u64 v[150:151], s[16:17], 0, v[128:129]
	s_add_i32 m0, s50, 0x2000
	s_nop 0
	global_load_lds_dwordx4 v[150:151], off
	s_waitcnt vmcnt(6)
	s_barrier
	v_mfma_f32_16x16x32_bf16 v[52:55], v[198:201], v[166:169], v[52:55]
	v_mfma_f32_16x16x32_bf16 v[48:51], v[206:209], v[166:169], v[48:51]
	v_mfma_f32_16x16x32_bf16 v[36:39], v[198:201], v[174:177], v[36:39]
	v_mfma_f32_16x16x32_bf16 v[32:35], v[206:209], v[174:177], v[32:35]
	v_mfma_f32_16x16x32_bf16 v[20:23], v[198:201], v[182:185], v[20:23]
	v_mfma_f32_16x16x32_bf16 v[16:19], v[206:209], v[182:185], v[16:19]
	v_mfma_f32_16x16x32_bf16 v[4:7], v[198:201], v[190:193], v[4:7]
	v_mfma_f32_16x16x32_bf16 v[0:3], v[206:209], v[190:193], v[0:3]
	v_mfma_f32_16x16x32_bf16 v[52:55], v[202:205], v[170:173], v[52:55]
	v_mfma_f32_16x16x32_bf16 v[48:51], v[210:213], v[170:173], v[48:51]
	v_mfma_f32_16x16x32_bf16 v[36:39], v[202:205], v[178:181], v[36:39]
	v_mfma_f32_16x16x32_bf16 v[32:35], v[210:213], v[178:181], v[32:35]
	v_mfma_f32_16x16x32_bf16 v[20:23], v[202:205], v[186:189], v[20:23]
	v_mfma_f32_16x16x32_bf16 v[16:19], v[210:213], v[186:189], v[16:19]
	s_add_i32 s50, 0, 0x18000
	v_add_u32_e32 v149, s50, v145
	v_mfma_f32_16x16x32_bf16 v[4:7], v[202:205], v[194:197], v[4:7]
	v_mfma_f32_16x16x32_bf16 v[0:3], v[210:213], v[194:197], v[0:3]
	s_barrier
	ds_read_b128 v[150:153], v149
	ds_read_b128 v[154:157], v149 offset:1024
	ds_read_b128 v[158:161], v149 offset:2048
	ds_read_b128 v[162:165], v149 offset:3072
	s_add_u32 s16, s22, 0x40000
	s_addc_u32 s17, s23, 0
	s_mov_b32 m0, s30
	v_lshl_add_u64 v[198:199], s[16:17], 0, v[130:131]
	ds_read_b128 v[166:169], v147 offset:32768
	ds_read_b128 v[170:173], v147 offset:33792
	ds_read_b128 v[174:177], v147 offset:34816
	ds_read_b128 v[178:181], v147 offset:35840
	ds_read_b128 v[182:185], v147 offset:36864
	ds_read_b128 v[186:189], v147 offset:37888
	ds_read_b128 v[190:193], v147 offset:38912
	ds_read_b128 v[194:197], v147 offset:39936
	global_load_lds_dwordx4 v[198:199], off
	v_lshl_add_u64 v[198:199], s[16:17], 0, v[128:129]
	s_mov_b32 m0, s31
	s_nop 0
	global_load_lds_dwordx4 v[198:199], off
	s_waitcnt lgkmcnt(8)
	s_barrier
	s_waitcnt lgkmcnt(0)
	s_waitcnt lgkmcnt(0)
	v_mfma_f32_16x16x32_bf16 v[124:127], v[150:153], v[166:169], v[124:127]
	v_mfma_f32_16x16x32_bf16 v[120:123], v[158:161], v[166:169], v[120:123]
	v_mfma_f32_16x16x32_bf16 v[108:111], v[150:153], v[174:177], v[108:111]
	v_mfma_f32_16x16x32_bf16 v[104:107], v[158:161], v[174:177], v[104:107]
	v_mfma_f32_16x16x32_bf16 v[92:95], v[150:153], v[182:185], v[92:95]
	v_mfma_f32_16x16x32_bf16 v[88:91], v[158:161], v[182:185], v[88:91]
	v_mfma_f32_16x16x32_bf16 v[76:79], v[150:153], v[190:193], v[76:79]
	v_mfma_f32_16x16x32_bf16 v[72:75], v[158:161], v[190:193], v[72:75]
	v_mfma_f32_16x16x32_bf16 v[124:127], v[154:157], v[170:173], v[124:127]
	v_mfma_f32_16x16x32_bf16 v[120:123], v[162:165], v[170:173], v[120:123]
	v_mfma_f32_16x16x32_bf16 v[108:111], v[154:157], v[178:181], v[108:111]
	v_mfma_f32_16x16x32_bf16 v[104:107], v[162:165], v[178:181], v[104:107]
	v_mfma_f32_16x16x32_bf16 v[92:95], v[154:157], v[186:189], v[92:95]
	v_mfma_f32_16x16x32_bf16 v[88:91], v[162:165], v[186:189], v[88:91]
	v_mfma_f32_16x16x32_bf16 v[76:79], v[154:157], v[194:197], v[76:79]
	v_mfma_f32_16x16x32_bf16 v[72:75], v[162:165], v[194:197], v[72:75]
	s_barrier
	s_add_i32 s22, 0, 0x1c000
	s_add_i32 s16, s50, s27
	v_add_u32_e32 v149, s22, v145
	v_lshl_add_u64 v[142:143], v[142:143], 0, s[6:7]
	s_mov_b32 m0, s16
	ds_read_b128 v[198:201], v149
	ds_read_b128 v[202:205], v149 offset:1024
	ds_read_b128 v[206:209], v149 offset:2048
	ds_read_b128 v[210:213], v149 offset:3072
	global_load_lds_dwordx4 v[142:143], off
	v_lshl_add_u64 v[142:143], v[214:215], 0, s[6:7]
	s_add_i32 m0, s16, 0x2000
	s_nop 0
	global_load_lds_dwordx4 v[142:143], off
	s_barrier
	s_waitcnt lgkmcnt(0)
	s_waitcnt lgkmcnt(0)
	v_mfma_f32_16x16x32_bf16 v[116:119], v[198:201], v[166:169], v[116:119]
	v_mfma_f32_16x16x32_bf16 v[112:115], v[206:209], v[166:169], v[112:115]
	v_mfma_f32_16x16x32_bf16 v[100:103], v[198:201], v[174:177], v[100:103]
	v_mfma_f32_16x16x32_bf16 v[96:99], v[206:209], v[174:177], v[96:99]
	v_mfma_f32_16x16x32_bf16 v[84:87], v[198:201], v[182:185], v[84:87]
	v_mfma_f32_16x16x32_bf16 v[80:83], v[206:209], v[182:185], v[80:83]
	v_mfma_f32_16x16x32_bf16 v[68:71], v[198:201], v[190:193], v[68:71]
	v_mfma_f32_16x16x32_bf16 v[64:67], v[206:209], v[190:193], v[64:67]
	v_mfma_f32_16x16x32_bf16 v[116:119], v[202:205], v[170:173], v[116:119]
	v_mfma_f32_16x16x32_bf16 v[112:115], v[210:213], v[170:173], v[112:115]
	v_mfma_f32_16x16x32_bf16 v[100:103], v[202:205], v[178:181], v[100:103]
	v_mfma_f32_16x16x32_bf16 v[96:99], v[210:213], v[178:181], v[96:99]
	v_mfma_f32_16x16x32_bf16 v[84:87], v[202:205], v[186:189], v[84:87]
	v_mfma_f32_16x16x32_bf16 v[80:83], v[210:213], v[186:189], v[80:83]
	s_mov_b32 m0, s34
	v_lshl_add_u64 v[142:143], v[216:217], 0, s[6:7]
	v_mfma_f32_16x16x32_bf16 v[68:71], v[202:205], v[194:197], v[68:71]
	v_mfma_f32_16x16x32_bf16 v[64:67], v[210:213], v[194:197], v[64:67]
	s_barrier
	ds_read_b128 v[166:169], v147 offset:49152
	ds_read_b128 v[170:173], v147 offset:50176
	ds_read_b128 v[174:177], v147 offset:51200
	ds_read_b128 v[178:181], v147 offset:52224
	ds_read_b128 v[182:185], v147 offset:53248
	ds_read_b128 v[186:189], v147 offset:54272
	ds_read_b128 v[190:193], v147 offset:55296
	ds_read_b128 v[194:197], v147 offset:56320
	global_load_lds_dwordx4 v[142:143], off
	v_lshl_add_u64 v[142:143], v[218:219], 0, s[6:7]
	s_mov_b32 m0, s35
	s_nop 0
	global_load_lds_dwordx4 v[142:143], off
	s_barrier
; #define STG(P, GB) do { const char* _gb = (GB); \
;     _Pragma("unroll") for (int _i = 0; _i < 2; ++_i) { \
;       __builtin_amdgcn_global_load_lds((const unsigned*)(_gb + voff[_i]), \
;         (LAS unsigned*)((LAS char*)(P) + ldsw + _i * 8192), 16, 0, 0); } } while (0)
; #define MMA(ai, bj, At_, Bt_) do { __builtin_amdgcn_s_setprio(1); \
;     _Pragma("unroll") for (int m = 0; m < 4; ++m) _Pragma("unroll") for (int n = 0; n < 2; ++n) _Pragma("unroll") for (int k = 0; k < 2; ++k) \
;       acc[ai][bj][m][n] = __builtin_amdgcn_mfma_f32_16x16x32_bf16(Bt_[n][k], At_[m][k], acc[ai][bj][m][n], 0, 0, 0); \
;     __builtin_amdgcn_s_setprio(0); } while (0)
; #define WAIT_V(n) asm volatile("s_waitcnt vmcnt(" #n ")" ::: "memory")
; #define WAIT_L(n) asm volatile("s_waitcnt lgkmcnt(" #n ")" ::: "memory")
; #define BAR __builtin_amdgcn_s_barrier()
; #define SCHED __builtin_amdgcn_sched_barrier(0)
; __device__ __forceinline__ void gemm_phase(const bf16_t* __restrict__ A, const bf16_t* __restrict__ Bt, bf16_t* __restrict__ C, int M, int N, int K,
;                                            int ldc, const int EPI, char* smem, const int wid_u) {
;     ...
;       BAR; WAIT_L(0); MMA(1, 0, At, B0); BAR; SCHED;
;       STG(SB(1, 1), b3 + hstep);
;       WAIT_V(6); BAR; MMA(1, 1, At, B1); BAR;
;     }
;     ...
;             float o[8];
; #pragma unroll
;             for (int n = 0; n < 2; ++n) {
;               const f32x4 a = acc[ai][0][m][n], b = acc[ai][1][m][n];
; #pragma unroll
;               for (int j = 0; j < 4; ++j) o[n * 4 + j] = a[j] * __builtin_amdgcn_rcpf(1.f + __expf(-a[j])) * b[j];
;             }
;             *(uint4*)(C + row * ldc + (bcol >> 1) + wc * 32 + fq * 8) = pack8(o);
	s_waitcnt lgkmcnt(0)
	s_waitcnt lgkmcnt(0)
	v_mfma_f32_16x16x32_bf16 v[60:63], v[150:153], v[166:169], v[60:63]
	v_mfma_f32_16x16x32_bf16 v[56:59], v[158:161], v[166:169], v[56:59]
	v_mfma_f32_16x16x32_bf16 v[44:47], v[150:153], v[174:177], v[44:47]
	v_mfma_f32_16x16x32_bf16 v[40:43], v[158:161], v[174:177], v[40:43]
	v_mfma_f32_16x16x32_bf16 v[28:31], v[150:153], v[182:185], v[28:31]
	v_mfma_f32_16x16x32_bf16 v[24:27], v[158:161], v[182:185], v[24:27]
	v_mfma_f32_16x16x32_bf16 v[12:15], v[150:153], v[190:193], v[12:15]
	v_mfma_f32_16x16x32_bf16 v[8:11], v[158:161], v[190:193], v[8:11]
	v_mfma_f32_16x16x32_bf16 v[60:63], v[154:157], v[170:173], v[60:63]
	v_mfma_f32_16x16x32_bf16 v[56:59], v[162:165], v[170:173], v[56:59]
	v_mfma_f32_16x16x32_bf16 v[44:47], v[154:157], v[178:181], v[44:47]
	v_mfma_f32_16x16x32_bf16 v[40:43], v[162:165], v[178:181], v[40:43]
	v_mfma_f32_16x16x32_bf16 v[28:31], v[154:157], v[186:189], v[28:31]
	v_mfma_f32_16x16x32_bf16 v[24:27], v[162:165], v[186:189], v[24:27]
	v_mfma_f32_16x16x32_bf16 v[12:15], v[154:157], v[194:197], v[12:15]
	v_mfma_f32_16x16x32_bf16 v[8:11], v[162:165], v[194:197], v[8:11]
	s_barrier
	s_add_u32 s16, s20, 0x40080
	s_addc_u32 s17, s21, 0
	s_add_i32 s20, s22, s27
	v_lshl_add_u64 v[142:143], s[16:17], 0, v[130:131]
	s_mov_b32 m0, s20
	s_nop 0
	global_load_lds_dwordx4 v[142:143], off
	v_lshl_add_u64 v[142:143], s[16:17], 0, v[128:129]
	s_add_i32 m0, s20, 0x2000
	s_nop 0
	global_load_lds_dwordx4 v[142:143], off
	s_waitcnt vmcnt(6)
	s_barrier
	v_mfma_f32_16x16x32_bf16 v[52:55], v[198:201], v[166:169], v[52:55]
	v_mfma_f32_16x16x32_bf16 v[48:51], v[206:209], v[166:169], v[48:51]
	v_mfma_f32_16x16x32_bf16 v[36:39], v[198:201], v[174:177], v[36:39]
	v_mfma_f32_16x16x32_bf16 v[32:35], v[206:209], v[174:177], v[32:35]
	v_mfma_f32_16x16x32_bf16 v[20:23], v[198:201], v[182:185], v[20:23]
	v_mfma_f32_16x16x32_bf16 v[16:19], v[206:209], v[182:185], v[16:19]
	v_mfma_f32_16x16x32_bf16 v[4:7], v[198:201], v[190:193], v[4:7]
	v_mfma_f32_16x16x32_bf16 v[0:3], v[206:209], v[190:193], v[0:3]
	v_mfma_f32_16x16x32_bf16 v[52:55], v[202:205], v[170:173], v[52:55]
	v_mfma_f32_16x16x32_bf16 v[48:51], v[210:213], v[170:173], v[48:51]
	v_mfma_f32_16x16x32_bf16 v[36:39], v[202:205], v[178:181], v[36:39]
	v_mfma_f32_16x16x32_bf16 v[32:35], v[210:213], v[178:181], v[32:35]
	v_mfma_f32_16x16x32_bf16 v[20:23], v[202:205], v[186:189], v[20:23]
	v_mfma_f32_16x16x32_bf16 v[16:19], v[210:213], v[186:189], v[16:19]
	s_add_i32 s49, s49, 2
	s_add_u32 s47, s47, 0x100
	s_addc_u32 s48, s48, 0
	s_cmp_gt_u32 s49, 13
	s_mov_b64 s[16:17], s[18:19]
	v_mfma_f32_16x16x32_bf16 v[4:7], v[202:205], v[194:197], v[4:7]
	v_mfma_f32_16x16x32_bf16 v[0:3], v[210:213], v[194:197], v[0:3]
	s_barrier
	s_cbranch_scc0 .LBB0_145
	v_mul_f32_e32 v142, 0xbfb8aa3b, v124
	v_exp_f32_e32 v142, v142
	v_mul_f32_e32 v143, 0xbfb8aa3b, v125
	v_exp_f32_e32 v143, v143
	s_lshl_b32 s16, s40, 8
	v_add_f32_e32 v142, 1.0, v142
	v_rcp_f32_e32 v150, v142
	v_add_f32_e32 v142, 1.0, v143
	v_rcp_f32_e32 v151, v142
	s_mov_b32 s17, s9
	v_lshl_add_u32 v149, s41, 8, v144
	v_lshl_add_u64 v[142:143], v[132:133], 0, s[16:17]
	v_pk_mul_f32 v[124:125], v[124:125], v[150:151]
	v_mul_f32_e32 v150, 0xbfb8aa3b, v126
	v_mul_f32_e32 v151, 0xbfb8aa3b, v127
	v_exp_f32_e32 v150, v150
	v_exp_f32_e32 v151, v151
	v_pk_mul_f32 v[116:117], v[124:125], v[116:117]
	s_and_b64 vcc, exec, s[2:3]
	v_add_f32_e32 v124, 1.0, v150
	v_add_f32_e32 v125, 1.0, v151
	v_mul_f32_e32 v150, 0xbfb8aa3b, v120
	v_mul_f32_e32 v151, 0xbfb8aa3b, v121
	v_rcp_f32_e32 v124, v124
	v_rcp_f32_e32 v125, v125
	v_exp_f32_e32 v150, v150
	v_exp_f32_e32 v151, v151
	s_mov_b32 s41, s8
	v_pk_mul_f32 v[124:125], v[126:127], v[124:125]
	v_add_f32_e32 v126, 1.0, v150
	v_add_f32_e32 v127, 1.0, v151
	v_mul_f32_e32 v150, 0xbfb8aa3b, v122
	v_mul_f32_e32 v151, 0xbfb8aa3b, v123
	v_exp_f32_e32 v150, v150
	v_exp_f32_e32 v151, v151
	v_rcp_f32_e32 v126, v126
	v_rcp_f32_e32 v127, v127
	v_add_f32_e32 v150, 1.0, v150
	v_add_f32_e32 v151, 1.0, v151
	v_rcp_f32_e32 v150, v150
	v_rcp_f32_e32 v151, v151
	v_pk_mul_f32 v[120:121], v[120:121], v[126:127]
	v_pk_mul_f32 v[118:119], v[124:125], v[118:119]
	v_pk_mul_f32 v[120:121], v[120:121], v[112:113]
	v_pk_mul_f32 v[112:113], v[122:123], v[150:151]
	s_mov_b32 s40, s10
	v_pk_mul_f32 v[122:123], v[112:113], v[114:115]
	v_mul_f32_e32 v115, 0xbfb8aa3b, v108
	v_cvt_pk_bf16_f32 v112, v116, v117
	v_exp_f32_e32 v116, v115
	v_mul_f32_e32 v115, 0xbfb8aa3b, v109
	v_exp_f32_e32 v117, v115
	v_cvt_pk_bf16_f32 v113, v118, v119
	v_cvt_pk_bf16_f32 v114, v120, v121
	v_cvt_pk_bf16_f32 v115, v122, v123
	v_add_f32_e32 v116, 1.0, v116
	v_add_f32_e32 v117, 1.0, v117
	v_mad_i64_i32 v[118:119], s[16:17], v149, s38, v[142:143]
	v_rcp_f32_e32 v116, v116
	v_rcp_f32_e32 v117, v117
	global_store_dwordx4 v[118:119], v[112:115], off
	s_mov_b64 s[18:19], s[14:15]
	v_pk_mul_f32 v[108:109], v[108:109], v[116:117]
	v_mul_f32_e32 v112, 0xbfb8aa3b, v110
	v_mul_f32_e32 v113, 0xbfb8aa3b, v111
	v_exp_f32_e32 v112, v112
	v_exp_f32_e32 v113, v113
	v_pk_mul_f32 v[100:101], v[108:109], v[100:101]
	v_or_b32_e32 v114, 16, v149
	v_add_f32_e32 v108, 1.0, v112
	v_add_f32_e32 v109, 1.0, v113
	v_mul_f32_e32 v112, 0xbfb8aa3b, v104
	v_mul_f32_e32 v113, 0xbfb8aa3b, v105
	v_rcp_f32_e32 v108, v108
	v_rcp_f32_e32 v109, v109
	v_exp_f32_e32 v112, v112
	v_exp_f32_e32 v113, v113
	v_pk_mul_f32 v[108:109], v[110:111], v[108:109]
	v_add_f32_e32 v110, 1.0, v112
	v_add_f32_e32 v111, 1.0, v113
	v_mul_f32_e32 v112, 0xbfb8aa3b, v106
	v_mul_f32_e32 v113, 0xbfb8aa3b, v107
	v_exp_f32_e32 v112, v112
	v_exp_f32_e32 v113, v113
	v_rcp_f32_e32 v110, v110
	v_rcp_f32_e32 v111, v111
; __device__ __forceinline__ void gemm_phase(const bf16_t* __restrict__ A, const bf16_t* __restrict__ Bt, bf16_t* __restrict__ C, int M, int N, int K,
;                                            int ldc, const int EPI, char* smem, const int wid_u) {
;     ...
;             float o[8];
; #pragma unroll
;             for (int n = 0; n < 2; ++n) {
;               const f32x4 a = acc[ai][0][m][n], b = acc[ai][1][m][n];
; #pragma unroll
;               for (int j = 0; j < 4; ++j) o[n * 4 + j] = a[j] * __builtin_amdgcn_rcpf(1.f + __expf(-a[j])) * b[j];
;             }
;             *(uint4*)(C + row * ldc + (bcol >> 1) + wc * 32 + fq * 8) = pack8(o);
	v_add_f32_e32 v112, 1.0, v112
	v_add_f32_e32 v113, 1.0, v113
	v_rcp_f32_e32 v112, v112
	v_rcp_f32_e32 v113, v113
	v_pk_mul_f32 v[104:105], v[104:105], v[110:111]
	v_pk_mul_f32 v[102:103], v[108:109], v[102:103]
	v_pk_mul_f32 v[104:105], v[104:105], v[96:97]
	v_pk_mul_f32 v[96:97], v[106:107], v[112:113]
	s_nop 0
	v_pk_mul_f32 v[106:107], v[96:97], v[98:99]
	v_mul_f32_e32 v99, 0xbfb8aa3b, v92
	v_cvt_pk_bf16_f32 v96, v100, v101
	v_exp_f32_e32 v100, v99
	v_mul_f32_e32 v99, 0xbfb8aa3b, v93
	v_exp_f32_e32 v101, v99
	v_cvt_pk_bf16_f32 v97, v102, v103
	v_cvt_pk_bf16_f32 v98, v104, v105
	v_cvt_pk_bf16_f32 v99, v106, v107
	v_add_f32_e32 v100, 1.0, v100
	v_add_f32_e32 v101, 1.0, v101
	v_mad_i64_i32 v[102:103], s[16:17], v114, s38, v[142:143]
	v_rcp_f32_e32 v100, v100
	v_rcp_f32_e32 v101, v101
	global_store_dwordx4 v[102:103], v[96:99], off
	v_pk_mul_f32 v[92:93], v[92:93], v[100:101]
	s_nop 0
	v_mul_f32_e32 v96, 0xbfb8aa3b, v94
	v_mul_f32_e32 v97, 0xbfb8aa3b, v95
	v_exp_f32_e32 v96, v96
	v_exp_f32_e32 v97, v97
	v_pk_mul_f32 v[84:85], v[92:93], v[84:85]
	v_or_b32_e32 v98, 32, v149
	v_add_f32_e32 v92, 1.0, v96
	v_add_f32_e32 v93, 1.0, v97
	v_mul_f32_e32 v96, 0xbfb8aa3b, v88
	v_mul_f32_e32 v97, 0xbfb8aa3b, v89
	v_rcp_f32_e32 v92, v92
	v_rcp_f32_e32 v93, v93
	v_exp_f32_e32 v96, v96
	v_exp_f32_e32 v97, v97
	v_pk_mul_f32 v[92:93], v[94:95], v[92:93]
	v_add_f32_e32 v94, 1.0, v96
	v_add_f32_e32 v95, 1.0, v97
	v_mul_f32_e32 v96, 0xbfb8aa3b, v90
	v_mul_f32_e32 v97, 0xbfb8aa3b, v91
	v_exp_f32_e32 v96, v96
	v_exp_f32_e32 v97, v97
	v_rcp_f32_e32 v94, v94
	v_rcp_f32_e32 v95, v95
	v_add_f32_e32 v96, 1.0, v96
	v_add_f32_e32 v97, 1.0, v97
	v_rcp_f32_e32 v96, v96
	v_rcp_f32_e32 v97, v97
	v_pk_mul_f32 v[88:89], v[88:89], v[94:95]
	v_pk_mul_f32 v[86:87], v[92:93], v[86:87]
	v_pk_mul_f32 v[88:89], v[88:89], v[80:81]
	v_pk_mul_f32 v[80:81], v[90:91], v[96:97]
	s_nop 0
	v_pk_mul_f32 v[90:91], v[80:81], v[82:83]
	v_mul_f32_e32 v83, 0xbfb8aa3b, v76
	v_cvt_pk_bf16_f32 v80, v84, v85
	v_exp_f32_e32 v84, v83
	v_mul_f32_e32 v83, 0xbfb8aa3b, v77
	v_exp_f32_e32 v85, v83
	v_cvt_pk_bf16_f32 v81, v86, v87
	v_cvt_pk_bf16_f32 v82, v88, v89
	v_cvt_pk_bf16_f32 v83, v90, v91
	v_add_f32_e32 v84, 1.0, v84
	v_add_f32_e32 v85, 1.0, v85
	v_mad_i64_i32 v[86:87], s[16:17], v98, s38, v[142:143]
	v_rcp_f32_e32 v84, v84
	v_rcp_f32_e32 v85, v85
	global_store_dwordx4 v[86:87], v[80:83], off
	v_pk_mul_f32 v[76:77], v[76:77], v[84:85]
	s_nop 0
	v_mul_f32_e32 v80, 0xbfb8aa3b, v78
	v_mul_f32_e32 v81, 0xbfb8aa3b, v79
	v_exp_f32_e32 v80, v80
	v_exp_f32_e32 v81, v81
	v_pk_mul_f32 v[68:69], v[76:77], v[68:69]
	v_or_b32_e32 v82, 48, v149
	v_add_f32_e32 v76, 1.0, v80
	v_add_f32_e32 v77, 1.0, v81
	v_mul_f32_e32 v80, 0xbfb8aa3b, v72
	v_mul_f32_e32 v81, 0xbfb8aa3b, v73
	v_rcp_f32_e32 v76, v76
	v_rcp_f32_e32 v77, v77
	v_exp_f32_e32 v80, v80
	v_exp_f32_e32 v81, v81
	v_pk_mul_f32 v[76:77], v[78:79], v[76:77]
	v_add_f32_e32 v78, 1.0, v80
	v_add_f32_e32 v79, 1.0, v81
	v_mul_f32_e32 v80, 0xbfb8aa3b, v74
	v_mul_f32_e32 v81, 0xbfb8aa3b, v75
	v_exp_f32_e32 v80, v80
	v_exp_f32_e32 v81, v81
	v_rcp_f32_e32 v78, v78
	v_rcp_f32_e32 v79, v79
	v_add_f32_e32 v80, 1.0, v80
	v_add_f32_e32 v81, 1.0, v81
	v_rcp_f32_e32 v80, v80
	v_rcp_f32_e32 v81, v81
	v_pk_mul_f32 v[72:73], v[72:73], v[78:79]
	v_pk_mul_f32 v[70:71], v[76:77], v[70:71]
	v_pk_mul_f32 v[72:73], v[72:73], v[64:65]
	v_pk_mul_f32 v[64:65], v[74:75], v[80:81]
	s_nop 0
	v_pk_mul_f32 v[74:75], v[64:65], v[66:67]
	v_mul_f32_e32 v67, 0xbfb8aa3b, v60
	v_cvt_pk_bf16_f32 v64, v68, v69
	v_exp_f32_e32 v68, v67
	v_mul_f32_e32 v67, 0xbfb8aa3b, v61
	v_exp_f32_e32 v69, v67
	v_cvt_pk_bf16_f32 v65, v70, v71
	v_cvt_pk_bf16_f32 v66, v72, v73
	v_cvt_pk_bf16_f32 v67, v74, v75
	v_add_f32_e32 v68, 1.0, v68
	v_add_f32_e32 v69, 1.0, v69
	v_mad_i64_i32 v[70:71], s[16:17], v82, s38, v[142:143]
	v_rcp_f32_e32 v68, v68
	v_rcp_f32_e32 v69, v69
	global_store_dwordx4 v[70:71], v[64:67], off
	v_pk_mul_f32 v[60:61], v[60:61], v[68:69]
	s_nop 0
	v_mul_f32_e32 v64, 0xbfb8aa3b, v62
	v_mul_f32_e32 v65, 0xbfb8aa3b, v63
	v_exp_f32_e32 v64, v64
	v_exp_f32_e32 v65, v65
	v_pk_mul_f32 v[52:53], v[60:61], v[52:53]
	v_add_u32_e32 v66, 0x80, v149
	v_add_f32_e32 v60, 1.0, v64
	v_add_f32_e32 v61, 1.0, v65
	v_mul_f32_e32 v64, 0xbfb8aa3b, v56
	v_mul_f32_e32 v65, 0xbfb8aa3b, v57
	v_rcp_f32_e32 v60, v60
	v_rcp_f32_e32 v61, v61
	v_exp_f32_e32 v64, v64
	v_exp_f32_e32 v65, v65
	v_pk_mul_f32 v[60:61], v[62:63], v[60:61]
	v_add_f32_e32 v62, 1.0, v64
	v_add_f32_e32 v63, 1.0, v65
	v_mul_f32_e32 v64, 0xbfb8aa3b, v58
	v_mul_f32_e32 v65, 0xbfb8aa3b, v59
	v_exp_f32_e32 v64, v64
	v_exp_f32_e32 v65, v65
	v_rcp_f32_e32 v62, v62
	v_rcp_f32_e32 v63, v63
	v_add_f32_e32 v64, 1.0, v64
	v_add_f32_e32 v65, 1.0, v65
	v_rcp_f32_e32 v64, v64
	v_rcp_f32_e32 v65, v65
	v_pk_mul_f32 v[56:57], v[56:57], v[62:63]
	v_pk_mul_f32 v[54:55], v[60:61], v[54:55]
	v_pk_mul_f32 v[56:57], v[56:57], v[48:49]
	v_pk_mul_f32 v[48:49], v[58:59], v[64:65]
	s_nop 0
; #define WAIT_V(n) asm volatile("s_waitcnt vmcnt(" #n ")" ::: "memory")
; #define BAR __builtin_amdgcn_s_barrier()
; __device__ __forceinline__ void gemm_phase(const bf16_t* __restrict__ A, const bf16_t* __restrict__ Bt, bf16_t* __restrict__ C, int M, int N, int K,
;                                            int ldc, const int EPI, char* smem, const int wid_u) {
;     ...
;             float o[8];
; #pragma unroll
;             for (int n = 0; n < 2; ++n) {
;               const f32x4 a = acc[ai][0][m][n], b = acc[ai][1][m][n];
; #pragma unroll
;               for (int j = 0; j < 4; ++j) o[n * 4 + j] = a[j] * __builtin_amdgcn_rcpf(1.f + __expf(-a[j])) * b[j];
;             }
;             *(uint4*)(C + row * ldc + (bcol >> 1) + wc * 32 + fq * 8) = pack8(o);
;           }
;         }
;     }
;     if (!has_next) break;
; #pragma unroll
;     for (int a = 0; a < 2; ++a)
; #pragma unroll
;       for (int b = 0; b < 2; ++b)
; #pragma unroll
;         for (int m = 0; m < 4; ++m)
; #pragma unroll
;           for (int n = 0; n < 2; ++n) acc[a][b][m][n] = (f32x4){0.f, 0.f, 0.f, 0.f};
;     pm = npm; pn = npn; cA = nA; cB = nB; ++ui;
;   }
;   WAIT_V(0);
;   if (wr == 0) BAR;
	v_pk_mul_f32 v[58:59], v[48:49], v[50:51]
	v_mul_f32_e32 v51, 0xbfb8aa3b, v44
	v_cvt_pk_bf16_f32 v48, v52, v53
	v_exp_f32_e32 v52, v51
	v_mul_f32_e32 v51, 0xbfb8aa3b, v45
	v_exp_f32_e32 v53, v51
	v_cvt_pk_bf16_f32 v49, v54, v55
	v_cvt_pk_bf16_f32 v50, v56, v57
	v_cvt_pk_bf16_f32 v51, v58, v59
	v_add_f32_e32 v52, 1.0, v52
	v_add_f32_e32 v53, 1.0, v53
	v_mad_i64_i32 v[54:55], s[16:17], v66, s38, v[142:143]
	v_rcp_f32_e32 v52, v52
	v_rcp_f32_e32 v53, v53
	global_store_dwordx4 v[54:55], v[48:51], off
	v_pk_mul_f32 v[44:45], v[44:45], v[52:53]
	s_nop 0
	v_mul_f32_e32 v48, 0xbfb8aa3b, v46
	v_mul_f32_e32 v49, 0xbfb8aa3b, v47
	v_exp_f32_e32 v48, v48
	v_exp_f32_e32 v49, v49
	v_pk_mul_f32 v[36:37], v[44:45], v[36:37]
	v_add_u32_e32 v50, 0x90, v149
	v_add_f32_e32 v44, 1.0, v48
	v_add_f32_e32 v45, 1.0, v49
	v_mul_f32_e32 v48, 0xbfb8aa3b, v40
	v_mul_f32_e32 v49, 0xbfb8aa3b, v41
	v_rcp_f32_e32 v44, v44
	v_rcp_f32_e32 v45, v45
	v_exp_f32_e32 v48, v48
	v_exp_f32_e32 v49, v49
	v_pk_mul_f32 v[44:45], v[46:47], v[44:45]
	v_add_f32_e32 v46, 1.0, v48
	v_add_f32_e32 v47, 1.0, v49
	v_mul_f32_e32 v48, 0xbfb8aa3b, v42
	v_mul_f32_e32 v49, 0xbfb8aa3b, v43
	v_exp_f32_e32 v48, v48
	v_exp_f32_e32 v49, v49
	v_rcp_f32_e32 v46, v46
	v_rcp_f32_e32 v47, v47
	v_add_f32_e32 v48, 1.0, v48
	v_add_f32_e32 v49, 1.0, v49
	v_rcp_f32_e32 v48, v48
	v_rcp_f32_e32 v49, v49
	v_pk_mul_f32 v[40:41], v[40:41], v[46:47]
	v_pk_mul_f32 v[38:39], v[44:45], v[38:39]
	v_pk_mul_f32 v[40:41], v[40:41], v[32:33]
	v_pk_mul_f32 v[32:33], v[42:43], v[48:49]
	s_nop 0
	v_pk_mul_f32 v[42:43], v[32:33], v[34:35]
	v_mul_f32_e32 v35, 0xbfb8aa3b, v28
	v_cvt_pk_bf16_f32 v32, v36, v37
	v_exp_f32_e32 v36, v35
	v_mul_f32_e32 v35, 0xbfb8aa3b, v29
	v_exp_f32_e32 v37, v35
	v_cvt_pk_bf16_f32 v33, v38, v39
	v_cvt_pk_bf16_f32 v34, v40, v41
	v_cvt_pk_bf16_f32 v35, v42, v43
	v_add_f32_e32 v36, 1.0, v36
	v_add_f32_e32 v37, 1.0, v37
	v_mad_i64_i32 v[38:39], s[16:17], v50, s38, v[142:143]
	v_rcp_f32_e32 v36, v36
	v_rcp_f32_e32 v37, v37
	global_store_dwordx4 v[38:39], v[32:35], off
	v_pk_mul_f32 v[28:29], v[28:29], v[36:37]
	s_nop 0
	v_mul_f32_e32 v32, 0xbfb8aa3b, v30
	v_mul_f32_e32 v33, 0xbfb8aa3b, v31
	v_exp_f32_e32 v32, v32
	v_exp_f32_e32 v33, v33
	v_pk_mul_f32 v[20:21], v[28:29], v[20:21]
	v_add_u32_e32 v34, 0xa0, v149
	v_add_f32_e32 v28, 1.0, v32
	v_add_f32_e32 v29, 1.0, v33
	v_mul_f32_e32 v32, 0xbfb8aa3b, v24
	v_mul_f32_e32 v33, 0xbfb8aa3b, v25
	v_rcp_f32_e32 v28, v28
	v_rcp_f32_e32 v29, v29
	v_exp_f32_e32 v32, v32
	v_exp_f32_e32 v33, v33
	v_pk_mul_f32 v[28:29], v[30:31], v[28:29]
	v_add_f32_e32 v30, 1.0, v32
	v_add_f32_e32 v31, 1.0, v33
	v_mul_f32_e32 v32, 0xbfb8aa3b, v26
	v_mul_f32_e32 v33, 0xbfb8aa3b, v27
	v_exp_f32_e32 v32, v32
	v_exp_f32_e32 v33, v33
	v_rcp_f32_e32 v30, v30
	v_rcp_f32_e32 v31, v31
	v_add_f32_e32 v32, 1.0, v32
	v_add_f32_e32 v33, 1.0, v33
	v_rcp_f32_e32 v32, v32
	v_rcp_f32_e32 v33, v33
	v_pk_mul_f32 v[24:25], v[24:25], v[30:31]
	v_pk_mul_f32 v[22:23], v[28:29], v[22:23]
	v_pk_mul_f32 v[24:25], v[24:25], v[16:17]
	v_pk_mul_f32 v[16:17], v[26:27], v[32:33]
	s_nop 0
	v_pk_mul_f32 v[26:27], v[16:17], v[18:19]
	v_mul_f32_e32 v19, 0xbfb8aa3b, v12
	v_cvt_pk_bf16_f32 v16, v20, v21
	v_exp_f32_e32 v20, v19
	v_mul_f32_e32 v19, 0xbfb8aa3b, v13
	v_exp_f32_e32 v21, v19
	v_cvt_pk_bf16_f32 v17, v22, v23
	v_cvt_pk_bf16_f32 v18, v24, v25
	v_cvt_pk_bf16_f32 v19, v26, v27
	v_add_f32_e32 v20, 1.0, v20
	v_add_f32_e32 v21, 1.0, v21
	v_mad_i64_i32 v[22:23], s[16:17], v34, s38, v[142:143]
	v_rcp_f32_e32 v20, v20
	v_rcp_f32_e32 v21, v21
	global_store_dwordx4 v[22:23], v[16:19], off
	v_pk_mul_f32 v[12:13], v[12:13], v[20:21]
	s_nop 0
	v_mul_f32_e32 v16, 0xbfb8aa3b, v14
	v_mul_f32_e32 v17, 0xbfb8aa3b, v15
	v_exp_f32_e32 v16, v16
	v_exp_f32_e32 v17, v17
	v_pk_mul_f32 v[4:5], v[12:13], v[4:5]
	v_add_u32_e32 v18, 0xb0, v149
	v_add_f32_e32 v12, 1.0, v16
	v_add_f32_e32 v13, 1.0, v17
	v_mul_f32_e32 v16, 0xbfb8aa3b, v8
	v_mul_f32_e32 v17, 0xbfb8aa3b, v9
	v_rcp_f32_e32 v12, v12
	v_rcp_f32_e32 v13, v13
	v_exp_f32_e32 v16, v16
	v_exp_f32_e32 v17, v17
	v_pk_mul_f32 v[12:13], v[14:15], v[12:13]
	v_add_f32_e32 v14, 1.0, v16
	v_add_f32_e32 v15, 1.0, v17
	v_mul_f32_e32 v16, 0xbfb8aa3b, v10
	v_mul_f32_e32 v17, 0xbfb8aa3b, v11
	v_exp_f32_e32 v16, v16
	v_exp_f32_e32 v17, v17
	v_rcp_f32_e32 v14, v14
	v_rcp_f32_e32 v15, v15
	v_add_f32_e32 v16, 1.0, v16
	v_add_f32_e32 v17, 1.0, v17
	v_rcp_f32_e32 v16, v16
	v_rcp_f32_e32 v17, v17
	v_pk_mul_f32 v[8:9], v[8:9], v[14:15]
	v_pk_mul_f32 v[6:7], v[12:13], v[6:7]
	v_pk_mul_f32 v[8:9], v[8:9], v[0:1]
	v_pk_mul_f32 v[0:1], v[10:11], v[16:17]
	s_nop 0
	v_pk_mul_f32 v[10:11], v[0:1], v[2:3]
	v_cvt_pk_bf16_f32 v0, v4, v5
	v_mad_i64_i32 v[4:5], s[16:17], v18, s38, v[142:143]
	v_cvt_pk_bf16_f32 v1, v6, v7
	v_cvt_pk_bf16_f32 v2, v8, v9
	v_cvt_pk_bf16_f32 v3, v10, v11
	s_mov_b64 s[16:17], s[12:13]
	global_store_dwordx4 v[4:5], v[0:3], off
	s_cbranch_vccz .LBB0_142
	s_waitcnt vmcnt(0)
	s_cmpk_gt_u32 s24, 0xff
	s_cbranch_scc1 .LBB0_149
	s_barrier

; #define STG(P, GB) do { const char* _gb = (GB); \
;     _Pragma("unroll") for (int _i = 0; _i < 2; ++_i) { \
;       __builtin_amdgcn_global_load_lds((const unsigned*)(_gb + voff[_i]), \
;         (LAS unsigned*)((LAS char*)(P) + ldsw + _i * 8192), 16, 0, 0); } } while (0)
; #define LDA(dst, b, h) _Pragma("unroll") for (int m = 0; m < 4; ++m) _Pragma("unroll") for (int k = 0; k < 2; ++k) \
;     dst[m][k] = *(const LAS bf16x8*)((LAS char*)SA(b, h) + aoff + m * 2048 + k * 1024)
; #define LDB(dst, b, h) _Pragma("unroll") for (int n = 0; n < 2; ++n) _Pragma("unroll") for (int k = 0; k < 2; ++k) \
;     dst[n][k] = *(const LAS bf16x8*)((LAS char*)SB(b, h) + boff + n * 2048 + k * 1024)
; #define MMA(ai, bj, At_, Bt_) do { __builtin_amdgcn_s_setprio(1); \
;     _Pragma("unroll") for (int m = 0; m < 4; ++m) _Pragma("unroll") for (int n = 0; n < 2; ++n) _Pragma("unroll") for (int k = 0; k < 2; ++k) \
;       acc[ai][bj][m][n] = __builtin_amdgcn_mfma_f32_16x16x32_bf16(Bt_[n][k], At_[m][k], acc[ai][bj][m][n], 0, 0, 0); \
;     __builtin_amdgcn_s_setprio(0); } while (0)
; #define WAIT_L(n) asm volatile("s_waitcnt lgkmcnt(" #n ")" ::: "memory")
; #define BAR __builtin_amdgcn_s_barrier()
; #define SCHED __builtin_amdgcn_sched_barrier(0)
; __device__ __forceinline__ void gemm_phase(const bf16_t* __restrict__ A, const bf16_t* __restrict__ Bt, bf16_t* __restrict__ C, int M, int N, int K,
;                                            int ldc, const int EPI, char* smem, const int wid_u) {
;     ...
;       LDB(B0, 0, 0); SCHED; LDA(At, 0, 0); STG(SA(1, 1), a1 + hstep);
;       WAIT_L(8); BAR; WAIT_L(0); MMA(0, 0, At, B0); BAR; SCHED;
;       LDB(B1, 0, 1); STG(SB(0, 0), b2);
;       BAR; WAIT_L(0); MMA(0, 1, At, B1); BAR;
;       LDA(At, 0, 1); STG(SA(0, 0), a2);
;       BAR; WAIT_L(0); MMA(1, 0, At, B0); BAR; SCHED;
.LBB0_213:
	ds_read_b128 v[148:151], v143
	ds_read_b128 v[152:155], v143 offset:1024
	ds_read_b128 v[156:159], v143 offset:2048
	ds_read_b128 v[160:163], v143 offset:3072
	s_add_u32 s16, s14, 0x100
	s_addc_u32 s17, s15, 0
	s_cmp_eq_u32 s53, 40
	s_cselect_b32 s21, s5, s17
	s_cselect_b32 s20, s4, s16
	s_cselect_b32 s19, s7, s52
	s_cselect_b32 s18, s6, s51
	s_mov_b32 m0, s36
	v_lshl_add_u64 v[196:197], s[14:15], 0, v[136:137]
	ds_read_b128 v[164:167], v144
	ds_read_b128 v[168:171], v144 offset:1024
	ds_read_b128 v[172:175], v144 offset:2048
	ds_read_b128 v[176:179], v144 offset:3072
	ds_read_b128 v[180:183], v144 offset:4096
	ds_read_b128 v[184:187], v144 offset:5120
	ds_read_b128 v[188:191], v144 offset:6144
	ds_read_b128 v[192:195], v144 offset:7168
	global_load_lds_dwordx4 v[196:197], off
	v_lshl_add_u64 v[196:197], s[14:15], 0, v[134:135]
	s_mov_b32 m0, s37
	s_nop 0
	global_load_lds_dwordx4 v[196:197], off
	s_waitcnt lgkmcnt(8)
	s_barrier
	s_waitcnt lgkmcnt(0)
	s_waitcnt lgkmcnt(0)
	v_mfma_f32_16x16x32_bf16 v[124:127], v[148:151], v[164:167], v[124:127]
	v_mfma_f32_16x16x32_bf16 v[120:123], v[156:159], v[164:167], v[120:123]
	v_mfma_f32_16x16x32_bf16 v[116:119], v[148:151], v[172:175], v[116:119]
	v_mfma_f32_16x16x32_bf16 v[112:115], v[156:159], v[172:175], v[112:115]
	v_mfma_f32_16x16x32_bf16 v[100:103], v[148:151], v[180:183], v[100:103]
	v_mfma_f32_16x16x32_bf16 v[96:99], v[156:159], v[180:183], v[96:99]
	v_mfma_f32_16x16x32_bf16 v[84:87], v[148:151], v[188:191], v[84:87]
	v_mfma_f32_16x16x32_bf16 v[80:83], v[156:159], v[188:191], v[80:83]
	v_mfma_f32_16x16x32_bf16 v[124:127], v[152:155], v[168:171], v[124:127]
	v_mfma_f32_16x16x32_bf16 v[120:123], v[160:163], v[168:171], v[120:123]
	v_mfma_f32_16x16x32_bf16 v[116:119], v[152:155], v[176:179], v[116:119]
	v_mfma_f32_16x16x32_bf16 v[112:115], v[160:163], v[176:179], v[112:115]
	v_mfma_f32_16x16x32_bf16 v[100:103], v[152:155], v[184:187], v[100:103]
	v_mfma_f32_16x16x32_bf16 v[96:99], v[160:163], v[184:187], v[96:99]
	v_mfma_f32_16x16x32_bf16 v[84:87], v[152:155], v[192:195], v[84:87]
	v_mfma_f32_16x16x32_bf16 v[80:83], v[160:163], v[192:195], v[80:83]
	s_barrier
	s_mov_b32 m0, s38
	v_lshl_add_u64 v[212:213], s[18:19], 0, v[130:131]
	ds_read_b128 v[196:199], v145
	ds_read_b128 v[200:203], v145 offset:1024
	ds_read_b128 v[204:207], v145 offset:2048
	ds_read_b128 v[208:211], v145 offset:3072
	global_load_lds_dwordx4 v[212:213], off
	v_lshl_add_u64 v[214:215], s[18:19], 0, v[128:129]
	s_mov_b32 m0, s39
	s_nop 0
	global_load_lds_dwordx4 v[214:215], off
	s_barrier
	s_waitcnt lgkmcnt(0)
	s_waitcnt lgkmcnt(0)
	v_mfma_f32_16x16x32_bf16 v[108:111], v[196:199], v[164:167], v[108:111]
	v_mfma_f32_16x16x32_bf16 v[104:107], v[204:207], v[164:167], v[104:107]
	v_mfma_f32_16x16x32_bf16 v[92:95], v[196:199], v[172:175], v[92:95]
	v_mfma_f32_16x16x32_bf16 v[88:91], v[204:207], v[172:175], v[88:91]
	v_mfma_f32_16x16x32_bf16 v[76:79], v[196:199], v[180:183], v[76:79]
	v_mfma_f32_16x16x32_bf16 v[72:75], v[204:207], v[180:183], v[72:75]
	v_mfma_f32_16x16x32_bf16 v[68:71], v[196:199], v[188:191], v[68:71]
	v_mfma_f32_16x16x32_bf16 v[64:67], v[204:207], v[188:191], v[64:67]
	v_mfma_f32_16x16x32_bf16 v[108:111], v[200:203], v[168:171], v[108:111]
	v_mfma_f32_16x16x32_bf16 v[104:107], v[208:211], v[168:171], v[104:107]
	v_mfma_f32_16x16x32_bf16 v[92:95], v[200:203], v[176:179], v[92:95]
	v_mfma_f32_16x16x32_bf16 v[88:91], v[208:211], v[176:179], v[88:91]
	v_mfma_f32_16x16x32_bf16 v[76:79], v[200:203], v[184:187], v[76:79]
	v_mfma_f32_16x16x32_bf16 v[72:75], v[208:211], v[184:187], v[72:75]
	s_mov_b32 m0, s28
	v_lshl_add_u64 v[216:217], s[20:21], 0, v[130:131]
	v_mfma_f32_16x16x32_bf16 v[68:71], v[200:203], v[192:195], v[68:71]
	v_mfma_f32_16x16x32_bf16 v[64:67], v[208:211], v[192:195], v[64:67]
	s_barrier
	ds_read_b128 v[164:167], v144 offset:16384
	ds_read_b128 v[168:171], v144 offset:17408
	ds_read_b128 v[172:175], v144 offset:18432
	ds_read_b128 v[176:179], v144 offset:19456
	ds_read_b128 v[180:183], v144 offset:20480
	ds_read_b128 v[184:187], v144 offset:21504
	ds_read_b128 v[188:191], v144 offset:22528
	ds_read_b128 v[192:195], v144 offset:23552
	global_load_lds_dwordx4 v[216:217], off
	v_lshl_add_u64 v[218:219], s[20:21], 0, v[128:129]
	s_mov_b32 m0, s29
	s_nop 0
	global_load_lds_dwordx4 v[218:219], off
	s_barrier
	s_waitcnt lgkmcnt(0)
	s_waitcnt lgkmcnt(0)
	v_mfma_f32_16x16x32_bf16 v[60:63], v[148:151], v[164:167], v[60:63]
	v_mfma_f32_16x16x32_bf16 v[56:59], v[156:159], v[164:167], v[56:59]
	v_mfma_f32_16x16x32_bf16 v[52:55], v[148:151], v[172:175], v[52:55]
	v_mfma_f32_16x16x32_bf16 v[48:51], v[156:159], v[172:175], v[48:51]
	v_mfma_f32_16x16x32_bf16 v[36:39], v[148:151], v[180:183], v[36:39]
	v_mfma_f32_16x16x32_bf16 v[32:35], v[156:159], v[180:183], v[32:35]
	v_mfma_f32_16x16x32_bf16 v[20:23], v[148:151], v[188:191], v[20:23]
	v_mfma_f32_16x16x32_bf16 v[16:19], v[156:159], v[188:191], v[16:19]
	v_mfma_f32_16x16x32_bf16 v[60:63], v[152:155], v[168:171], v[60:63]
	v_mfma_f32_16x16x32_bf16 v[56:59], v[160:163], v[168:171], v[56:59]
	v_mfma_f32_16x16x32_bf16 v[52:55], v[152:155], v[176:179], v[52:55]
	v_mfma_f32_16x16x32_bf16 v[48:51], v[160:163], v[176:179], v[48:51]
	v_mfma_f32_16x16x32_bf16 v[36:39], v[152:155], v[184:187], v[36:39]
	v_mfma_f32_16x16x32_bf16 v[32:35], v[160:163], v[184:187], v[32:35]
	v_mfma_f32_16x16x32_bf16 v[20:23], v[152:155], v[192:195], v[20:23]
	v_mfma_f32_16x16x32_bf16 v[16:19], v[160:163], v[192:195], v[16:19]
	s_barrier
; #define STG(P, GB) do { const char* _gb = (GB); \
;     _Pragma("unroll") for (int _i = 0; _i < 2; ++_i) { \
;       __builtin_amdgcn_global_load_lds((const unsigned*)(_gb + voff[_i]), \
;         (LAS unsigned*)((LAS char*)(P) + ldsw + _i * 8192), 16, 0, 0); } } while (0)
; #define LDA(dst, b, h) _Pragma("unroll") for (int m = 0; m < 4; ++m) _Pragma("unroll") for (int k = 0; k < 2; ++k) \
;     dst[m][k] = *(const LAS bf16x8*)((LAS char*)SA(b, h) + aoff + m * 2048 + k * 1024)
; #define LDB(dst, b, h) _Pragma("unroll") for (int n = 0; n < 2; ++n) _Pragma("unroll") for (int k = 0; k < 2; ++k) \
;     dst[n][k] = *(const LAS bf16x8*)((LAS char*)SB(b, h) + boff + n * 2048 + k * 1024)
; #define MMA(ai, bj, At_, Bt_) do { __builtin_amdgcn_s_setprio(1); \
;     _Pragma("unroll") for (int m = 0; m < 4; ++m) _Pragma("unroll") for (int n = 0; n < 2; ++n) _Pragma("unroll") for (int k = 0; k < 2; ++k) \
;       acc[ai][bj][m][n] = __builtin_amdgcn_mfma_f32_16x16x32_bf16(Bt_[n][k], At_[m][k], acc[ai][bj][m][n], 0, 0, 0); \
;     __builtin_amdgcn_s_setprio(0); } while (0)
; #define WAIT_V(n) asm volatile("s_waitcnt vmcnt(" #n ")" ::: "memory")
; #define WAIT_L(n) asm volatile("s_waitcnt lgkmcnt(" #n ")" ::: "memory")
; #define BAR __builtin_amdgcn_s_barrier()
; #define SCHED __builtin_amdgcn_sched_barrier(0)
; __device__ __forceinline__ void gemm_phase(const bf16_t* __restrict__ A, const bf16_t* __restrict__ Bt, bf16_t* __restrict__ C, int M, int N, int K,
;                                            int ldc, const int EPI, char* smem, const int wid_u) {
;     ...
;       STG(SB(0, 1), b2 + hstep);
;       WAIT_V(6); BAR; MMA(1, 1, At, B1); BAR;
;       LDB(B0, 1, 0); SCHED; LDA(At, 1, 0); STG(SA(0, 1), a2 + hstep);
;       WAIT_L(8); BAR; WAIT_L(0); MMA(0, 0, At, B0); BAR; SCHED;
;       LDB(B1, 1, 1); STG(SB(1, 0), b3);
;       BAR; WAIT_L(0); MMA(0, 1, At, B1); BAR;
;       LDA(At, 1, 1); STG(SA(1, 0), a3);
	s_add_u32 s14, s18, 0xb0000
	s_addc_u32 s15, s19, 0
	s_mov_b32 m0, s40
	v_lshl_add_u64 v[148:149], s[14:15], 0, v[130:131]
	global_load_lds_dwordx4 v[148:149], off
	v_lshl_add_u64 v[148:149], s[14:15], 0, v[128:129]
	s_mov_b32 m0, s41
	s_nop 0
	global_load_lds_dwordx4 v[148:149], off
	s_waitcnt vmcnt(6)
	s_barrier
	v_mfma_f32_16x16x32_bf16 v[44:47], v[196:199], v[164:167], v[44:47]
	v_mfma_f32_16x16x32_bf16 v[40:43], v[204:207], v[164:167], v[40:43]
	v_mfma_f32_16x16x32_bf16 v[28:31], v[196:199], v[172:175], v[28:31]
	v_mfma_f32_16x16x32_bf16 v[24:27], v[204:207], v[172:175], v[24:27]
	v_mfma_f32_16x16x32_bf16 v[12:15], v[196:199], v[180:183], v[12:15]
	v_mfma_f32_16x16x32_bf16 v[8:11], v[204:207], v[180:183], v[8:11]
	v_mfma_f32_16x16x32_bf16 v[4:7], v[196:199], v[188:191], v[4:7]
	v_mfma_f32_16x16x32_bf16 v[0:3], v[204:207], v[188:191], v[0:3]
	v_mfma_f32_16x16x32_bf16 v[44:47], v[200:203], v[168:171], v[44:47]
	v_mfma_f32_16x16x32_bf16 v[40:43], v[208:211], v[168:171], v[40:43]
	v_mfma_f32_16x16x32_bf16 v[28:31], v[200:203], v[176:179], v[28:31]
	v_mfma_f32_16x16x32_bf16 v[24:27], v[208:211], v[176:179], v[24:27]
	v_mfma_f32_16x16x32_bf16 v[12:15], v[200:203], v[184:187], v[12:15]
	v_mfma_f32_16x16x32_bf16 v[8:11], v[208:211], v[184:187], v[8:11]
	v_mfma_f32_16x16x32_bf16 v[4:7], v[200:203], v[192:195], v[4:7]
	v_mfma_f32_16x16x32_bf16 v[0:3], v[208:211], v[192:195], v[0:3]
	s_barrier
	ds_read_b128 v[148:151], v146
	ds_read_b128 v[152:155], v146 offset:1024
	ds_read_b128 v[156:159], v146 offset:2048
	ds_read_b128 v[160:163], v146 offset:3072
	s_add_u32 s14, s20, 0xb0000
	s_addc_u32 s15, s21, 0
	s_mov_b32 m0, s30
	v_lshl_add_u64 v[196:197], s[14:15], 0, v[130:131]
	ds_read_b128 v[164:167], v144 offset:32768
	ds_read_b128 v[168:171], v144 offset:33792
	ds_read_b128 v[172:175], v144 offset:34816
	ds_read_b128 v[176:179], v144 offset:35840
	ds_read_b128 v[180:183], v144 offset:36864
	ds_read_b128 v[184:187], v144 offset:37888
	ds_read_b128 v[188:191], v144 offset:38912
	ds_read_b128 v[192:195], v144 offset:39936
	global_load_lds_dwordx4 v[196:197], off
	v_lshl_add_u64 v[196:197], s[14:15], 0, v[128:129]
	s_mov_b32 m0, s31
	s_nop 0
	global_load_lds_dwordx4 v[196:197], off
	s_waitcnt lgkmcnt(8)
	s_barrier
	s_waitcnt lgkmcnt(0)
	s_waitcnt lgkmcnt(0)
	v_mfma_f32_16x16x32_bf16 v[124:127], v[148:151], v[164:167], v[124:127]
	v_mfma_f32_16x16x32_bf16 v[120:123], v[156:159], v[164:167], v[120:123]
	v_mfma_f32_16x16x32_bf16 v[116:119], v[148:151], v[172:175], v[116:119]
	v_mfma_f32_16x16x32_bf16 v[112:115], v[156:159], v[172:175], v[112:115]
	v_mfma_f32_16x16x32_bf16 v[100:103], v[148:151], v[180:183], v[100:103]
	v_mfma_f32_16x16x32_bf16 v[96:99], v[156:159], v[180:183], v[96:99]
	v_mfma_f32_16x16x32_bf16 v[84:87], v[148:151], v[188:191], v[84:87]
	v_mfma_f32_16x16x32_bf16 v[80:83], v[156:159], v[188:191], v[80:83]
	v_mfma_f32_16x16x32_bf16 v[124:127], v[152:155], v[168:171], v[124:127]
	v_mfma_f32_16x16x32_bf16 v[120:123], v[160:163], v[168:171], v[120:123]
	v_mfma_f32_16x16x32_bf16 v[116:119], v[152:155], v[176:179], v[116:119]
	v_mfma_f32_16x16x32_bf16 v[112:115], v[160:163], v[176:179], v[112:115]
	v_mfma_f32_16x16x32_bf16 v[100:103], v[152:155], v[184:187], v[100:103]
	v_mfma_f32_16x16x32_bf16 v[96:99], v[160:163], v[184:187], v[96:99]
	v_mfma_f32_16x16x32_bf16 v[84:87], v[152:155], v[192:195], v[84:87]
	v_mfma_f32_16x16x32_bf16 v[80:83], v[160:163], v[192:195], v[80:83]
	s_barrier
	s_mov_b32 m0, s45
	v_lshl_add_u64 v[212:213], v[212:213], 0, s[12:13]
	ds_read_b128 v[196:199], v147
	ds_read_b128 v[200:203], v147 offset:1024
	ds_read_b128 v[204:207], v147 offset:2048
	ds_read_b128 v[208:211], v147 offset:3072
	global_load_lds_dwordx4 v[212:213], off
	v_lshl_add_u64 v[212:213], v[214:215], 0, s[12:13]
	s_mov_b32 m0, s46
	s_nop 0
	global_load_lds_dwordx4 v[212:213], off
	s_barrier
	s_waitcnt lgkmcnt(0)
	s_waitcnt lgkmcnt(0)
	v_mfma_f32_16x16x32_bf16 v[108:111], v[196:199], v[164:167], v[108:111]
	v_mfma_f32_16x16x32_bf16 v[104:107], v[204:207], v[164:167], v[104:107]
	v_mfma_f32_16x16x32_bf16 v[92:95], v[196:199], v[172:175], v[92:95]
	v_mfma_f32_16x16x32_bf16 v[88:91], v[204:207], v[172:175], v[88:91]
	v_mfma_f32_16x16x32_bf16 v[76:79], v[196:199], v[180:183], v[76:79]
	v_mfma_f32_16x16x32_bf16 v[72:75], v[204:207], v[180:183], v[72:75]
	v_mfma_f32_16x16x32_bf16 v[68:71], v[196:199], v[188:191], v[68:71]
	v_mfma_f32_16x16x32_bf16 v[64:67], v[204:207], v[188:191], v[64:67]
	v_mfma_f32_16x16x32_bf16 v[108:111], v[200:203], v[168:171], v[108:111]
	v_mfma_f32_16x16x32_bf16 v[104:107], v[208:211], v[168:171], v[104:107]
	v_mfma_f32_16x16x32_bf16 v[92:95], v[200:203], v[176:179], v[92:95]
	v_mfma_f32_16x16x32_bf16 v[88:91], v[208:211], v[176:179], v[88:91]
	v_mfma_f32_16x16x32_bf16 v[76:79], v[200:203], v[184:187], v[76:79]
	v_mfma_f32_16x16x32_bf16 v[72:75], v[208:211], v[184:187], v[72:75]
	s_mov_b32 m0, s34
	v_lshl_add_u64 v[212:213], v[216:217], 0, s[12:13]
	v_mfma_f32_16x16x32_bf16 v[68:71], v[200:203], v[192:195], v[68:71]
	v_mfma_f32_16x16x32_bf16 v[64:67], v[208:211], v[192:195], v[64:67]
	s_barrier
	ds_read_b128 v[164:167], v144 offset:49152
	ds_read_b128 v[168:171], v144 offset:50176
	ds_read_b128 v[172:175], v144 offset:51200
	ds_read_b128 v[176:179], v144 offset:52224
	ds_read_b128 v[180:183], v144 offset:53248
	ds_read_b128 v[184:187], v144 offset:54272
	ds_read_b128 v[188:191], v144 offset:55296
	ds_read_b128 v[192:195], v144 offset:56320
	global_load_lds_dwordx4 v[212:213], off
	v_lshl_add_u64 v[212:213], v[218:219], 0, s[12:13]
	s_mov_b32 m0, s35
	s_nop 0
	global_load_lds_dwordx4 v[212:213], off
	s_barrier
; #define STG(P, GB) do { const char* _gb = (GB); \
;     _Pragma("unroll") for (int _i = 0; _i < 2; ++_i) { \
;       __builtin_amdgcn_global_load_lds((const unsigned*)(_gb + voff[_i]), \
;         (LAS unsigned*)((LAS char*)(P) + ldsw + _i * 8192), 16, 0, 0); } } while (0)
; #define MMA(ai, bj, At_, Bt_) do { __builtin_amdgcn_s_setprio(1); \
;     _Pragma("unroll") for (int m = 0; m < 4; ++m) _Pragma("unroll") for (int n = 0; n < 2; ++n) _Pragma("unroll") for (int k = 0; k < 2; ++k) \
;       acc[ai][bj][m][n] = __builtin_amdgcn_mfma_f32_16x16x32_bf16(Bt_[n][k], At_[m][k], acc[ai][bj][m][n], 0, 0, 0); \
;     __builtin_amdgcn_s_setprio(0); } while (0)
; #define WAIT_V(n) asm volatile("s_waitcnt vmcnt(" #n ")" ::: "memory")
; #define WAIT_L(n) asm volatile("s_waitcnt lgkmcnt(" #n ")" ::: "memory")
; #define BAR __builtin_amdgcn_s_barrier()
; #define SCHED __builtin_amdgcn_sched_barrier(0)
; __device__ __forceinline__ void gemm_phase(const bf16_t* __restrict__ A, const bf16_t* __restrict__ Bt, bf16_t* __restrict__ C, int M, int N, int K,
;                                            int ldc, const int EPI, char* smem, const int wid_u) {
;     ...
;       BAR; WAIT_L(0); MMA(1, 0, At, B0); BAR; SCHED;
;       STG(SB(1, 1), b3 + hstep);
;       WAIT_V(6); BAR; MMA(1, 1, At, B1); BAR;
;     }
	s_waitcnt lgkmcnt(0)
	s_waitcnt lgkmcnt(0)
	v_mfma_f32_16x16x32_bf16 v[60:63], v[148:151], v[164:167], v[60:63]
	v_mfma_f32_16x16x32_bf16 v[56:59], v[156:159], v[164:167], v[56:59]
	v_mfma_f32_16x16x32_bf16 v[52:55], v[148:151], v[172:175], v[52:55]
	v_mfma_f32_16x16x32_bf16 v[48:51], v[156:159], v[172:175], v[48:51]
	v_mfma_f32_16x16x32_bf16 v[36:39], v[148:151], v[180:183], v[36:39]
	v_mfma_f32_16x16x32_bf16 v[32:35], v[156:159], v[180:183], v[32:35]
	v_mfma_f32_16x16x32_bf16 v[20:23], v[148:151], v[188:191], v[20:23]
	v_mfma_f32_16x16x32_bf16 v[16:19], v[156:159], v[188:191], v[16:19]
	v_mfma_f32_16x16x32_bf16 v[60:63], v[152:155], v[168:171], v[60:63]
	v_mfma_f32_16x16x32_bf16 v[56:59], v[160:163], v[168:171], v[56:59]
	v_mfma_f32_16x16x32_bf16 v[52:55], v[152:155], v[176:179], v[52:55]
	v_mfma_f32_16x16x32_bf16 v[48:51], v[160:163], v[176:179], v[48:51]
	v_mfma_f32_16x16x32_bf16 v[36:39], v[152:155], v[184:187], v[36:39]
	v_mfma_f32_16x16x32_bf16 v[32:35], v[160:163], v[184:187], v[32:35]
	v_mfma_f32_16x16x32_bf16 v[20:23], v[152:155], v[192:195], v[20:23]
	v_mfma_f32_16x16x32_bf16 v[16:19], v[160:163], v[192:195], v[16:19]
	s_barrier
	s_add_u32 s14, s18, 0xb0080
	s_addc_u32 s15, s19, 0
	s_add_i32 s18, s44, s27
	v_lshl_add_u64 v[148:149], s[14:15], 0, v[130:131]
	s_mov_b32 m0, s18
	s_nop 0
	global_load_lds_dwordx4 v[148:149], off
	v_lshl_add_u64 v[148:149], s[14:15], 0, v[128:129]
	s_add_i32 m0, s18, 0x2000
	s_nop 0
	global_load_lds_dwordx4 v[148:149], off
	s_waitcnt vmcnt(6)
	s_barrier
	v_mfma_f32_16x16x32_bf16 v[44:47], v[196:199], v[164:167], v[44:47]
	v_mfma_f32_16x16x32_bf16 v[40:43], v[204:207], v[164:167], v[40:43]
	v_mfma_f32_16x16x32_bf16 v[28:31], v[196:199], v[172:175], v[28:31]
	v_mfma_f32_16x16x32_bf16 v[24:27], v[204:207], v[172:175], v[24:27]
	v_mfma_f32_16x16x32_bf16 v[12:15], v[196:199], v[180:183], v[12:15]
	v_mfma_f32_16x16x32_bf16 v[8:11], v[204:207], v[180:183], v[8:11]
	v_mfma_f32_16x16x32_bf16 v[4:7], v[196:199], v[188:191], v[4:7]
	v_mfma_f32_16x16x32_bf16 v[0:3], v[204:207], v[188:191], v[0:3]
	v_mfma_f32_16x16x32_bf16 v[44:47], v[200:203], v[168:171], v[44:47]
	v_mfma_f32_16x16x32_bf16 v[40:43], v[208:211], v[168:171], v[40:43]
	v_mfma_f32_16x16x32_bf16 v[28:31], v[200:203], v[176:179], v[28:31]
	v_mfma_f32_16x16x32_bf16 v[24:27], v[208:211], v[176:179], v[24:27]
	v_mfma_f32_16x16x32_bf16 v[12:15], v[200:203], v[184:187], v[12:15]
	v_mfma_f32_16x16x32_bf16 v[8:11], v[208:211], v[184:187], v[8:11]
	s_add_i32 s53, s53, 2
	s_add_u32 s51, s51, 0x100
	s_addc_u32 s52, s52, 0
	s_cmp_gt_u32 s53, 41
	s_mov_b64 s[14:15], s[16:17]
	v_mfma_f32_16x16x32_bf16 v[4:7], v[200:203], v[192:195], v[4:7]
	v_mfma_f32_16x16x32_bf16 v[0:3], v[208:211], v[192:195], v[0:3]
	s_barrier
	s_cbranch_scc0 .LBB0_213
; #define WAIT_V(n) asm volatile("s_waitcnt vmcnt(" #n ")" ::: "memory")
; #define BAR __builtin_amdgcn_s_barrier()
; __device__ __forceinline__ void gemm_phase(const bf16_t* __restrict__ A, const bf16_t* __restrict__ Bt, bf16_t* __restrict__ C, int M, int N, int K,
;                                            int ldc, const int EPI, char* smem, const int wid_u) {
;     ...
;           if (EPI == 0) {
; #pragma unroll
;             for (int bj = 0; bj < 2; ++bj) {
;               const f32x4 v0 = acc[ai][bj][m][0], v1 = acc[ai][bj][m][1];
;               uint4 u; u.x = cvt_pk_bf16(v0[0], v0[1]); u.y = cvt_pk_bf16(v0[2], v0[3]); u.z = cvt_pk_bf16(v1[0], v1[1]); u.w = cvt_pk_bf16(v1[2], v1[3]);
;               *(uint4*)(C + row * ldc + bcol + bj * HALF + wc * 32 + fq * 8) = u;
;             }
;           } else {
;             float o[8];
; #pragma unroll
;             for (int n = 0; n < 2; ++n) {
;               const f32x4 a = acc[ai][0][m][n], b = acc[ai][1][m][n];
; #pragma unroll
;               for (int j = 0; j < 4; ++j) o[n * 4 + j] = a[j] * __builtin_amdgcn_rcpf(1.f + __expf(-a[j])) * b[j];
;             }
;             *(uint4*)(C + row * ldc + (bcol >> 1) + wc * 32 + fq * 8) = pack8(o);
;           }
;         }
;     }
;     if (!has_next) break;
; #pragma unroll
;     for (int a = 0; a < 2; ++a)
; #pragma unroll
;       for (int b = 0; b < 2; ++b)
; #pragma unroll
;         for (int m = 0; m < 4; ++m)
; #pragma unroll
;           for (int n = 0; n < 2; ++n) acc[a][b][m][n] = (f32x4){0.f, 0.f, 0.f, 0.f};
;     pm = npm; pn = npn; cA = nA; cB = nB; ++ui;
;   }
;   WAIT_V(0);
;   if (wr == 0) BAR;
	v_lshl_add_u32 v148, s10, 8, v142
	v_cvt_pk_bf16_f32 v68, v68, v69
	v_cvt_pk_bf16_f32 v69, v70, v71
	v_cvt_pk_bf16_f32 v70, v64, v65
	v_add_u32_e32 v64, 0x80, v148
	s_lshl_b32 s10, s50, 9
	v_ashrrev_i32_e32 v149, 31, v148
	v_cvt_pk_bf16_f32 v108, v108, v109
	v_cvt_pk_bf16_f32 v109, v110, v111
	v_cvt_pk_bf16_f32 v110, v104, v105
	v_or_b32_e32 v104, 16, v148
	v_ashrrev_i32_e32 v65, 31, v64
	v_cvt_pk_bf16_f32 v44, v44, v45
	v_cvt_pk_bf16_f32 v45, v46, v47
	v_cvt_pk_bf16_f32 v46, v40, v41
	v_add_u32_e32 v40, 0x90, v148
	v_lshl_add_u64 v[150:151], v[132:133], 0, s[10:11]
	v_lshlrev_b64 v[152:153], 11, v[148:149]
	v_ashrrev_i32_e32 v105, 31, v104
	v_cvt_pk_bf16_f32 v92, v92, v93
	v_cvt_pk_bf16_f32 v93, v94, v95
	v_cvt_pk_bf16_f32 v94, v88, v89
	v_or_b32_e32 v88, 32, v148
	v_lshlrev_b64 v[64:65], 11, v[64:65]
	v_ashrrev_i32_e32 v41, 31, v40
	v_cvt_pk_bf16_f32 v28, v28, v29
	v_cvt_pk_bf16_f32 v29, v30, v31
	v_cvt_pk_bf16_f32 v30, v24, v25
	v_add_u32_e32 v24, 0xa0, v148
	v_lshl_add_u64 v[152:153], v[150:151], 0, v[152:153]
	v_cvt_pk_bf16_f32 v111, v106, v107
	v_lshlrev_b64 v[104:105], 11, v[104:105]
	v_ashrrev_i32_e32 v89, 31, v88
	v_cvt_pk_bf16_f32 v76, v76, v77
	v_cvt_pk_bf16_f32 v77, v78, v79
	v_cvt_pk_bf16_f32 v78, v72, v73
	v_or_b32_e32 v72, 48, v148
	v_lshl_add_u64 v[64:65], v[150:151], 0, v[64:65]
	v_cvt_pk_bf16_f32 v47, v42, v43
	v_lshlrev_b64 v[40:41], 11, v[40:41]
	v_ashrrev_i32_e32 v25, 31, v24
	v_cvt_pk_bf16_f32 v12, v12, v13
	v_cvt_pk_bf16_f32 v13, v14, v15
	v_cvt_pk_bf16_f32 v14, v8, v9
	v_add_u32_e32 v8, 0xb0, v148
	global_store_dwordx4 v[152:153], v[108:111], off offset:256
	v_cvt_pk_bf16_f32 v95, v90, v91
	v_lshlrev_b64 v[88:89], 11, v[88:89]
	v_lshl_add_u64 v[108:109], v[150:151], 0, v[104:105]
	v_ashrrev_i32_e32 v73, 31, v72
	global_store_dwordx4 v[64:65], v[44:47], off offset:256
	v_cvt_pk_bf16_f32 v31, v26, v27
	v_lshlrev_b64 v[24:25], 11, v[24:25]
	v_lshl_add_u64 v[44:45], v[150:151], 0, v[40:41]
	v_ashrrev_i32_e32 v9, 31, v8
	global_store_dwordx4 v[108:109], v[92:95], off offset:256
	v_cvt_pk_bf16_f32 v79, v74, v75
	v_lshlrev_b64 v[72:73], 11, v[72:73]
	v_lshl_add_u64 v[92:93], v[150:151], 0, v[88:89]
	global_store_dwordx4 v[44:45], v[28:31], off offset:256
	v_cvt_pk_bf16_f32 v15, v10, v11
	v_lshlrev_b64 v[8:9], 11, v[8:9]
	v_lshl_add_u64 v[28:29], v[150:151], 0, v[24:25]
	v_cvt_pk_bf16_f32 v124, v124, v125
	v_cvt_pk_bf16_f32 v125, v126, v127
	v_cvt_pk_bf16_f32 v126, v120, v121
	v_cvt_pk_bf16_f32 v127, v122, v123
	v_cvt_pk_bf16_f32 v104, v116, v117
	v_cvt_pk_bf16_f32 v105, v118, v119
	v_cvt_pk_bf16_f32 v106, v112, v113
	v_cvt_pk_bf16_f32 v107, v114, v115
	v_cvt_pk_bf16_f32 v88, v100, v101
	v_cvt_pk_bf16_f32 v89, v102, v103
	v_cvt_pk_bf16_f32 v90, v96, v97
	v_cvt_pk_bf16_f32 v91, v98, v99
	global_store_dwordx4 v[92:93], v[76:79], off offset:256
	v_cvt_pk_bf16_f32 v74, v80, v81
	v_cvt_pk_bf16_f32 v75, v82, v83
	v_lshl_add_u64 v[76:77], v[150:151], 0, v[72:73]
	v_cvt_pk_bf16_f32 v72, v84, v85
	v_cvt_pk_bf16_f32 v73, v86, v87
	v_cvt_pk_bf16_f32 v71, v66, v67
	v_cvt_pk_bf16_f32 v60, v60, v61
	v_cvt_pk_bf16_f32 v61, v62, v63
	v_cvt_pk_bf16_f32 v62, v56, v57
	v_cvt_pk_bf16_f32 v63, v58, v59
	v_cvt_pk_bf16_f32 v40, v52, v53
	v_cvt_pk_bf16_f32 v41, v54, v55
	v_cvt_pk_bf16_f32 v42, v48, v49
	v_cvt_pk_bf16_f32 v43, v50, v51
	v_cvt_pk_bf16_f32 v24, v36, v37
	v_cvt_pk_bf16_f32 v25, v38, v39
	v_cvt_pk_bf16_f32 v26, v32, v33
	v_cvt_pk_bf16_f32 v27, v34, v35
	global_store_dwordx4 v[28:29], v[12:15], off offset:256
	v_cvt_pk_bf16_f32 v10, v16, v17
	v_cvt_pk_bf16_f32 v11, v18, v19
	v_lshl_add_u64 v[12:13], v[150:151], 0, v[8:9]
	v_cvt_pk_bf16_f32 v8, v20, v21
	v_cvt_pk_bf16_f32 v9, v22, v23
	v_cvt_pk_bf16_f32 v4, v4, v5
	v_cvt_pk_bf16_f32 v5, v6, v7
	v_cvt_pk_bf16_f32 v6, v0, v1
	v_cvt_pk_bf16_f32 v7, v2, v3
	s_and_b64 vcc, exec, s[2:3]
	s_mov_b32 s10, s48
	s_mov_b32 s50, s49
	s_mov_b64 s[16:17], s[6:7]
	s_mov_b64 s[14:15], s[4:5]
	global_store_dwordx4 v[152:153], v[124:127], off
	global_store_dwordx4 v[108:109], v[104:107], off
	global_store_dwordx4 v[92:93], v[88:91], off
	global_store_dwordx4 v[76:77], v[72:75], off
	global_store_dwordx4 v[76:77], v[68:71], off offset:256
	global_store_dwordx4 v[64:65], v[60:63], off
	global_store_dwordx4 v[44:45], v[40:43], off
	global_store_dwordx4 v[28:29], v[24:27], off
	global_store_dwordx4 v[12:13], v[8:11], off
	global_store_dwordx4 v[12:13], v[4:7], off offset:256
	s_cbranch_vccz .LBB0_206
	s_waitcnt vmcnt(0)
	s_cmpk_gt_u32 s22, 0xff
	s_cbranch_scc1 .LBB0_217
	s_barrier

; #define STG(P, GB) do { const char* _gb = (GB); \
;     _Pragma("unroll") for (int _i = 0; _i < 2; ++_i) { \
;       __builtin_amdgcn_global_load_lds((const unsigned*)(_gb + voff[_i]), \
;         (LAS unsigned*)((LAS char*)(P) + ldsw + _i * 8192), 16, 0, 0); } } while (0)
; #define LDA(dst, b, h) _Pragma("unroll") for (int m = 0; m < 4; ++m) _Pragma("unroll") for (int k = 0; k < 2; ++k) \
;     dst[m][k] = *(const LAS bf16x8*)((LAS char*)SA(b, h) + aoff + m * 2048 + k * 1024)
; #define LDB(dst, b, h) _Pragma("unroll") for (int n = 0; n < 2; ++n) _Pragma("unroll") for (int k = 0; k < 2; ++k) \
;     dst[n][k] = *(const LAS bf16x8*)((LAS char*)SB(b, h) + boff + n * 2048 + k * 1024)
; #define MMA(ai, bj, At_, Bt_) do { __builtin_amdgcn_s_setprio(1); \
;     _Pragma("unroll") for (int m = 0; m < 4; ++m) _Pragma("unroll") for (int n = 0; n < 2; ++n) _Pragma("unroll") for (int k = 0; k < 2; ++k) \
;       acc[ai][bj][m][n] = __builtin_amdgcn_mfma_f32_16x16x32_bf16(Bt_[n][k], At_[m][k], acc[ai][bj][m][n], 0, 0, 0); \
;     __builtin_amdgcn_s_setprio(0); } while (0)
; #define WAIT_L(n) asm volatile("s_waitcnt lgkmcnt(" #n ")" ::: "memory")
; #define BAR __builtin_amdgcn_s_barrier()
; #define SCHED __builtin_amdgcn_sched_barrier(0)
; __device__ __forceinline__ void gemm_phase(const bf16_t* __restrict__ A, const bf16_t* __restrict__ Bt, bf16_t* __restrict__ C, int M, int N, int K,
;                                            int ldc, const int EPI, char* smem, const int wid_u) {
;     ...
;       LDB(B0, 0, 0); SCHED; LDA(At, 0, 0); STG(SA(1, 1), a1 + hstep);
;       WAIT_L(8); BAR; WAIT_L(0); MMA(0, 0, At, B0); BAR; SCHED;
;       LDB(B1, 0, 1); STG(SB(0, 0), b2);
;       BAR; WAIT_L(0); MMA(0, 1, At, B1); BAR;
;       LDA(At, 0, 1); STG(SA(0, 0), a2);
;       BAR; WAIT_L(0); MMA(1, 0, At, B0); BAR; SCHED;
.LBB0_334:
	ds_read_b128 v[148:151], v144
	ds_read_b128 v[152:155], v144 offset:1024
	ds_read_b128 v[156:159], v144 offset:2048
	ds_read_b128 v[160:163], v144 offset:3072
	s_add_u32 s18, s16, 0x100
	s_addc_u32 s19, s17, 0
	s_cmp_eq_u32 s51, 12
	s_cselect_b32 s23, s46, s19
	s_cselect_b32 s22, s47, s18
	s_cselect_b32 s21, s11, s50
	s_cselect_b32 s20, s48, s49
	v_lshl_add_u64 v[196:197], s[16:17], 0, v[136:137]
	s_add_i32 m0, s30, 0xc000
	ds_read_b128 v[164:167], v145
	ds_read_b128 v[168:171], v145 offset:1024
	ds_read_b128 v[172:175], v145 offset:2048
	ds_read_b128 v[176:179], v145 offset:3072
	ds_read_b128 v[180:183], v145 offset:4096
	ds_read_b128 v[184:187], v145 offset:5120
	ds_read_b128 v[188:191], v145 offset:6144
	ds_read_b128 v[192:195], v145 offset:7168
	global_load_lds_dwordx4 v[196:197], off
	v_lshl_add_u64 v[196:197], s[16:17], 0, v[134:135]
	s_add_i32 m0, s30, 0xe000
	s_nop 0
	global_load_lds_dwordx4 v[196:197], off
	s_waitcnt lgkmcnt(8)
	s_barrier
	s_waitcnt lgkmcnt(0)
	s_waitcnt lgkmcnt(0)
	v_mfma_f32_16x16x32_bf16 v[124:127], v[148:151], v[164:167], v[124:127]
	v_mfma_f32_16x16x32_bf16 v[120:123], v[156:159], v[164:167], v[120:123]
	v_mfma_f32_16x16x32_bf16 v[116:119], v[148:151], v[172:175], v[116:119]
	v_mfma_f32_16x16x32_bf16 v[112:115], v[156:159], v[172:175], v[112:115]
	v_mfma_f32_16x16x32_bf16 v[100:103], v[148:151], v[180:183], v[100:103]
	v_mfma_f32_16x16x32_bf16 v[96:99], v[156:159], v[180:183], v[96:99]
	v_mfma_f32_16x16x32_bf16 v[84:87], v[148:151], v[188:191], v[84:87]
	v_mfma_f32_16x16x32_bf16 v[80:83], v[156:159], v[188:191], v[80:83]
	v_mfma_f32_16x16x32_bf16 v[124:127], v[152:155], v[168:171], v[124:127]
	v_mfma_f32_16x16x32_bf16 v[120:123], v[160:163], v[168:171], v[120:123]
	v_mfma_f32_16x16x32_bf16 v[116:119], v[152:155], v[176:179], v[116:119]
	v_mfma_f32_16x16x32_bf16 v[112:115], v[160:163], v[176:179], v[112:115]
	v_mfma_f32_16x16x32_bf16 v[100:103], v[152:155], v[184:187], v[100:103]
	v_mfma_f32_16x16x32_bf16 v[96:99], v[160:163], v[184:187], v[96:99]
	v_mfma_f32_16x16x32_bf16 v[84:87], v[152:155], v[192:195], v[84:87]
	v_mfma_f32_16x16x32_bf16 v[80:83], v[160:163], v[192:195], v[80:83]
	s_barrier
	s_add_i32 s16, s38, s29
	v_lshl_add_u64 v[212:213], s[20:21], 0, v[130:131]
	s_mov_b32 m0, s16
	ds_read_b128 v[196:199], v146
	ds_read_b128 v[200:203], v146 offset:1024
	ds_read_b128 v[204:207], v146 offset:2048
	ds_read_b128 v[208:211], v146 offset:3072
	global_load_lds_dwordx4 v[212:213], off
	v_lshl_add_u64 v[214:215], s[20:21], 0, v[128:129]
	s_add_i32 m0, s16, 0x2000
	s_nop 0
	global_load_lds_dwordx4 v[214:215], off
	s_barrier
	s_waitcnt lgkmcnt(0)
	s_waitcnt lgkmcnt(0)
	v_mfma_f32_16x16x32_bf16 v[108:111], v[196:199], v[164:167], v[108:111]
	v_mfma_f32_16x16x32_bf16 v[104:107], v[204:207], v[164:167], v[104:107]
	v_mfma_f32_16x16x32_bf16 v[92:95], v[196:199], v[172:175], v[92:95]
	v_mfma_f32_16x16x32_bf16 v[88:91], v[204:207], v[172:175], v[88:91]
	v_mfma_f32_16x16x32_bf16 v[76:79], v[196:199], v[180:183], v[76:79]
	v_mfma_f32_16x16x32_bf16 v[72:75], v[204:207], v[180:183], v[72:75]
	v_mfma_f32_16x16x32_bf16 v[68:71], v[196:199], v[188:191], v[68:71]
	v_mfma_f32_16x16x32_bf16 v[64:67], v[204:207], v[188:191], v[64:67]
	v_mfma_f32_16x16x32_bf16 v[108:111], v[200:203], v[168:171], v[108:111]
	v_mfma_f32_16x16x32_bf16 v[104:107], v[208:211], v[168:171], v[104:107]
	v_mfma_f32_16x16x32_bf16 v[92:95], v[200:203], v[176:179], v[92:95]
	v_mfma_f32_16x16x32_bf16 v[88:91], v[208:211], v[176:179], v[88:91]
	v_mfma_f32_16x16x32_bf16 v[76:79], v[200:203], v[184:187], v[76:79]
	v_mfma_f32_16x16x32_bf16 v[72:75], v[208:211], v[184:187], v[72:75]
	s_mov_b32 m0, s30
	v_lshl_add_u64 v[216:217], s[22:23], 0, v[130:131]
	v_mfma_f32_16x16x32_bf16 v[68:71], v[200:203], v[192:195], v[68:71]
	v_mfma_f32_16x16x32_bf16 v[64:67], v[208:211], v[192:195], v[64:67]
	s_barrier
	ds_read_b128 v[164:167], v145 offset:16384
	ds_read_b128 v[168:171], v145 offset:17408
	ds_read_b128 v[172:175], v145 offset:18432
	ds_read_b128 v[176:179], v145 offset:19456
	ds_read_b128 v[180:183], v145 offset:20480
	ds_read_b128 v[184:187], v145 offset:21504
	ds_read_b128 v[188:191], v145 offset:22528
	ds_read_b128 v[192:195], v145 offset:23552
	global_load_lds_dwordx4 v[216:217], off
	v_lshl_add_u64 v[218:219], s[22:23], 0, v[128:129]
	s_mov_b32 m0, s31
	s_nop 0
	global_load_lds_dwordx4 v[218:219], off
	s_barrier
	s_waitcnt lgkmcnt(0)
	s_waitcnt lgkmcnt(0)
	v_mfma_f32_16x16x32_bf16 v[60:63], v[148:151], v[164:167], v[60:63]
	v_mfma_f32_16x16x32_bf16 v[56:59], v[156:159], v[164:167], v[56:59]
	v_mfma_f32_16x16x32_bf16 v[52:55], v[148:151], v[172:175], v[52:55]
	v_mfma_f32_16x16x32_bf16 v[48:51], v[156:159], v[172:175], v[48:51]
	v_mfma_f32_16x16x32_bf16 v[36:39], v[148:151], v[180:183], v[36:39]
	v_mfma_f32_16x16x32_bf16 v[32:35], v[156:159], v[180:183], v[32:35]
	v_mfma_f32_16x16x32_bf16 v[20:23], v[148:151], v[188:191], v[20:23]
	v_mfma_f32_16x16x32_bf16 v[16:19], v[156:159], v[188:191], v[16:19]
	v_mfma_f32_16x16x32_bf16 v[60:63], v[152:155], v[168:171], v[60:63]
	v_mfma_f32_16x16x32_bf16 v[56:59], v[160:163], v[168:171], v[56:59]
	v_mfma_f32_16x16x32_bf16 v[52:55], v[152:155], v[176:179], v[52:55]
	v_mfma_f32_16x16x32_bf16 v[48:51], v[160:163], v[176:179], v[48:51]
	v_mfma_f32_16x16x32_bf16 v[36:39], v[152:155], v[184:187], v[36:39]
	v_mfma_f32_16x16x32_bf16 v[32:35], v[160:163], v[184:187], v[32:35]
	v_mfma_f32_16x16x32_bf16 v[20:23], v[152:155], v[192:195], v[20:23]
	v_mfma_f32_16x16x32_bf16 v[16:19], v[160:163], v[192:195], v[16:19]
	s_barrier
; #define STG(P, GB) do { const char* _gb = (GB); \
;     _Pragma("unroll") for (int _i = 0; _i < 2; ++_i) { \
;       __builtin_amdgcn_global_load_lds((const unsigned*)(_gb + voff[_i]), \
;         (LAS unsigned*)((LAS char*)(P) + ldsw + _i * 8192), 16, 0, 0); } } while (0)
; #define LDA(dst, b, h) _Pragma("unroll") for (int m = 0; m < 4; ++m) _Pragma("unroll") for (int k = 0; k < 2; ++k) \
;     dst[m][k] = *(const LAS bf16x8*)((LAS char*)SA(b, h) + aoff + m * 2048 + k * 1024)
; #define LDB(dst, b, h) _Pragma("unroll") for (int n = 0; n < 2; ++n) _Pragma("unroll") for (int k = 0; k < 2; ++k) \
;     dst[n][k] = *(const LAS bf16x8*)((LAS char*)SB(b, h) + boff + n * 2048 + k * 1024)
; #define MMA(ai, bj, At_, Bt_) do { __builtin_amdgcn_s_setprio(1); \
;     _Pragma("unroll") for (int m = 0; m < 4; ++m) _Pragma("unroll") for (int n = 0; n < 2; ++n) _Pragma("unroll") for (int k = 0; k < 2; ++k) \
;       acc[ai][bj][m][n] = __builtin_amdgcn_mfma_f32_16x16x32_bf16(Bt_[n][k], At_[m][k], acc[ai][bj][m][n], 0, 0, 0); \
;     __builtin_amdgcn_s_setprio(0); } while (0)
; #define WAIT_V(n) asm volatile("s_waitcnt vmcnt(" #n ")" ::: "memory")
; #define WAIT_L(n) asm volatile("s_waitcnt lgkmcnt(" #n ")" ::: "memory")
; #define BAR __builtin_amdgcn_s_barrier()
; #define SCHED __builtin_amdgcn_sched_barrier(0)
; __device__ __forceinline__ void gemm_phase(const bf16_t* __restrict__ A, const bf16_t* __restrict__ Bt, bf16_t* __restrict__ C, int M, int N, int K,
;                                            int ldc, const int EPI, char* smem, const int wid_u) {
;     ...
;       STG(SB(0, 1), b2 + hstep);
;       WAIT_V(6); BAR; MMA(1, 1, At, B1); BAR;
;       LDB(B0, 1, 0); SCHED; LDA(At, 1, 0); STG(SA(0, 1), a2 + hstep);
;       WAIT_L(8); BAR; WAIT_L(0); MMA(0, 0, At, B0); BAR; SCHED;
;       LDB(B1, 1, 1); STG(SB(1, 0), b3);
;       BAR; WAIT_L(0); MMA(0, 1, At, B1); BAR;
;       LDA(At, 1, 1); STG(SA(1, 0), a3);
	s_add_u32 s16, s20, 0x40000
	s_addc_u32 s17, s21, 0
	s_add_i32 s52, s39, s29
	v_lshl_add_u64 v[148:149], s[16:17], 0, v[130:131]
	s_mov_b32 m0, s52
	s_nop 0
	global_load_lds_dwordx4 v[148:149], off
	v_lshl_add_u64 v[148:149], s[16:17], 0, v[128:129]
	s_add_i32 m0, s52, 0x2000
	s_nop 0
	global_load_lds_dwordx4 v[148:149], off
	s_waitcnt vmcnt(6)
	s_barrier
	v_mfma_f32_16x16x32_bf16 v[44:47], v[196:199], v[164:167], v[44:47]
	v_mfma_f32_16x16x32_bf16 v[40:43], v[204:207], v[164:167], v[40:43]
	v_mfma_f32_16x16x32_bf16 v[28:31], v[196:199], v[172:175], v[28:31]
	v_mfma_f32_16x16x32_bf16 v[24:27], v[204:207], v[172:175], v[24:27]
	v_mfma_f32_16x16x32_bf16 v[12:15], v[196:199], v[180:183], v[12:15]
	v_mfma_f32_16x16x32_bf16 v[8:11], v[204:207], v[180:183], v[8:11]
	v_mfma_f32_16x16x32_bf16 v[4:7], v[196:199], v[188:191], v[4:7]
	v_mfma_f32_16x16x32_bf16 v[0:3], v[204:207], v[188:191], v[0:3]
	v_mfma_f32_16x16x32_bf16 v[44:47], v[200:203], v[168:171], v[44:47]
	v_mfma_f32_16x16x32_bf16 v[40:43], v[208:211], v[168:171], v[40:43]
	v_mfma_f32_16x16x32_bf16 v[28:31], v[200:203], v[176:179], v[28:31]
	v_mfma_f32_16x16x32_bf16 v[24:27], v[208:211], v[176:179], v[24:27]
	v_mfma_f32_16x16x32_bf16 v[12:15], v[200:203], v[184:187], v[12:15]
	v_mfma_f32_16x16x32_bf16 v[8:11], v[208:211], v[184:187], v[8:11]
	s_add_i32 s52, 0, 0x18000
	v_add_u32_e32 v147, s52, v143
	v_mfma_f32_16x16x32_bf16 v[4:7], v[200:203], v[192:195], v[4:7]
	v_mfma_f32_16x16x32_bf16 v[0:3], v[208:211], v[192:195], v[0:3]
	s_barrier
	ds_read_b128 v[148:151], v147
	ds_read_b128 v[152:155], v147 offset:1024
	ds_read_b128 v[156:159], v147 offset:2048
	ds_read_b128 v[160:163], v147 offset:3072
	s_add_u32 s16, s22, 0x40000
	s_addc_u32 s17, s23, 0
	s_mov_b32 m0, s34
	v_lshl_add_u64 v[196:197], s[16:17], 0, v[130:131]
	ds_read_b128 v[164:167], v145 offset:32768
	ds_read_b128 v[168:171], v145 offset:33792
	ds_read_b128 v[172:175], v145 offset:34816
	ds_read_b128 v[176:179], v145 offset:35840
	ds_read_b128 v[180:183], v145 offset:36864
	ds_read_b128 v[184:187], v145 offset:37888
	ds_read_b128 v[188:191], v145 offset:38912
	ds_read_b128 v[192:195], v145 offset:39936
	global_load_lds_dwordx4 v[196:197], off
	v_lshl_add_u64 v[196:197], s[16:17], 0, v[128:129]
	s_mov_b32 m0, s35
	s_nop 0
	global_load_lds_dwordx4 v[196:197], off
	s_waitcnt lgkmcnt(8)
	s_barrier
	s_waitcnt lgkmcnt(0)
	s_waitcnt lgkmcnt(0)
	v_mfma_f32_16x16x32_bf16 v[124:127], v[148:151], v[164:167], v[124:127]
	v_mfma_f32_16x16x32_bf16 v[120:123], v[156:159], v[164:167], v[120:123]
	v_mfma_f32_16x16x32_bf16 v[116:119], v[148:151], v[172:175], v[116:119]
	v_mfma_f32_16x16x32_bf16 v[112:115], v[156:159], v[172:175], v[112:115]
	v_mfma_f32_16x16x32_bf16 v[100:103], v[148:151], v[180:183], v[100:103]
	v_mfma_f32_16x16x32_bf16 v[96:99], v[156:159], v[180:183], v[96:99]
	v_mfma_f32_16x16x32_bf16 v[84:87], v[148:151], v[188:191], v[84:87]
	v_mfma_f32_16x16x32_bf16 v[80:83], v[156:159], v[188:191], v[80:83]
	v_mfma_f32_16x16x32_bf16 v[124:127], v[152:155], v[168:171], v[124:127]
	v_mfma_f32_16x16x32_bf16 v[120:123], v[160:163], v[168:171], v[120:123]
	v_mfma_f32_16x16x32_bf16 v[116:119], v[152:155], v[176:179], v[116:119]
	v_mfma_f32_16x16x32_bf16 v[112:115], v[160:163], v[176:179], v[112:115]
	v_mfma_f32_16x16x32_bf16 v[100:103], v[152:155], v[184:187], v[100:103]
	v_mfma_f32_16x16x32_bf16 v[96:99], v[160:163], v[184:187], v[96:99]
	v_mfma_f32_16x16x32_bf16 v[84:87], v[152:155], v[192:195], v[84:87]
	v_mfma_f32_16x16x32_bf16 v[80:83], v[160:163], v[192:195], v[80:83]
	s_barrier
	s_add_i32 s22, 0, 0x1c000
	s_add_i32 s16, s52, s29
	v_add_u32_e32 v147, s22, v143
	v_lshl_add_u64 v[212:213], v[212:213], 0, s[8:9]
	s_mov_b32 m0, s16
	ds_read_b128 v[196:199], v147
	ds_read_b128 v[200:203], v147 offset:1024
	ds_read_b128 v[204:207], v147 offset:2048
	ds_read_b128 v[208:211], v147 offset:3072
	global_load_lds_dwordx4 v[212:213], off
	v_lshl_add_u64 v[212:213], v[214:215], 0, s[8:9]
	s_add_i32 m0, s16, 0x2000
	s_nop 0
	global_load_lds_dwordx4 v[212:213], off
	s_barrier
	s_waitcnt lgkmcnt(0)
	s_waitcnt lgkmcnt(0)
	v_mfma_f32_16x16x32_bf16 v[108:111], v[196:199], v[164:167], v[108:111]
	v_mfma_f32_16x16x32_bf16 v[104:107], v[204:207], v[164:167], v[104:107]
	v_mfma_f32_16x16x32_bf16 v[92:95], v[196:199], v[172:175], v[92:95]
	v_mfma_f32_16x16x32_bf16 v[88:91], v[204:207], v[172:175], v[88:91]
	v_mfma_f32_16x16x32_bf16 v[76:79], v[196:199], v[180:183], v[76:79]
	v_mfma_f32_16x16x32_bf16 v[72:75], v[204:207], v[180:183], v[72:75]
	v_mfma_f32_16x16x32_bf16 v[68:71], v[196:199], v[188:191], v[68:71]
	v_mfma_f32_16x16x32_bf16 v[64:67], v[204:207], v[188:191], v[64:67]
	v_mfma_f32_16x16x32_bf16 v[108:111], v[200:203], v[168:171], v[108:111]
	v_mfma_f32_16x16x32_bf16 v[104:107], v[208:211], v[168:171], v[104:107]
	v_mfma_f32_16x16x32_bf16 v[92:95], v[200:203], v[176:179], v[92:95]
	v_mfma_f32_16x16x32_bf16 v[88:91], v[208:211], v[176:179], v[88:91]
	v_mfma_f32_16x16x32_bf16 v[76:79], v[200:203], v[184:187], v[76:79]
	v_mfma_f32_16x16x32_bf16 v[72:75], v[208:211], v[184:187], v[72:75]
	s_mov_b32 m0, s36
	v_lshl_add_u64 v[212:213], v[216:217], 0, s[8:9]
	v_mfma_f32_16x16x32_bf16 v[68:71], v[200:203], v[192:195], v[68:71]
	v_mfma_f32_16x16x32_bf16 v[64:67], v[208:211], v[192:195], v[64:67]
	s_barrier
	ds_read_b128 v[164:167], v145 offset:49152
	ds_read_b128 v[168:171], v145 offset:50176
	ds_read_b128 v[172:175], v145 offset:51200
	ds_read_b128 v[176:179], v145 offset:52224
	ds_read_b128 v[180:183], v145 offset:53248
	ds_read_b128 v[184:187], v145 offset:54272
	ds_read_b128 v[188:191], v145 offset:55296
	ds_read_b128 v[192:195], v145 offset:56320
	global_load_lds_dwordx4 v[212:213], off
	v_lshl_add_u64 v[212:213], v[218:219], 0, s[8:9]
	s_mov_b32 m0, s37
	s_nop 0
	global_load_lds_dwordx4 v[212:213], off
	s_barrier
; #define STG(P, GB) do { const char* _gb = (GB); \
;     _Pragma("unroll") for (int _i = 0; _i < 2; ++_i) { \
;       __builtin_amdgcn_global_load_lds((const unsigned*)(_gb + voff[_i]), \
;         (LAS unsigned*)((LAS char*)(P) + ldsw + _i * 8192), 16, 0, 0); } } while (0)
; #define MMA(ai, bj, At_, Bt_) do { __builtin_amdgcn_s_setprio(1); \
;     _Pragma("unroll") for (int m = 0; m < 4; ++m) _Pragma("unroll") for (int n = 0; n < 2; ++n) _Pragma("unroll") for (int k = 0; k < 2; ++k) \
;       acc[ai][bj][m][n] = __builtin_amdgcn_mfma_f32_16x16x32_bf16(Bt_[n][k], At_[m][k], acc[ai][bj][m][n], 0, 0, 0); \
;     __builtin_amdgcn_s_setprio(0); } while (0)
; #define WAIT_V(n) asm volatile("s_waitcnt vmcnt(" #n ")" ::: "memory")
; #define WAIT_L(n) asm volatile("s_waitcnt lgkmcnt(" #n ")" ::: "memory")
; #define BAR __builtin_amdgcn_s_barrier()
; #define SCHED __builtin_amdgcn_sched_barrier(0)
; __device__ __forceinline__ void gemm_phase(const bf16_t* __restrict__ A, const bf16_t* __restrict__ Bt, bf16_t* __restrict__ C, int M, int N, int K,
;                                            int ldc, const int EPI, char* smem, const int wid_u) {
;     ...
;       BAR; WAIT_L(0); MMA(1, 0, At, B0); BAR; SCHED;
;       STG(SB(1, 1), b3 + hstep);
;       WAIT_V(6); BAR; MMA(1, 1, At, B1); BAR;
;     }
;     {
;       const int brow = pm * BM, bcol = pn * BM;
; #pragma unroll
;       for (int ai = 0; ai < 2; ++ai)
; #pragma unroll
;         for (int m = 0; m < 4; ++m) {
;           const size_t row = (size_t)(brow + ai * HALF + wr * 64 + m * 16 + fr);
;           if (EPI == 0) {
; #pragma unroll
;             for (int bj = 0; bj < 2; ++bj) {
;               const f32x4 v0 = acc[ai][bj][m][0], v1 = acc[ai][bj][m][1];
;               uint4 u; u.x = cvt_pk_bf16(v0[0], v0[1]); u.y = cvt_pk_bf16(v0[2], v0[3]); u.z = cvt_pk_bf16(v1[0], v1[1]); u.w = cvt_pk_bf16(v1[2], v1[3]);
;               *(uint4*)(C + row * ldc + bcol + bj * HALF + wc * 32 + fq * 8) = u;
;             }
	s_waitcnt lgkmcnt(0)
	s_waitcnt lgkmcnt(0)
	v_mfma_f32_16x16x32_bf16 v[60:63], v[148:151], v[164:167], v[60:63]
	v_mfma_f32_16x16x32_bf16 v[56:59], v[156:159], v[164:167], v[56:59]
	v_mfma_f32_16x16x32_bf16 v[52:55], v[148:151], v[172:175], v[52:55]
	v_mfma_f32_16x16x32_bf16 v[48:51], v[156:159], v[172:175], v[48:51]
	v_mfma_f32_16x16x32_bf16 v[36:39], v[148:151], v[180:183], v[36:39]
	v_mfma_f32_16x16x32_bf16 v[32:35], v[156:159], v[180:183], v[32:35]
	v_mfma_f32_16x16x32_bf16 v[20:23], v[148:151], v[188:191], v[20:23]
	v_mfma_f32_16x16x32_bf16 v[16:19], v[156:159], v[188:191], v[16:19]
	v_mfma_f32_16x16x32_bf16 v[60:63], v[152:155], v[168:171], v[60:63]
	v_mfma_f32_16x16x32_bf16 v[56:59], v[160:163], v[168:171], v[56:59]
	v_mfma_f32_16x16x32_bf16 v[52:55], v[152:155], v[176:179], v[52:55]
	v_mfma_f32_16x16x32_bf16 v[48:51], v[160:163], v[176:179], v[48:51]
	v_mfma_f32_16x16x32_bf16 v[36:39], v[152:155], v[184:187], v[36:39]
	v_mfma_f32_16x16x32_bf16 v[32:35], v[160:163], v[184:187], v[32:35]
	v_mfma_f32_16x16x32_bf16 v[20:23], v[152:155], v[192:195], v[20:23]
	v_mfma_f32_16x16x32_bf16 v[16:19], v[160:163], v[192:195], v[16:19]
	s_barrier
	s_add_u32 s16, s20, 0x40080
	s_addc_u32 s17, s21, 0
	s_add_i32 s20, s22, s29
	v_lshl_add_u64 v[148:149], s[16:17], 0, v[130:131]
	s_mov_b32 m0, s20
	s_nop 0
	global_load_lds_dwordx4 v[148:149], off
	v_lshl_add_u64 v[148:149], s[16:17], 0, v[128:129]
	s_add_i32 m0, s20, 0x2000
	s_nop 0
	global_load_lds_dwordx4 v[148:149], off
	s_waitcnt vmcnt(6)
	s_barrier
	v_mfma_f32_16x16x32_bf16 v[44:47], v[196:199], v[164:167], v[44:47]
	v_mfma_f32_16x16x32_bf16 v[40:43], v[204:207], v[164:167], v[40:43]
	v_mfma_f32_16x16x32_bf16 v[28:31], v[196:199], v[172:175], v[28:31]
	v_mfma_f32_16x16x32_bf16 v[24:27], v[204:207], v[172:175], v[24:27]
	v_mfma_f32_16x16x32_bf16 v[12:15], v[196:199], v[180:183], v[12:15]
	v_mfma_f32_16x16x32_bf16 v[8:11], v[204:207], v[180:183], v[8:11]
	v_mfma_f32_16x16x32_bf16 v[4:7], v[196:199], v[188:191], v[4:7]
	v_mfma_f32_16x16x32_bf16 v[0:3], v[204:207], v[188:191], v[0:3]
	v_mfma_f32_16x16x32_bf16 v[44:47], v[200:203], v[168:171], v[44:47]
	v_mfma_f32_16x16x32_bf16 v[40:43], v[208:211], v[168:171], v[40:43]
	v_mfma_f32_16x16x32_bf16 v[28:31], v[200:203], v[176:179], v[28:31]
	v_mfma_f32_16x16x32_bf16 v[24:27], v[208:211], v[176:179], v[24:27]
	v_mfma_f32_16x16x32_bf16 v[12:15], v[200:203], v[184:187], v[12:15]
	v_mfma_f32_16x16x32_bf16 v[8:11], v[208:211], v[184:187], v[8:11]
	s_add_i32 s51, s51, 2
	s_add_u32 s49, s49, 0x100
	s_addc_u32 s50, s50, 0
	s_cmp_gt_u32 s51, 13
	s_mov_b64 s[16:17], s[18:19]
	v_mfma_f32_16x16x32_bf16 v[4:7], v[200:203], v[192:195], v[4:7]
	v_mfma_f32_16x16x32_bf16 v[0:3], v[208:211], v[192:195], v[0:3]
	s_barrier
	s_cbranch_scc0 .LBB0_334
	v_lshl_add_u32 v147, s44, 8, v142
	s_lshl_b32 s16, s45, 9
	s_mov_b32 s17, s7
	v_lshl_add_u64 v[148:149], v[132:133], 0, s[16:17]
	v_cvt_pk_bf16_f32 v68, v68, v69
	v_cvt_pk_bf16_f32 v69, v70, v71
	v_cvt_pk_bf16_f32 v70, v64, v65
	v_add_u32_e32 v64, 0x80, v147
	v_mad_i64_i32 v[150:151], s[16:17], v147, s40, v[148:149]
	v_cvt_pk_bf16_f32 v108, v108, v109
	v_cvt_pk_bf16_f32 v109, v110, v111
	v_cvt_pk_bf16_f32 v110, v104, v105
	v_cvt_pk_bf16_f32 v111, v106, v107
	v_or_b32_e32 v104, 16, v147
	v_mad_i64_i32 v[64:65], s[16:17], v64, s40, v[148:149]
	v_cvt_pk_bf16_f32 v44, v44, v45
	v_cvt_pk_bf16_f32 v45, v46, v47
	v_cvt_pk_bf16_f32 v46, v40, v41
	v_cvt_pk_bf16_f32 v47, v42, v43
	v_add_u32_e32 v40, 0x90, v147
	global_store_dwordx4 v[150:151], v[108:111], off offset:256
	v_cvt_pk_bf16_f32 v92, v92, v93
	v_cvt_pk_bf16_f32 v93, v94, v95
	v_mad_i64_i32 v[108:109], s[16:17], v104, s40, v[148:149]
	v_cvt_pk_bf16_f32 v94, v88, v89
	v_cvt_pk_bf16_f32 v95, v90, v91
	v_or_b32_e32 v88, 32, v147
	global_store_dwordx4 v[64:65], v[44:47], off offset:256
	v_cvt_pk_bf16_f32 v28, v28, v29
	v_cvt_pk_bf16_f32 v29, v30, v31
	v_mad_i64_i32 v[44:45], s[16:17], v40, s40, v[148:149]
	v_cvt_pk_bf16_f32 v30, v24, v25
	v_cvt_pk_bf16_f32 v31, v26, v27
	v_add_u32_e32 v24, 0xa0, v147
	global_store_dwordx4 v[108:109], v[92:95], off offset:256
	v_cvt_pk_bf16_f32 v76, v76, v77
	v_cvt_pk_bf16_f32 v77, v78, v79
	v_mad_i64_i32 v[92:93], s[16:17], v88, s40, v[148:149]
	v_cvt_pk_bf16_f32 v78, v72, v73
	v_cvt_pk_bf16_f32 v79, v74, v75
	v_or_b32_e32 v72, 48, v147
	global_store_dwordx4 v[44:45], v[28:31], off offset:256
	v_cvt_pk_bf16_f32 v12, v12, v13
	v_cvt_pk_bf16_f32 v13, v14, v15
	v_mad_i64_i32 v[28:29], s[16:17], v24, s40, v[148:149]
	v_cvt_pk_bf16_f32 v14, v8, v9
	v_cvt_pk_bf16_f32 v15, v10, v11
	v_add_u32_e32 v8, 0xb0, v147
	global_store_dwordx4 v[92:93], v[76:79], off offset:256
	global_store_dwordx4 v[28:29], v[12:15], off offset:256
	v_cvt_pk_bf16_f32 v124, v124, v125
	v_mad_i64_i32 v[76:77], s[16:17], v72, s40, v[148:149]
	v_mad_i64_i32 v[12:13], s[16:17], v8, s40, v[148:149]
	v_cvt_pk_bf16_f32 v125, v126, v127
	v_cvt_pk_bf16_f32 v126, v120, v121
	v_cvt_pk_bf16_f32 v127, v122, v123
	v_cvt_pk_bf16_f32 v104, v116, v117
	v_cvt_pk_bf16_f32 v105, v118, v119
	v_cvt_pk_bf16_f32 v106, v112, v113
	v_cvt_pk_bf16_f32 v107, v114, v115
	v_cvt_pk_bf16_f32 v88, v100, v101
	v_cvt_pk_bf16_f32 v89, v102, v103
	v_cvt_pk_bf16_f32 v90, v96, v97
	v_cvt_pk_bf16_f32 v91, v98, v99
	v_cvt_pk_bf16_f32 v72, v84, v85
	v_cvt_pk_bf16_f32 v73, v86, v87
	v_cvt_pk_bf16_f32 v74, v80, v81
	v_cvt_pk_bf16_f32 v75, v82, v83
	v_cvt_pk_bf16_f32 v71, v66, v67
	v_cvt_pk_bf16_f32 v60, v60, v61
	v_cvt_pk_bf16_f32 v61, v62, v63
	v_cvt_pk_bf16_f32 v62, v56, v57
	v_cvt_pk_bf16_f32 v63, v58, v59
	v_cvt_pk_bf16_f32 v40, v52, v53
	v_cvt_pk_bf16_f32 v41, v54, v55
	v_cvt_pk_bf16_f32 v42, v48, v49
	v_cvt_pk_bf16_f32 v43, v50, v51
	v_cvt_pk_bf16_f32 v24, v36, v37
	v_cvt_pk_bf16_f32 v25, v38, v39
	v_cvt_pk_bf16_f32 v26, v32, v33
	v_cvt_pk_bf16_f32 v27, v34, v35
	v_cvt_pk_bf16_f32 v8, v20, v21
	v_cvt_pk_bf16_f32 v9, v22, v23
	v_cvt_pk_bf16_f32 v10, v16, v17
	v_cvt_pk_bf16_f32 v11, v18, v19
	v_cvt_pk_bf16_f32 v4, v4, v5
	v_cvt_pk_bf16_f32 v5, v6, v7
	v_cvt_pk_bf16_f32 v6, v0, v1
	v_cvt_pk_bf16_f32 v7, v2, v3
	s_and_b64 vcc, exec, s[2:3]
	s_mov_b32 s44, s6
	s_mov_b32 s45, s10
	s_mov_b64 s[18:19], s[14:15]
	s_mov_b64 s[16:17], s[12:13]
	global_store_dwordx4 v[150:151], v[124:127], off
	global_store_dwordx4 v[108:109], v[104:107], off
	global_store_dwordx4 v[92:93], v[88:91], off
	global_store_dwordx4 v[76:77], v[72:75], off
	global_store_dwordx4 v[76:77], v[68:71], off offset:256
	global_store_dwordx4 v[64:65], v[60:63], off
	global_store_dwordx4 v[44:45], v[40:43], off
	global_store_dwordx4 v[28:29], v[24:27], off
	global_store_dwordx4 v[12:13], v[8:11], off
	global_store_dwordx4 v[12:13], v[4:7], off offset:256
	s_cbranch_vccz .LBB0_331
	s_waitcnt vmcnt(0)
	s_cmpk_gt_u32 s24, 0xff
	s_cbranch_scc1 .LBB0_338
	s_barrier

; #define STG(P, GB) do { const char* _gb = (GB); \
;     _Pragma("unroll") for (int _i = 0; _i < 2; ++_i) { \
;       __builtin_amdgcn_global_load_lds((const unsigned*)(_gb + voff[_i]), \
;         (LAS unsigned*)((LAS char*)(P) + ldsw + _i * 8192), 16, 0, 0); } } while (0)
; #define LDA(dst, b, h) _Pragma("unroll") for (int m = 0; m < 4; ++m) _Pragma("unroll") for (int k = 0; k < 2; ++k) \
;     dst[m][k] = *(const LAS bf16x8*)((LAS char*)SA(b, h) + aoff + m * 2048 + k * 1024)
; #define LDB(dst, b, h) _Pragma("unroll") for (int n = 0; n < 2; ++n) _Pragma("unroll") for (int k = 0; k < 2; ++k) \
;     dst[n][k] = *(const LAS bf16x8*)((LAS char*)SB(b, h) + boff + n * 2048 + k * 1024)
; #define MMA(ai, bj, At_, Bt_) do { __builtin_amdgcn_s_setprio(1); \
;     _Pragma("unroll") for (int m = 0; m < 4; ++m) _Pragma("unroll") for (int n = 0; n < 2; ++n) _Pragma("unroll") for (int k = 0; k < 2; ++k) \
;       acc[ai][bj][m][n] = __builtin_amdgcn_mfma_f32_16x16x32_bf16(Bt_[n][k], At_[m][k], acc[ai][bj][m][n], 0, 0, 0); \
;     __builtin_amdgcn_s_setprio(0); } while (0)
; #define WAIT_L(n) asm volatile("s_waitcnt lgkmcnt(" #n ")" ::: "memory")
; #define BAR __builtin_amdgcn_s_barrier()
; #define SCHED __builtin_amdgcn_sched_barrier(0)
; __device__ __forceinline__ void gemm_phase(const bf16_t* __restrict__ A, const bf16_t* __restrict__ Bt, bf16_t* __restrict__ C, int M, int N, int K,
;                                            int ldc, const int EPI, char* smem, const int wid_u) {
;     ...
;       LDB(B0, 0, 0); SCHED; LDA(At, 0, 0); STG(SA(1, 1), a1 + hstep);
;       WAIT_L(8); BAR; WAIT_L(0); MMA(0, 0, At, B0); BAR; SCHED;
;       LDB(B1, 0, 1); STG(SB(0, 0), b2);
;       BAR; WAIT_L(0); MMA(0, 1, At, B1); BAR;
;       LDA(At, 0, 1); STG(SA(0, 0), a2);
;       BAR; WAIT_L(0); MMA(1, 0, At, B0); BAR; SCHED;
.LBB0_905:
	ds_read_b128 v[148:151], v144
	ds_read_b128 v[152:155], v144 offset:1024
	ds_read_b128 v[156:159], v144 offset:2048
	ds_read_b128 v[160:163], v144 offset:3072
	s_add_u32 s18, s16, 0x100
	s_addc_u32 s19, s17, 0
	s_cmp_eq_u32 s55, 12
	s_cselect_b32 s23, s49, s19
	s_cselect_b32 s22, s50, s18
	s_cselect_b32 s21, s51, s54
	s_cselect_b32 s20, s52, s53
	s_mov_b32 m0, s38
	v_lshl_add_u64 v[196:197], s[16:17], 0, v[136:137]
	ds_read_b128 v[164:167], v145
	ds_read_b128 v[168:171], v145 offset:1024
	ds_read_b128 v[172:175], v145 offset:2048
	ds_read_b128 v[176:179], v145 offset:3072
	ds_read_b128 v[180:183], v145 offset:4096
	ds_read_b128 v[184:187], v145 offset:5120
	ds_read_b128 v[188:191], v145 offset:6144
	ds_read_b128 v[192:195], v145 offset:7168
	global_load_lds_dwordx4 v[196:197], off
	v_lshl_add_u64 v[196:197], s[16:17], 0, v[134:135]
	s_mov_b32 m0, s39
	s_nop 0
	global_load_lds_dwordx4 v[196:197], off
	s_waitcnt lgkmcnt(8)
	s_barrier
	s_waitcnt lgkmcnt(0)
	s_waitcnt lgkmcnt(0)
	v_mfma_f32_16x16x32_bf16 v[124:127], v[148:151], v[164:167], v[124:127]
	v_mfma_f32_16x16x32_bf16 v[120:123], v[156:159], v[164:167], v[120:123]
	v_mfma_f32_16x16x32_bf16 v[116:119], v[148:151], v[172:175], v[116:119]
	v_mfma_f32_16x16x32_bf16 v[112:115], v[156:159], v[172:175], v[112:115]
	v_mfma_f32_16x16x32_bf16 v[100:103], v[148:151], v[180:183], v[100:103]
	v_mfma_f32_16x16x32_bf16 v[96:99], v[156:159], v[180:183], v[96:99]
	v_mfma_f32_16x16x32_bf16 v[84:87], v[148:151], v[188:191], v[84:87]
	v_mfma_f32_16x16x32_bf16 v[80:83], v[156:159], v[188:191], v[80:83]
	v_mfma_f32_16x16x32_bf16 v[124:127], v[152:155], v[168:171], v[124:127]
	v_mfma_f32_16x16x32_bf16 v[120:123], v[160:163], v[168:171], v[120:123]
	v_mfma_f32_16x16x32_bf16 v[116:119], v[152:155], v[176:179], v[116:119]
	v_mfma_f32_16x16x32_bf16 v[112:115], v[160:163], v[176:179], v[112:115]
	v_mfma_f32_16x16x32_bf16 v[100:103], v[152:155], v[184:187], v[100:103]
	v_mfma_f32_16x16x32_bf16 v[96:99], v[160:163], v[184:187], v[96:99]
	v_mfma_f32_16x16x32_bf16 v[84:87], v[152:155], v[192:195], v[84:87]
	v_mfma_f32_16x16x32_bf16 v[80:83], v[160:163], v[192:195], v[80:83]
	s_barrier
	s_mov_b32 m0, s40
	v_lshl_add_u64 v[212:213], s[20:21], 0, v[130:131]
	ds_read_b128 v[196:199], v146
	ds_read_b128 v[200:203], v146 offset:1024
	ds_read_b128 v[204:207], v146 offset:2048
	ds_read_b128 v[208:211], v146 offset:3072
	global_load_lds_dwordx4 v[212:213], off
	v_lshl_add_u64 v[214:215], s[20:21], 0, v[128:129]
	s_mov_b32 m0, s41
	s_nop 0
	global_load_lds_dwordx4 v[214:215], off
	s_barrier
	s_waitcnt lgkmcnt(0)
	s_waitcnt lgkmcnt(0)
	v_mfma_f32_16x16x32_bf16 v[108:111], v[196:199], v[164:167], v[108:111]
	v_mfma_f32_16x16x32_bf16 v[104:107], v[204:207], v[164:167], v[104:107]
	v_mfma_f32_16x16x32_bf16 v[92:95], v[196:199], v[172:175], v[92:95]
	v_mfma_f32_16x16x32_bf16 v[88:91], v[204:207], v[172:175], v[88:91]
	v_mfma_f32_16x16x32_bf16 v[76:79], v[196:199], v[180:183], v[76:79]
	v_mfma_f32_16x16x32_bf16 v[72:75], v[204:207], v[180:183], v[72:75]
	v_mfma_f32_16x16x32_bf16 v[68:71], v[196:199], v[188:191], v[68:71]
	v_mfma_f32_16x16x32_bf16 v[64:67], v[204:207], v[188:191], v[64:67]
	v_mfma_f32_16x16x32_bf16 v[108:111], v[200:203], v[168:171], v[108:111]
	v_mfma_f32_16x16x32_bf16 v[104:107], v[208:211], v[168:171], v[104:107]
	v_mfma_f32_16x16x32_bf16 v[92:95], v[200:203], v[176:179], v[92:95]
	v_mfma_f32_16x16x32_bf16 v[88:91], v[208:211], v[176:179], v[88:91]
	v_mfma_f32_16x16x32_bf16 v[76:79], v[200:203], v[184:187], v[76:79]
	v_mfma_f32_16x16x32_bf16 v[72:75], v[208:211], v[184:187], v[72:75]
	s_mov_b32 m0, s30
	v_lshl_add_u64 v[216:217], s[22:23], 0, v[130:131]
	v_mfma_f32_16x16x32_bf16 v[68:71], v[200:203], v[192:195], v[68:71]
	v_mfma_f32_16x16x32_bf16 v[64:67], v[208:211], v[192:195], v[64:67]
	s_barrier
	ds_read_b128 v[164:167], v145 offset:16384
	ds_read_b128 v[168:171], v145 offset:17408
	ds_read_b128 v[172:175], v145 offset:18432
	ds_read_b128 v[176:179], v145 offset:19456
	ds_read_b128 v[180:183], v145 offset:20480
	ds_read_b128 v[184:187], v145 offset:21504
	ds_read_b128 v[188:191], v145 offset:22528
	ds_read_b128 v[192:195], v145 offset:23552
	global_load_lds_dwordx4 v[216:217], off
	v_lshl_add_u64 v[218:219], s[22:23], 0, v[128:129]
	s_mov_b32 m0, s31
	s_nop 0
	global_load_lds_dwordx4 v[218:219], off
	s_barrier
	s_waitcnt lgkmcnt(0)
	s_waitcnt lgkmcnt(0)
	v_mfma_f32_16x16x32_bf16 v[60:63], v[148:151], v[164:167], v[60:63]
	v_mfma_f32_16x16x32_bf16 v[56:59], v[156:159], v[164:167], v[56:59]
	v_mfma_f32_16x16x32_bf16 v[52:55], v[148:151], v[172:175], v[52:55]
	v_mfma_f32_16x16x32_bf16 v[48:51], v[156:159], v[172:175], v[48:51]
	v_mfma_f32_16x16x32_bf16 v[36:39], v[148:151], v[180:183], v[36:39]
	v_mfma_f32_16x16x32_bf16 v[32:35], v[156:159], v[180:183], v[32:35]
	v_mfma_f32_16x16x32_bf16 v[20:23], v[148:151], v[188:191], v[20:23]
	v_mfma_f32_16x16x32_bf16 v[16:19], v[156:159], v[188:191], v[16:19]
	v_mfma_f32_16x16x32_bf16 v[60:63], v[152:155], v[168:171], v[60:63]
	v_mfma_f32_16x16x32_bf16 v[56:59], v[160:163], v[168:171], v[56:59]
	v_mfma_f32_16x16x32_bf16 v[52:55], v[152:155], v[176:179], v[52:55]
	v_mfma_f32_16x16x32_bf16 v[48:51], v[160:163], v[176:179], v[48:51]
	v_mfma_f32_16x16x32_bf16 v[36:39], v[152:155], v[184:187], v[36:39]
	v_mfma_f32_16x16x32_bf16 v[32:35], v[160:163], v[184:187], v[32:35]
	v_mfma_f32_16x16x32_bf16 v[20:23], v[152:155], v[192:195], v[20:23]
	v_mfma_f32_16x16x32_bf16 v[16:19], v[160:163], v[192:195], v[16:19]
	s_barrier
; #define STG(P, GB) do { const char* _gb = (GB); \
;     _Pragma("unroll") for (int _i = 0; _i < 2; ++_i) { \
;       __builtin_amdgcn_global_load_lds((const unsigned*)(_gb + voff[_i]), \
;         (LAS unsigned*)((LAS char*)(P) + ldsw + _i * 8192), 16, 0, 0); } } while (0)
; #define LDA(dst, b, h) _Pragma("unroll") for (int m = 0; m < 4; ++m) _Pragma("unroll") for (int k = 0; k < 2; ++k) \
;     dst[m][k] = *(const LAS bf16x8*)((LAS char*)SA(b, h) + aoff + m * 2048 + k * 1024)
; #define LDB(dst, b, h) _Pragma("unroll") for (int n = 0; n < 2; ++n) _Pragma("unroll") for (int k = 0; k < 2; ++k) \
;     dst[n][k] = *(const LAS bf16x8*)((LAS char*)SB(b, h) + boff + n * 2048 + k * 1024)
; #define MMA(ai, bj, At_, Bt_) do { __builtin_amdgcn_s_setprio(1); \
;     _Pragma("unroll") for (int m = 0; m < 4; ++m) _Pragma("unroll") for (int n = 0; n < 2; ++n) _Pragma("unroll") for (int k = 0; k < 2; ++k) \
;       acc[ai][bj][m][n] = __builtin_amdgcn_mfma_f32_16x16x32_bf16(Bt_[n][k], At_[m][k], acc[ai][bj][m][n], 0, 0, 0); \
;     __builtin_amdgcn_s_setprio(0); } while (0)
; #define WAIT_V(n) asm volatile("s_waitcnt vmcnt(" #n ")" ::: "memory")
; #define WAIT_L(n) asm volatile("s_waitcnt lgkmcnt(" #n ")" ::: "memory")
; #define BAR __builtin_amdgcn_s_barrier()
; #define SCHED __builtin_amdgcn_sched_barrier(0)
; __device__ __forceinline__ void gemm_phase(const bf16_t* __restrict__ A, const bf16_t* __restrict__ Bt, bf16_t* __restrict__ C, int M, int N, int K,
;                                            int ldc, const int EPI, char* smem, const int wid_u) {
;     ...
;       STG(SB(0, 1), b2 + hstep);
;       WAIT_V(6); BAR; MMA(1, 1, At, B1); BAR;
;       LDB(B0, 1, 0); SCHED; LDA(At, 1, 0); STG(SA(0, 1), a2 + hstep);
;       WAIT_L(8); BAR; WAIT_L(0); MMA(0, 0, At, B0); BAR; SCHED;
;       LDB(B1, 1, 1); STG(SB(1, 0), b3);
;       BAR; WAIT_L(0); MMA(0, 1, At, B1); BAR;
;       LDA(At, 1, 1); STG(SA(1, 0), a3);
	s_add_u32 s16, s20, 0x40000
	s_addc_u32 s17, s21, 0
	s_mov_b32 m0, s44
	v_lshl_add_u64 v[148:149], s[16:17], 0, v[130:131]
	global_load_lds_dwordx4 v[148:149], off
	v_lshl_add_u64 v[148:149], s[16:17], 0, v[128:129]
	s_add_i32 m0, s44, 0x2000
	s_nop 0
	global_load_lds_dwordx4 v[148:149], off
	s_waitcnt vmcnt(6)
	s_barrier
	v_mfma_f32_16x16x32_bf16 v[44:47], v[196:199], v[164:167], v[44:47]
	v_mfma_f32_16x16x32_bf16 v[40:43], v[204:207], v[164:167], v[40:43]
	v_mfma_f32_16x16x32_bf16 v[28:31], v[196:199], v[172:175], v[28:31]
	v_mfma_f32_16x16x32_bf16 v[24:27], v[204:207], v[172:175], v[24:27]
	v_mfma_f32_16x16x32_bf16 v[12:15], v[196:199], v[180:183], v[12:15]
	v_mfma_f32_16x16x32_bf16 v[8:11], v[204:207], v[180:183], v[8:11]
	v_mfma_f32_16x16x32_bf16 v[4:7], v[196:199], v[188:191], v[4:7]
	v_mfma_f32_16x16x32_bf16 v[0:3], v[204:207], v[188:191], v[0:3]
	v_mfma_f32_16x16x32_bf16 v[44:47], v[200:203], v[168:171], v[44:47]
	v_mfma_f32_16x16x32_bf16 v[40:43], v[208:211], v[168:171], v[40:43]
	v_mfma_f32_16x16x32_bf16 v[28:31], v[200:203], v[176:179], v[28:31]
	v_mfma_f32_16x16x32_bf16 v[24:27], v[208:211], v[176:179], v[24:27]
	v_mfma_f32_16x16x32_bf16 v[12:15], v[200:203], v[184:187], v[12:15]
	v_mfma_f32_16x16x32_bf16 v[8:11], v[208:211], v[184:187], v[8:11]
	s_add_i32 s56, 0, 0x18000
	v_add_u32_e32 v147, s56, v143
	v_mfma_f32_16x16x32_bf16 v[4:7], v[200:203], v[192:195], v[4:7]
	v_mfma_f32_16x16x32_bf16 v[0:3], v[208:211], v[192:195], v[0:3]
	s_barrier
	ds_read_b128 v[148:151], v147
	ds_read_b128 v[152:155], v147 offset:1024
	ds_read_b128 v[156:159], v147 offset:2048
	ds_read_b128 v[160:163], v147 offset:3072
	s_add_u32 s16, s22, 0x40000
	s_addc_u32 s17, s23, 0
	s_mov_b32 m0, s34
	v_lshl_add_u64 v[196:197], s[16:17], 0, v[130:131]
	ds_read_b128 v[164:167], v145 offset:32768
	ds_read_b128 v[168:171], v145 offset:33792
	ds_read_b128 v[172:175], v145 offset:34816
	ds_read_b128 v[176:179], v145 offset:35840
	ds_read_b128 v[180:183], v145 offset:36864
	ds_read_b128 v[184:187], v145 offset:37888
	ds_read_b128 v[188:191], v145 offset:38912
	ds_read_b128 v[192:195], v145 offset:39936
	global_load_lds_dwordx4 v[196:197], off
	v_lshl_add_u64 v[196:197], s[16:17], 0, v[128:129]
	s_mov_b32 m0, s35
	s_nop 0
	global_load_lds_dwordx4 v[196:197], off
	s_waitcnt lgkmcnt(8)
	s_barrier
	s_waitcnt lgkmcnt(0)
	s_waitcnt lgkmcnt(0)
	v_mfma_f32_16x16x32_bf16 v[124:127], v[148:151], v[164:167], v[124:127]
	v_mfma_f32_16x16x32_bf16 v[120:123], v[156:159], v[164:167], v[120:123]
	v_mfma_f32_16x16x32_bf16 v[116:119], v[148:151], v[172:175], v[116:119]
	v_mfma_f32_16x16x32_bf16 v[112:115], v[156:159], v[172:175], v[112:115]
	v_mfma_f32_16x16x32_bf16 v[100:103], v[148:151], v[180:183], v[100:103]
	v_mfma_f32_16x16x32_bf16 v[96:99], v[156:159], v[180:183], v[96:99]
	v_mfma_f32_16x16x32_bf16 v[84:87], v[148:151], v[188:191], v[84:87]
	v_mfma_f32_16x16x32_bf16 v[80:83], v[156:159], v[188:191], v[80:83]
	v_mfma_f32_16x16x32_bf16 v[124:127], v[152:155], v[168:171], v[124:127]
	v_mfma_f32_16x16x32_bf16 v[120:123], v[160:163], v[168:171], v[120:123]
	v_mfma_f32_16x16x32_bf16 v[116:119], v[152:155], v[176:179], v[116:119]
	v_mfma_f32_16x16x32_bf16 v[112:115], v[160:163], v[176:179], v[112:115]
	v_mfma_f32_16x16x32_bf16 v[100:103], v[152:155], v[184:187], v[100:103]
	v_mfma_f32_16x16x32_bf16 v[96:99], v[160:163], v[184:187], v[96:99]
	v_mfma_f32_16x16x32_bf16 v[84:87], v[152:155], v[192:195], v[84:87]
	v_mfma_f32_16x16x32_bf16 v[80:83], v[160:163], v[192:195], v[80:83]
	s_barrier
	s_add_i32 s22, 0, 0x1c000
	s_add_i32 s16, s56, s29
	v_add_u32_e32 v147, s22, v143
	v_lshl_add_u64 v[212:213], v[212:213], 0, s[10:11]
	s_mov_b32 m0, s16
	ds_read_b128 v[196:199], v147
	ds_read_b128 v[200:203], v147 offset:1024
	ds_read_b128 v[204:207], v147 offset:2048
	ds_read_b128 v[208:211], v147 offset:3072
	global_load_lds_dwordx4 v[212:213], off
	v_lshl_add_u64 v[212:213], v[214:215], 0, s[10:11]
	s_add_i32 m0, s16, 0x2000
	s_nop 0
	global_load_lds_dwordx4 v[212:213], off
	s_barrier
	s_waitcnt lgkmcnt(0)
	s_waitcnt lgkmcnt(0)
	v_mfma_f32_16x16x32_bf16 v[108:111], v[196:199], v[164:167], v[108:111]
	v_mfma_f32_16x16x32_bf16 v[104:107], v[204:207], v[164:167], v[104:107]
	v_mfma_f32_16x16x32_bf16 v[92:95], v[196:199], v[172:175], v[92:95]
	v_mfma_f32_16x16x32_bf16 v[88:91], v[204:207], v[172:175], v[88:91]
	v_mfma_f32_16x16x32_bf16 v[76:79], v[196:199], v[180:183], v[76:79]
	v_mfma_f32_16x16x32_bf16 v[72:75], v[204:207], v[180:183], v[72:75]
	v_mfma_f32_16x16x32_bf16 v[68:71], v[196:199], v[188:191], v[68:71]
	v_mfma_f32_16x16x32_bf16 v[64:67], v[204:207], v[188:191], v[64:67]
	v_mfma_f32_16x16x32_bf16 v[108:111], v[200:203], v[168:171], v[108:111]
	v_mfma_f32_16x16x32_bf16 v[104:107], v[208:211], v[168:171], v[104:107]
	v_mfma_f32_16x16x32_bf16 v[92:95], v[200:203], v[176:179], v[92:95]
	v_mfma_f32_16x16x32_bf16 v[88:91], v[208:211], v[176:179], v[88:91]
	v_mfma_f32_16x16x32_bf16 v[76:79], v[200:203], v[184:187], v[76:79]
	v_mfma_f32_16x16x32_bf16 v[72:75], v[208:211], v[184:187], v[72:75]
	s_mov_b32 m0, s36
	v_lshl_add_u64 v[212:213], v[216:217], 0, s[10:11]
	v_mfma_f32_16x16x32_bf16 v[68:71], v[200:203], v[192:195], v[68:71]
	v_mfma_f32_16x16x32_bf16 v[64:67], v[208:211], v[192:195], v[64:67]
	s_barrier
	ds_read_b128 v[164:167], v145 offset:49152
	ds_read_b128 v[168:171], v145 offset:50176
	ds_read_b128 v[172:175], v145 offset:51200
	ds_read_b128 v[176:179], v145 offset:52224
	ds_read_b128 v[180:183], v145 offset:53248
	ds_read_b128 v[184:187], v145 offset:54272
	ds_read_b128 v[188:191], v145 offset:55296
	ds_read_b128 v[192:195], v145 offset:56320
	global_load_lds_dwordx4 v[212:213], off
	v_lshl_add_u64 v[212:213], v[218:219], 0, s[10:11]
	s_mov_b32 m0, s37
	s_nop 0
	global_load_lds_dwordx4 v[212:213], off
	s_barrier
; #define STG(P, GB) do { const char* _gb = (GB); \
;     _Pragma("unroll") for (int _i = 0; _i < 2; ++_i) { \
;       __builtin_amdgcn_global_load_lds((const unsigned*)(_gb + voff[_i]), \
;         (LAS unsigned*)((LAS char*)(P) + ldsw + _i * 8192), 16, 0, 0); } } while (0)
; #define MMA(ai, bj, At_, Bt_) do { __builtin_amdgcn_s_setprio(1); \
;     _Pragma("unroll") for (int m = 0; m < 4; ++m) _Pragma("unroll") for (int n = 0; n < 2; ++n) _Pragma("unroll") for (int k = 0; k < 2; ++k) \
;       acc[ai][bj][m][n] = __builtin_amdgcn_mfma_f32_16x16x32_bf16(Bt_[n][k], At_[m][k], acc[ai][bj][m][n], 0, 0, 0); \
;     __builtin_amdgcn_s_setprio(0); } while (0)
; #define WAIT_V(n) asm volatile("s_waitcnt vmcnt(" #n ")" ::: "memory")
; #define WAIT_L(n) asm volatile("s_waitcnt lgkmcnt(" #n ")" ::: "memory")
; #define BAR __builtin_amdgcn_s_barrier()
; #define SCHED __builtin_amdgcn_sched_barrier(0)
; __device__ __forceinline__ void gemm_phase(const bf16_t* __restrict__ A, const bf16_t* __restrict__ Bt, bf16_t* __restrict__ C, int M, int N, int K,
;                                            int ldc, const int EPI, char* smem, const int wid_u) {
;     ...
;       BAR; WAIT_L(0); MMA(1, 0, At, B0); BAR; SCHED;
;       STG(SB(1, 1), b3 + hstep);
;       WAIT_V(6); BAR; MMA(1, 1, At, B1); BAR;
;     }
	s_waitcnt lgkmcnt(0)
	s_waitcnt lgkmcnt(0)
	v_mfma_f32_16x16x32_bf16 v[60:63], v[148:151], v[164:167], v[60:63]
	v_mfma_f32_16x16x32_bf16 v[56:59], v[156:159], v[164:167], v[56:59]
	v_mfma_f32_16x16x32_bf16 v[52:55], v[148:151], v[172:175], v[52:55]
	v_mfma_f32_16x16x32_bf16 v[48:51], v[156:159], v[172:175], v[48:51]
	v_mfma_f32_16x16x32_bf16 v[36:39], v[148:151], v[180:183], v[36:39]
	v_mfma_f32_16x16x32_bf16 v[32:35], v[156:159], v[180:183], v[32:35]
	v_mfma_f32_16x16x32_bf16 v[20:23], v[148:151], v[188:191], v[20:23]
	v_mfma_f32_16x16x32_bf16 v[16:19], v[156:159], v[188:191], v[16:19]
	v_mfma_f32_16x16x32_bf16 v[60:63], v[152:155], v[168:171], v[60:63]
	v_mfma_f32_16x16x32_bf16 v[56:59], v[160:163], v[168:171], v[56:59]
	v_mfma_f32_16x16x32_bf16 v[52:55], v[152:155], v[176:179], v[52:55]
	v_mfma_f32_16x16x32_bf16 v[48:51], v[160:163], v[176:179], v[48:51]
	v_mfma_f32_16x16x32_bf16 v[36:39], v[152:155], v[184:187], v[36:39]
	v_mfma_f32_16x16x32_bf16 v[32:35], v[160:163], v[184:187], v[32:35]
	v_mfma_f32_16x16x32_bf16 v[20:23], v[152:155], v[192:195], v[20:23]
	v_mfma_f32_16x16x32_bf16 v[16:19], v[160:163], v[192:195], v[16:19]
	s_barrier
	s_add_u32 s16, s20, 0x40080
	s_addc_u32 s17, s21, 0
	s_add_i32 s20, s22, s29
	v_lshl_add_u64 v[148:149], s[16:17], 0, v[130:131]
	s_mov_b32 m0, s20
	s_nop 0
	global_load_lds_dwordx4 v[148:149], off
	v_lshl_add_u64 v[148:149], s[16:17], 0, v[128:129]
	s_add_i32 m0, s20, 0x2000
	s_nop 0
	global_load_lds_dwordx4 v[148:149], off
	s_waitcnt vmcnt(6)
	s_barrier
	v_mfma_f32_16x16x32_bf16 v[44:47], v[196:199], v[164:167], v[44:47]
	v_mfma_f32_16x16x32_bf16 v[40:43], v[204:207], v[164:167], v[40:43]
	v_mfma_f32_16x16x32_bf16 v[28:31], v[196:199], v[172:175], v[28:31]
	v_mfma_f32_16x16x32_bf16 v[24:27], v[204:207], v[172:175], v[24:27]
	v_mfma_f32_16x16x32_bf16 v[12:15], v[196:199], v[180:183], v[12:15]
	v_mfma_f32_16x16x32_bf16 v[8:11], v[204:207], v[180:183], v[8:11]
	v_mfma_f32_16x16x32_bf16 v[4:7], v[196:199], v[188:191], v[4:7]
	v_mfma_f32_16x16x32_bf16 v[0:3], v[204:207], v[188:191], v[0:3]
	v_mfma_f32_16x16x32_bf16 v[44:47], v[200:203], v[168:171], v[44:47]
	v_mfma_f32_16x16x32_bf16 v[40:43], v[208:211], v[168:171], v[40:43]
	v_mfma_f32_16x16x32_bf16 v[28:31], v[200:203], v[176:179], v[28:31]
	v_mfma_f32_16x16x32_bf16 v[24:27], v[208:211], v[176:179], v[24:27]
	v_mfma_f32_16x16x32_bf16 v[12:15], v[200:203], v[184:187], v[12:15]
	v_mfma_f32_16x16x32_bf16 v[8:11], v[208:211], v[184:187], v[8:11]
	s_add_i32 s55, s55, 2
	s_add_u32 s53, s53, 0x100
	s_addc_u32 s54, s54, 0
	s_cmp_gt_u32 s55, 13
	s_mov_b64 s[16:17], s[18:19]
	v_mfma_f32_16x16x32_bf16 v[4:7], v[200:203], v[192:195], v[4:7]
	v_mfma_f32_16x16x32_bf16 v[0:3], v[208:211], v[192:195], v[0:3]
	s_barrier
	s_cbranch_scc0 .LBB0_905
; #define WAIT_V(n) asm volatile("s_waitcnt vmcnt(" #n ")" ::: "memory")
; #define BAR __builtin_amdgcn_s_barrier()
; __device__ __forceinline__ void gemm_phase(const bf16_t* __restrict__ A, const bf16_t* __restrict__ Bt, bf16_t* __restrict__ C, int M, int N, int K,
;                                            int ldc, const int EPI, char* smem, const int wid_u) {
;     ...
;           if (EPI == 0) {
; #pragma unroll
;             for (int bj = 0; bj < 2; ++bj) {
;               const f32x4 v0 = acc[ai][bj][m][0], v1 = acc[ai][bj][m][1];
;               uint4 u; u.x = cvt_pk_bf16(v0[0], v0[1]); u.y = cvt_pk_bf16(v0[2], v0[3]); u.z = cvt_pk_bf16(v1[0], v1[1]); u.w = cvt_pk_bf16(v1[2], v1[3]);
;               *(uint4*)(C + row * ldc + bcol + bj * HALF + wc * 32 + fq * 8) = u;
;             }
;           } else {
;             float o[8];
; #pragma unroll
;             for (int n = 0; n < 2; ++n) {
;               const f32x4 a = acc[ai][0][m][n], b = acc[ai][1][m][n];
; #pragma unroll
;               for (int j = 0; j < 4; ++j) o[n * 4 + j] = a[j] * __builtin_amdgcn_rcpf(1.f + __expf(-a[j])) * b[j];
;             }
;             *(uint4*)(C + row * ldc + (bcol >> 1) + wc * 32 + fq * 8) = pack8(o);
;           }
;         }
;     }
;     if (!has_next) break;
; #pragma unroll
;     for (int a = 0; a < 2; ++a)
; #pragma unroll
;       for (int b = 0; b < 2; ++b)
; #pragma unroll
;         for (int m = 0; m < 4; ++m)
; #pragma unroll
;           for (int n = 0; n < 2; ++n) acc[a][b][m][n] = (f32x4){0.f, 0.f, 0.f, 0.f};
;     pm = npm; pn = npn; cA = nA; cB = nB; ++ui;
;   }
;   WAIT_V(0);
;   if (wr == 0) BAR;
	v_lshl_add_u32 v148, s47, 8, v142
	v_cvt_pk_bf16_f32 v68, v68, v69
	v_cvt_pk_bf16_f32 v69, v70, v71
	v_cvt_pk_bf16_f32 v70, v64, v65
	v_add_u32_e32 v64, 0x80, v148
	s_lshl_b32 s16, s48, 9
	s_mov_b32 s17, s9
	v_ashrrev_i32_e32 v149, 31, v148
	v_cvt_pk_bf16_f32 v108, v108, v109
	v_cvt_pk_bf16_f32 v109, v110, v111
	v_cvt_pk_bf16_f32 v110, v104, v105
	v_or_b32_e32 v104, 16, v148
	v_ashrrev_i32_e32 v65, 31, v64
	v_cvt_pk_bf16_f32 v44, v44, v45
	v_cvt_pk_bf16_f32 v45, v46, v47
	v_cvt_pk_bf16_f32 v46, v40, v41
	v_add_u32_e32 v40, 0x90, v148
	v_lshl_add_u64 v[150:151], v[132:133], 0, s[16:17]
	v_lshlrev_b64 v[152:153], 11, v[148:149]
	v_ashrrev_i32_e32 v105, 31, v104
	v_cvt_pk_bf16_f32 v92, v92, v93
	v_cvt_pk_bf16_f32 v93, v94, v95
	v_cvt_pk_bf16_f32 v94, v88, v89
	v_or_b32_e32 v88, 32, v148
	v_lshlrev_b64 v[64:65], 11, v[64:65]
	v_ashrrev_i32_e32 v41, 31, v40
	v_cvt_pk_bf16_f32 v28, v28, v29
	v_cvt_pk_bf16_f32 v29, v30, v31
	v_cvt_pk_bf16_f32 v30, v24, v25
	v_add_u32_e32 v24, 0xa0, v148
	v_lshl_add_u64 v[152:153], v[150:151], 0, v[152:153]
	v_cvt_pk_bf16_f32 v111, v106, v107
	v_lshlrev_b64 v[104:105], 11, v[104:105]
	v_ashrrev_i32_e32 v89, 31, v88
	v_cvt_pk_bf16_f32 v76, v76, v77
	v_cvt_pk_bf16_f32 v77, v78, v79
	v_cvt_pk_bf16_f32 v78, v72, v73
	v_or_b32_e32 v72, 48, v148
	v_lshl_add_u64 v[64:65], v[150:151], 0, v[64:65]
	v_cvt_pk_bf16_f32 v47, v42, v43
	v_lshlrev_b64 v[40:41], 11, v[40:41]
	v_ashrrev_i32_e32 v25, 31, v24
	v_cvt_pk_bf16_f32 v12, v12, v13
	v_cvt_pk_bf16_f32 v13, v14, v15
	v_cvt_pk_bf16_f32 v14, v8, v9
	v_add_u32_e32 v8, 0xb0, v148
	global_store_dwordx4 v[152:153], v[108:111], off offset:256
	v_cvt_pk_bf16_f32 v95, v90, v91
	v_lshlrev_b64 v[88:89], 11, v[88:89]
	v_lshl_add_u64 v[108:109], v[150:151], 0, v[104:105]
	v_ashrrev_i32_e32 v73, 31, v72
	global_store_dwordx4 v[64:65], v[44:47], off offset:256
	v_cvt_pk_bf16_f32 v31, v26, v27
	v_lshlrev_b64 v[24:25], 11, v[24:25]
	v_lshl_add_u64 v[44:45], v[150:151], 0, v[40:41]
	v_ashrrev_i32_e32 v9, 31, v8
	global_store_dwordx4 v[108:109], v[92:95], off offset:256
	v_cvt_pk_bf16_f32 v79, v74, v75
	v_lshlrev_b64 v[72:73], 11, v[72:73]
	v_lshl_add_u64 v[92:93], v[150:151], 0, v[88:89]
	global_store_dwordx4 v[44:45], v[28:31], off offset:256
	v_cvt_pk_bf16_f32 v15, v10, v11
	v_lshlrev_b64 v[8:9], 11, v[8:9]
	v_lshl_add_u64 v[28:29], v[150:151], 0, v[24:25]
	v_cvt_pk_bf16_f32 v124, v124, v125
	v_cvt_pk_bf16_f32 v125, v126, v127
	v_cvt_pk_bf16_f32 v126, v120, v121
	v_cvt_pk_bf16_f32 v127, v122, v123
	v_cvt_pk_bf16_f32 v104, v116, v117
	v_cvt_pk_bf16_f32 v105, v118, v119
	v_cvt_pk_bf16_f32 v106, v112, v113
	v_cvt_pk_bf16_f32 v107, v114, v115
	v_cvt_pk_bf16_f32 v88, v100, v101
	v_cvt_pk_bf16_f32 v89, v102, v103
	v_cvt_pk_bf16_f32 v90, v96, v97
	v_cvt_pk_bf16_f32 v91, v98, v99
	global_store_dwordx4 v[92:93], v[76:79], off offset:256
	v_cvt_pk_bf16_f32 v74, v80, v81
	v_cvt_pk_bf16_f32 v75, v82, v83
	v_lshl_add_u64 v[76:77], v[150:151], 0, v[72:73]
	v_cvt_pk_bf16_f32 v72, v84, v85
	v_cvt_pk_bf16_f32 v73, v86, v87
	v_cvt_pk_bf16_f32 v71, v66, v67
	v_cvt_pk_bf16_f32 v60, v60, v61
	v_cvt_pk_bf16_f32 v61, v62, v63
	v_cvt_pk_bf16_f32 v62, v56, v57
	v_cvt_pk_bf16_f32 v63, v58, v59
	v_cvt_pk_bf16_f32 v40, v52, v53
	v_cvt_pk_bf16_f32 v41, v54, v55
	v_cvt_pk_bf16_f32 v42, v48, v49
	v_cvt_pk_bf16_f32 v43, v50, v51
	v_cvt_pk_bf16_f32 v24, v36, v37
	v_cvt_pk_bf16_f32 v25, v38, v39
	v_cvt_pk_bf16_f32 v26, v32, v33
	v_cvt_pk_bf16_f32 v27, v34, v35
	global_store_dwordx4 v[28:29], v[12:15], off offset:256
	v_cvt_pk_bf16_f32 v10, v16, v17
	v_cvt_pk_bf16_f32 v11, v18, v19
	v_lshl_add_u64 v[12:13], v[150:151], 0, v[8:9]
	v_cvt_pk_bf16_f32 v8, v20, v21
	v_cvt_pk_bf16_f32 v9, v22, v23
	v_cvt_pk_bf16_f32 v4, v4, v5
	v_cvt_pk_bf16_f32 v5, v6, v7
	v_cvt_pk_bf16_f32 v6, v0, v1
	v_cvt_pk_bf16_f32 v7, v2, v3
	s_and_b64 vcc, exec, s[4:5]
	s_mov_b32 s47, s8
	s_mov_b32 s48, s46
	s_mov_b64 s[18:19], s[14:15]
	s_mov_b64 s[16:17], s[12:13]
	global_store_dwordx4 v[152:153], v[124:127], off
	global_store_dwordx4 v[108:109], v[104:107], off
	global_store_dwordx4 v[92:93], v[88:91], off
	global_store_dwordx4 v[76:77], v[72:75], off
	global_store_dwordx4 v[76:77], v[68:71], off offset:256
	global_store_dwordx4 v[64:65], v[60:63], off
	global_store_dwordx4 v[44:45], v[40:43], off
	global_store_dwordx4 v[28:29], v[24:27], off
	global_store_dwordx4 v[12:13], v[8:11], off
	global_store_dwordx4 v[12:13], v[4:7], off offset:256
	s_cbranch_vccz .LBB0_902
	s_waitcnt vmcnt(0)
	s_cmpk_gt_u32 s24, 0xff
	s_cbranch_scc1 .LBB0_909
	s_barrier

; #define STG(P, GB) do { const char* _gb = (GB); \
;     _Pragma("unroll") for (int _i = 0; _i < 2; ++_i) { \
;       __builtin_amdgcn_global_load_lds((const unsigned*)(_gb + voff[_i]), \
;         (LAS unsigned*)((LAS char*)(P) + ldsw + _i * 8192), 16, 0, 0); } } while (0)
; #define LDA(dst, b, h) _Pragma("unroll") for (int m = 0; m < 4; ++m) _Pragma("unroll") for (int k = 0; k < 2; ++k) \
;     dst[m][k] = *(const LAS bf16x8*)((LAS char*)SA(b, h) + aoff + m * 2048 + k * 1024)
; #define LDB(dst, b, h) _Pragma("unroll") for (int n = 0; n < 2; ++n) _Pragma("unroll") for (int k = 0; k < 2; ++k) \
;     dst[n][k] = *(const LAS bf16x8*)((LAS char*)SB(b, h) + boff + n * 2048 + k * 1024)
; #define MMA(ai, bj, At_, Bt_) do { __builtin_amdgcn_s_setprio(1); \
;     _Pragma("unroll") for (int m = 0; m < 4; ++m) _Pragma("unroll") for (int n = 0; n < 2; ++n) _Pragma("unroll") for (int k = 0; k < 2; ++k) \
;       acc[ai][bj][m][n] = __builtin_amdgcn_mfma_f32_16x16x32_bf16(Bt_[n][k], At_[m][k], acc[ai][bj][m][n], 0, 0, 0); \
;     __builtin_amdgcn_s_setprio(0); } while (0)
; #define WAIT_L(n) asm volatile("s_waitcnt lgkmcnt(" #n ")" ::: "memory")
; #define BAR __builtin_amdgcn_s_barrier()
; #define SCHED __builtin_amdgcn_sched_barrier(0)
; __device__ __forceinline__ void gemm_phase(const bf16_t* __restrict__ A, const bf16_t* __restrict__ Bt, bf16_t* __restrict__ C, int M, int N, int K,
;                                            int ldc, const int EPI, char* smem, const int wid_u) {
;     ...
;       LDB(B0, 0, 0); SCHED; LDA(At, 0, 0); STG(SA(1, 1), a1 + hstep);
;       WAIT_L(8); BAR; WAIT_L(0); MMA(0, 0, At, B0); BAR; SCHED;
;       LDB(B1, 0, 1); STG(SB(0, 0), b2);
;       BAR; WAIT_L(0); MMA(0, 1, At, B1); BAR;
;       LDA(At, 0, 1); STG(SA(0, 0), a2);
;       BAR; WAIT_L(0); MMA(1, 0, At, B0); BAR; SCHED;
.LBB0_1026:
	ds_read_b128 v[150:153], v146
	ds_read_b128 v[154:157], v146 offset:1024
	ds_read_b128 v[158:161], v146 offset:2048
	ds_read_b128 v[162:165], v146 offset:3072
	s_add_u32 s20, s18, 0x100
	s_addc_u32 s21, s19, 0
	s_cmp_eq_u32 s53, 12
	s_cselect_b32 s25, s48, s21
	s_cselect_b32 s24, s49, s20
	s_cselect_b32 s23, s13, s52
	s_cselect_b32 s22, s50, s51
	v_lshl_add_u64 v[142:143], s[18:19], 0, v[136:137]
	s_add_i32 m0, s34, 0xc000
	ds_read_b128 v[166:169], v147
	ds_read_b128 v[170:173], v147 offset:1024
	ds_read_b128 v[174:177], v147 offset:2048
	ds_read_b128 v[178:181], v147 offset:3072
	ds_read_b128 v[182:185], v147 offset:4096
	ds_read_b128 v[186:189], v147 offset:5120
	ds_read_b128 v[190:193], v147 offset:6144
	ds_read_b128 v[194:197], v147 offset:7168
	global_load_lds_dwordx4 v[142:143], off
	v_lshl_add_u64 v[142:143], s[18:19], 0, v[134:135]
	s_add_i32 m0, s34, 0xe000
	s_nop 0
	global_load_lds_dwordx4 v[142:143], off
	s_waitcnt lgkmcnt(8)
	s_barrier
	s_waitcnt lgkmcnt(0)
	s_waitcnt lgkmcnt(0)
	v_mfma_f32_16x16x32_bf16 v[124:127], v[150:153], v[166:169], v[124:127]
	v_mfma_f32_16x16x32_bf16 v[120:123], v[158:161], v[166:169], v[120:123]
	v_mfma_f32_16x16x32_bf16 v[108:111], v[150:153], v[174:177], v[108:111]
	v_mfma_f32_16x16x32_bf16 v[104:107], v[158:161], v[174:177], v[104:107]
	v_mfma_f32_16x16x32_bf16 v[92:95], v[150:153], v[182:185], v[92:95]
	v_mfma_f32_16x16x32_bf16 v[88:91], v[158:161], v[182:185], v[88:91]
	v_mfma_f32_16x16x32_bf16 v[76:79], v[150:153], v[190:193], v[76:79]
	v_mfma_f32_16x16x32_bf16 v[72:75], v[158:161], v[190:193], v[72:75]
	v_mfma_f32_16x16x32_bf16 v[124:127], v[154:157], v[170:173], v[124:127]
	v_mfma_f32_16x16x32_bf16 v[120:123], v[162:165], v[170:173], v[120:123]
	v_mfma_f32_16x16x32_bf16 v[108:111], v[154:157], v[178:181], v[108:111]
	v_mfma_f32_16x16x32_bf16 v[104:107], v[162:165], v[178:181], v[104:107]
	v_mfma_f32_16x16x32_bf16 v[92:95], v[154:157], v[186:189], v[92:95]
	v_mfma_f32_16x16x32_bf16 v[88:91], v[162:165], v[186:189], v[88:91]
	v_mfma_f32_16x16x32_bf16 v[76:79], v[154:157], v[194:197], v[76:79]
	v_mfma_f32_16x16x32_bf16 v[72:75], v[162:165], v[194:197], v[72:75]
	s_barrier
	s_add_i32 s18, s40, s31
	v_lshl_add_u64 v[142:143], s[22:23], 0, v[130:131]
	s_mov_b32 m0, s18
	ds_read_b128 v[198:201], v148
	ds_read_b128 v[202:205], v148 offset:1024
	ds_read_b128 v[206:209], v148 offset:2048
	ds_read_b128 v[210:213], v148 offset:3072
	global_load_lds_dwordx4 v[142:143], off
	v_lshl_add_u64 v[214:215], s[22:23], 0, v[128:129]
	s_add_i32 m0, s18, 0x2000
	s_nop 0
	global_load_lds_dwordx4 v[214:215], off
	s_barrier
	s_waitcnt lgkmcnt(0)
	s_waitcnt lgkmcnt(0)
	v_mfma_f32_16x16x32_bf16 v[116:119], v[198:201], v[166:169], v[116:119]
	v_mfma_f32_16x16x32_bf16 v[112:115], v[206:209], v[166:169], v[112:115]
	v_mfma_f32_16x16x32_bf16 v[100:103], v[198:201], v[174:177], v[100:103]
	v_mfma_f32_16x16x32_bf16 v[96:99], v[206:209], v[174:177], v[96:99]
	v_mfma_f32_16x16x32_bf16 v[84:87], v[198:201], v[182:185], v[84:87]
	v_mfma_f32_16x16x32_bf16 v[80:83], v[206:209], v[182:185], v[80:83]
	v_mfma_f32_16x16x32_bf16 v[68:71], v[198:201], v[190:193], v[68:71]
	v_mfma_f32_16x16x32_bf16 v[64:67], v[206:209], v[190:193], v[64:67]
	v_mfma_f32_16x16x32_bf16 v[116:119], v[202:205], v[170:173], v[116:119]
	v_mfma_f32_16x16x32_bf16 v[112:115], v[210:213], v[170:173], v[112:115]
	v_mfma_f32_16x16x32_bf16 v[100:103], v[202:205], v[178:181], v[100:103]
	v_mfma_f32_16x16x32_bf16 v[96:99], v[210:213], v[178:181], v[96:99]
	v_mfma_f32_16x16x32_bf16 v[84:87], v[202:205], v[186:189], v[84:87]
	v_mfma_f32_16x16x32_bf16 v[80:83], v[210:213], v[186:189], v[80:83]
	s_mov_b32 m0, s34
	v_lshl_add_u64 v[216:217], s[24:25], 0, v[130:131]
	v_mfma_f32_16x16x32_bf16 v[68:71], v[202:205], v[194:197], v[68:71]
	v_mfma_f32_16x16x32_bf16 v[64:67], v[210:213], v[194:197], v[64:67]
	s_barrier
	ds_read_b128 v[166:169], v147 offset:16384
	ds_read_b128 v[170:173], v147 offset:17408
	ds_read_b128 v[174:177], v147 offset:18432
	ds_read_b128 v[178:181], v147 offset:19456
	ds_read_b128 v[182:185], v147 offset:20480
	ds_read_b128 v[186:189], v147 offset:21504
	ds_read_b128 v[190:193], v147 offset:22528
	ds_read_b128 v[194:197], v147 offset:23552
	global_load_lds_dwordx4 v[216:217], off
	v_lshl_add_u64 v[218:219], s[24:25], 0, v[128:129]
	s_mov_b32 m0, s35
	s_nop 0
	global_load_lds_dwordx4 v[218:219], off
	s_barrier
	s_waitcnt lgkmcnt(0)
	s_waitcnt lgkmcnt(0)
	v_mfma_f32_16x16x32_bf16 v[60:63], v[150:153], v[166:169], v[60:63]
	v_mfma_f32_16x16x32_bf16 v[56:59], v[158:161], v[166:169], v[56:59]
	v_mfma_f32_16x16x32_bf16 v[44:47], v[150:153], v[174:177], v[44:47]
	v_mfma_f32_16x16x32_bf16 v[40:43], v[158:161], v[174:177], v[40:43]
	v_mfma_f32_16x16x32_bf16 v[28:31], v[150:153], v[182:185], v[28:31]
	v_mfma_f32_16x16x32_bf16 v[24:27], v[158:161], v[182:185], v[24:27]
	v_mfma_f32_16x16x32_bf16 v[12:15], v[150:153], v[190:193], v[12:15]
	v_mfma_f32_16x16x32_bf16 v[8:11], v[158:161], v[190:193], v[8:11]
	v_mfma_f32_16x16x32_bf16 v[60:63], v[154:157], v[170:173], v[60:63]
	v_mfma_f32_16x16x32_bf16 v[56:59], v[162:165], v[170:173], v[56:59]
	v_mfma_f32_16x16x32_bf16 v[44:47], v[154:157], v[178:181], v[44:47]
	v_mfma_f32_16x16x32_bf16 v[40:43], v[162:165], v[178:181], v[40:43]
	v_mfma_f32_16x16x32_bf16 v[28:31], v[154:157], v[186:189], v[28:31]
	v_mfma_f32_16x16x32_bf16 v[24:27], v[162:165], v[186:189], v[24:27]
	v_mfma_f32_16x16x32_bf16 v[12:15], v[154:157], v[194:197], v[12:15]
	v_mfma_f32_16x16x32_bf16 v[8:11], v[162:165], v[194:197], v[8:11]
	s_barrier
; #define STG(P, GB) do { const char* _gb = (GB); \
;     _Pragma("unroll") for (int _i = 0; _i < 2; ++_i) { \
;       __builtin_amdgcn_global_load_lds((const unsigned*)(_gb + voff[_i]), \
;         (LAS unsigned*)((LAS char*)(P) + ldsw + _i * 8192), 16, 0, 0); } } while (0)
; #define LDA(dst, b, h) _Pragma("unroll") for (int m = 0; m < 4; ++m) _Pragma("unroll") for (int k = 0; k < 2; ++k) \
;     dst[m][k] = *(const LAS bf16x8*)((LAS char*)SA(b, h) + aoff + m * 2048 + k * 1024)
; #define LDB(dst, b, h) _Pragma("unroll") for (int n = 0; n < 2; ++n) _Pragma("unroll") for (int k = 0; k < 2; ++k) \
;     dst[n][k] = *(const LAS bf16x8*)((LAS char*)SB(b, h) + boff + n * 2048 + k * 1024)
; #define MMA(ai, bj, At_, Bt_) do { __builtin_amdgcn_s_setprio(1); \
;     _Pragma("unroll") for (int m = 0; m < 4; ++m) _Pragma("unroll") for (int n = 0; n < 2; ++n) _Pragma("unroll") for (int k = 0; k < 2; ++k) \
;       acc[ai][bj][m][n] = __builtin_amdgcn_mfma_f32_16x16x32_bf16(Bt_[n][k], At_[m][k], acc[ai][bj][m][n], 0, 0, 0); \
;     __builtin_amdgcn_s_setprio(0); } while (0)
; #define WAIT_V(n) asm volatile("s_waitcnt vmcnt(" #n ")" ::: "memory")
; #define WAIT_L(n) asm volatile("s_waitcnt lgkmcnt(" #n ")" ::: "memory")
; #define BAR __builtin_amdgcn_s_barrier()
; #define SCHED __builtin_amdgcn_sched_barrier(0)
; __device__ __forceinline__ void gemm_phase(const bf16_t* __restrict__ A, const bf16_t* __restrict__ Bt, bf16_t* __restrict__ C, int M, int N, int K,
;                                            int ldc, const int EPI, char* smem, const int wid_u) {
;     ...
;       STG(SB(0, 1), b2 + hstep);
;       WAIT_V(6); BAR; MMA(1, 1, At, B1); BAR;
;       LDB(B0, 1, 0); SCHED; LDA(At, 1, 0); STG(SA(0, 1), a2 + hstep);
;       WAIT_L(8); BAR; WAIT_L(0); MMA(0, 0, At, B0); BAR; SCHED;
;       LDB(B1, 1, 1); STG(SB(1, 0), b3);
;       BAR; WAIT_L(0); MMA(0, 1, At, B1); BAR;
;       LDA(At, 1, 1); STG(SA(1, 0), a3);
	s_add_u32 s18, s22, 0x40000
	s_addc_u32 s19, s23, 0
	s_add_i32 s54, s41, s31
	v_lshl_add_u64 v[150:151], s[18:19], 0, v[130:131]
	s_mov_b32 m0, s54
	s_nop 0
	global_load_lds_dwordx4 v[150:151], off
	v_lshl_add_u64 v[150:151], s[18:19], 0, v[128:129]
	s_add_i32 m0, s54, 0x2000
	s_nop 0
	global_load_lds_dwordx4 v[150:151], off
	s_waitcnt vmcnt(6)
	s_barrier
	v_mfma_f32_16x16x32_bf16 v[52:55], v[198:201], v[166:169], v[52:55]
	v_mfma_f32_16x16x32_bf16 v[48:51], v[206:209], v[166:169], v[48:51]
	v_mfma_f32_16x16x32_bf16 v[36:39], v[198:201], v[174:177], v[36:39]
	v_mfma_f32_16x16x32_bf16 v[32:35], v[206:209], v[174:177], v[32:35]
	v_mfma_f32_16x16x32_bf16 v[20:23], v[198:201], v[182:185], v[20:23]
	v_mfma_f32_16x16x32_bf16 v[16:19], v[206:209], v[182:185], v[16:19]
	v_mfma_f32_16x16x32_bf16 v[4:7], v[198:201], v[190:193], v[4:7]
	v_mfma_f32_16x16x32_bf16 v[0:3], v[206:209], v[190:193], v[0:3]
	v_mfma_f32_16x16x32_bf16 v[52:55], v[202:205], v[170:173], v[52:55]
	v_mfma_f32_16x16x32_bf16 v[48:51], v[210:213], v[170:173], v[48:51]
	v_mfma_f32_16x16x32_bf16 v[36:39], v[202:205], v[178:181], v[36:39]
	v_mfma_f32_16x16x32_bf16 v[32:35], v[210:213], v[178:181], v[32:35]
	v_mfma_f32_16x16x32_bf16 v[20:23], v[202:205], v[186:189], v[20:23]
	v_mfma_f32_16x16x32_bf16 v[16:19], v[210:213], v[186:189], v[16:19]
	s_add_i32 s54, 0, 0x18000
	v_add_u32_e32 v149, s54, v145
	v_mfma_f32_16x16x32_bf16 v[4:7], v[202:205], v[194:197], v[4:7]
	v_mfma_f32_16x16x32_bf16 v[0:3], v[210:213], v[194:197], v[0:3]
	s_barrier
	ds_read_b128 v[150:153], v149
	ds_read_b128 v[154:157], v149 offset:1024
	ds_read_b128 v[158:161], v149 offset:2048
	ds_read_b128 v[162:165], v149 offset:3072
	s_add_u32 s18, s24, 0x40000
	s_addc_u32 s19, s25, 0
	s_mov_b32 m0, s36
	v_lshl_add_u64 v[198:199], s[18:19], 0, v[130:131]
	ds_read_b128 v[166:169], v147 offset:32768
	ds_read_b128 v[170:173], v147 offset:33792
	ds_read_b128 v[174:177], v147 offset:34816
	ds_read_b128 v[178:181], v147 offset:35840
	ds_read_b128 v[182:185], v147 offset:36864
	ds_read_b128 v[186:189], v147 offset:37888
	ds_read_b128 v[190:193], v147 offset:38912
	ds_read_b128 v[194:197], v147 offset:39936
	global_load_lds_dwordx4 v[198:199], off
	v_lshl_add_u64 v[198:199], s[18:19], 0, v[128:129]
	s_mov_b32 m0, s37
	s_nop 0
	global_load_lds_dwordx4 v[198:199], off
	s_waitcnt lgkmcnt(8)
	s_barrier
	s_waitcnt lgkmcnt(0)
	s_waitcnt lgkmcnt(0)
	v_mfma_f32_16x16x32_bf16 v[124:127], v[150:153], v[166:169], v[124:127]
	v_mfma_f32_16x16x32_bf16 v[120:123], v[158:161], v[166:169], v[120:123]
	v_mfma_f32_16x16x32_bf16 v[108:111], v[150:153], v[174:177], v[108:111]
	v_mfma_f32_16x16x32_bf16 v[104:107], v[158:161], v[174:177], v[104:107]
	v_mfma_f32_16x16x32_bf16 v[92:95], v[150:153], v[182:185], v[92:95]
	v_mfma_f32_16x16x32_bf16 v[88:91], v[158:161], v[182:185], v[88:91]
	v_mfma_f32_16x16x32_bf16 v[76:79], v[150:153], v[190:193], v[76:79]
	v_mfma_f32_16x16x32_bf16 v[72:75], v[158:161], v[190:193], v[72:75]
	v_mfma_f32_16x16x32_bf16 v[124:127], v[154:157], v[170:173], v[124:127]
	v_mfma_f32_16x16x32_bf16 v[120:123], v[162:165], v[170:173], v[120:123]
	v_mfma_f32_16x16x32_bf16 v[108:111], v[154:157], v[178:181], v[108:111]
	v_mfma_f32_16x16x32_bf16 v[104:107], v[162:165], v[178:181], v[104:107]
	v_mfma_f32_16x16x32_bf16 v[92:95], v[154:157], v[186:189], v[92:95]
	v_mfma_f32_16x16x32_bf16 v[88:91], v[162:165], v[186:189], v[88:91]
	v_mfma_f32_16x16x32_bf16 v[76:79], v[154:157], v[194:197], v[76:79]
	v_mfma_f32_16x16x32_bf16 v[72:75], v[162:165], v[194:197], v[72:75]
	s_barrier
	s_add_i32 s24, 0, 0x1c000
	s_add_i32 s18, s54, s31
	v_add_u32_e32 v149, s24, v145
	v_lshl_add_u64 v[142:143], v[142:143], 0, s[10:11]
	s_mov_b32 m0, s18
	ds_read_b128 v[198:201], v149
	ds_read_b128 v[202:205], v149 offset:1024
	ds_read_b128 v[206:209], v149 offset:2048
	ds_read_b128 v[210:213], v149 offset:3072
	global_load_lds_dwordx4 v[142:143], off
	v_lshl_add_u64 v[142:143], v[214:215], 0, s[10:11]
	s_add_i32 m0, s18, 0x2000
	s_nop 0
	global_load_lds_dwordx4 v[142:143], off
	s_barrier
	s_waitcnt lgkmcnt(0)
	s_waitcnt lgkmcnt(0)
	v_mfma_f32_16x16x32_bf16 v[116:119], v[198:201], v[166:169], v[116:119]
	v_mfma_f32_16x16x32_bf16 v[112:115], v[206:209], v[166:169], v[112:115]
	v_mfma_f32_16x16x32_bf16 v[100:103], v[198:201], v[174:177], v[100:103]
	v_mfma_f32_16x16x32_bf16 v[96:99], v[206:209], v[174:177], v[96:99]
	v_mfma_f32_16x16x32_bf16 v[84:87], v[198:201], v[182:185], v[84:87]
	v_mfma_f32_16x16x32_bf16 v[80:83], v[206:209], v[182:185], v[80:83]
	v_mfma_f32_16x16x32_bf16 v[68:71], v[198:201], v[190:193], v[68:71]
	v_mfma_f32_16x16x32_bf16 v[64:67], v[206:209], v[190:193], v[64:67]
	v_mfma_f32_16x16x32_bf16 v[116:119], v[202:205], v[170:173], v[116:119]
	v_mfma_f32_16x16x32_bf16 v[112:115], v[210:213], v[170:173], v[112:115]
	v_mfma_f32_16x16x32_bf16 v[100:103], v[202:205], v[178:181], v[100:103]
	v_mfma_f32_16x16x32_bf16 v[96:99], v[210:213], v[178:181], v[96:99]
	v_mfma_f32_16x16x32_bf16 v[84:87], v[202:205], v[186:189], v[84:87]
	v_mfma_f32_16x16x32_bf16 v[80:83], v[210:213], v[186:189], v[80:83]
	s_mov_b32 m0, s38
	v_lshl_add_u64 v[142:143], v[216:217], 0, s[10:11]
	v_mfma_f32_16x16x32_bf16 v[68:71], v[202:205], v[194:197], v[68:71]
	v_mfma_f32_16x16x32_bf16 v[64:67], v[210:213], v[194:197], v[64:67]
	s_barrier
	ds_read_b128 v[166:169], v147 offset:49152
	ds_read_b128 v[170:173], v147 offset:50176
	ds_read_b128 v[174:177], v147 offset:51200
	ds_read_b128 v[178:181], v147 offset:52224
	ds_read_b128 v[182:185], v147 offset:53248
	ds_read_b128 v[186:189], v147 offset:54272
	ds_read_b128 v[190:193], v147 offset:55296
	ds_read_b128 v[194:197], v147 offset:56320
	global_load_lds_dwordx4 v[142:143], off
	v_lshl_add_u64 v[142:143], v[218:219], 0, s[10:11]
	s_mov_b32 m0, s39
	s_nop 0
	global_load_lds_dwordx4 v[142:143], off
	s_barrier
; #define STG(P, GB) do { const char* _gb = (GB); \
;     _Pragma("unroll") for (int _i = 0; _i < 2; ++_i) { \
;       __builtin_amdgcn_global_load_lds((const unsigned*)(_gb + voff[_i]), \
;         (LAS unsigned*)((LAS char*)(P) + ldsw + _i * 8192), 16, 0, 0); } } while (0)
; #define MMA(ai, bj, At_, Bt_) do { __builtin_amdgcn_s_setprio(1); \
;     _Pragma("unroll") for (int m = 0; m < 4; ++m) _Pragma("unroll") for (int n = 0; n < 2; ++n) _Pragma("unroll") for (int k = 0; k < 2; ++k) \
;       acc[ai][bj][m][n] = __builtin_amdgcn_mfma_f32_16x16x32_bf16(Bt_[n][k], At_[m][k], acc[ai][bj][m][n], 0, 0, 0); \
;     __builtin_amdgcn_s_setprio(0); } while (0)
; #define WAIT_V(n) asm volatile("s_waitcnt vmcnt(" #n ")" ::: "memory")
; #define WAIT_L(n) asm volatile("s_waitcnt lgkmcnt(" #n ")" ::: "memory")
; #define BAR __builtin_amdgcn_s_barrier()
; #define SCHED __builtin_amdgcn_sched_barrier(0)
; __device__ __forceinline__ void gemm_phase(const bf16_t* __restrict__ A, const bf16_t* __restrict__ Bt, bf16_t* __restrict__ C, int M, int N, int K,
;                                            int ldc, const int EPI, char* smem, const int wid_u) {
;     ...
;       BAR; WAIT_L(0); MMA(1, 0, At, B0); BAR; SCHED;
;       STG(SB(1, 1), b3 + hstep);
;       WAIT_V(6); BAR; MMA(1, 1, At, B1); BAR;
;     }
;     {
;       const int brow = pm * BM, bcol = pn * BM;
; #pragma unroll
;       for (int ai = 0; ai < 2; ++ai)
; #pragma unroll
;         for (int m = 0; m < 4; ++m) {
;           const size_t row = (size_t)(brow + ai * HALF + wr * 64 + m * 16 + fr);
;           if (EPI == 0) {
; #pragma unroll
;             for (int bj = 0; bj < 2; ++bj) {
;               const f32x4 v0 = acc[ai][bj][m][0], v1 = acc[ai][bj][m][1];
;               uint4 u; u.x = cvt_pk_bf16(v0[0], v0[1]); u.y = cvt_pk_bf16(v0[2], v0[3]); u.z = cvt_pk_bf16(v1[0], v1[1]); u.w = cvt_pk_bf16(v1[2], v1[3]);
;               *(uint4*)(C + row * ldc + bcol + bj * HALF + wc * 32 + fq * 8) = u;
;             }
;           } else {
;             float o[8];
; #pragma unroll
;             for (int n = 0; n < 2; ++n) {
;               const f32x4 a = acc[ai][0][m][n], b = acc[ai][1][m][n];
; #pragma unroll
;               for (int j = 0; j < 4; ++j) o[n * 4 + j] = a[j] * __builtin_amdgcn_rcpf(1.f + __expf(-a[j])) * b[j];
;             }
;             *(uint4*)(C + row * ldc + (bcol >> 1) + wc * 32 + fq * 8) = pack8(o);
	s_waitcnt lgkmcnt(0)
	s_waitcnt lgkmcnt(0)
	v_mfma_f32_16x16x32_bf16 v[60:63], v[150:153], v[166:169], v[60:63]
	v_mfma_f32_16x16x32_bf16 v[56:59], v[158:161], v[166:169], v[56:59]
	v_mfma_f32_16x16x32_bf16 v[44:47], v[150:153], v[174:177], v[44:47]
	v_mfma_f32_16x16x32_bf16 v[40:43], v[158:161], v[174:177], v[40:43]
	v_mfma_f32_16x16x32_bf16 v[28:31], v[150:153], v[182:185], v[28:31]
	v_mfma_f32_16x16x32_bf16 v[24:27], v[158:161], v[182:185], v[24:27]
	v_mfma_f32_16x16x32_bf16 v[12:15], v[150:153], v[190:193], v[12:15]
	v_mfma_f32_16x16x32_bf16 v[8:11], v[158:161], v[190:193], v[8:11]
	v_mfma_f32_16x16x32_bf16 v[60:63], v[154:157], v[170:173], v[60:63]
	v_mfma_f32_16x16x32_bf16 v[56:59], v[162:165], v[170:173], v[56:59]
	v_mfma_f32_16x16x32_bf16 v[44:47], v[154:157], v[178:181], v[44:47]
	v_mfma_f32_16x16x32_bf16 v[40:43], v[162:165], v[178:181], v[40:43]
	v_mfma_f32_16x16x32_bf16 v[28:31], v[154:157], v[186:189], v[28:31]
	v_mfma_f32_16x16x32_bf16 v[24:27], v[162:165], v[186:189], v[24:27]
	v_mfma_f32_16x16x32_bf16 v[12:15], v[154:157], v[194:197], v[12:15]
	v_mfma_f32_16x16x32_bf16 v[8:11], v[162:165], v[194:197], v[8:11]
	s_barrier
	s_add_u32 s18, s22, 0x40080
	s_addc_u32 s19, s23, 0
	s_add_i32 s22, s24, s31
	v_lshl_add_u64 v[142:143], s[18:19], 0, v[130:131]
	s_mov_b32 m0, s22
	s_nop 0
	global_load_lds_dwordx4 v[142:143], off
	v_lshl_add_u64 v[142:143], s[18:19], 0, v[128:129]
	s_add_i32 m0, s22, 0x2000
	s_nop 0
	global_load_lds_dwordx4 v[142:143], off
	s_waitcnt vmcnt(6)
	s_barrier
	v_mfma_f32_16x16x32_bf16 v[52:55], v[198:201], v[166:169], v[52:55]
	v_mfma_f32_16x16x32_bf16 v[48:51], v[206:209], v[166:169], v[48:51]
	v_mfma_f32_16x16x32_bf16 v[36:39], v[198:201], v[174:177], v[36:39]
	v_mfma_f32_16x16x32_bf16 v[32:35], v[206:209], v[174:177], v[32:35]
	v_mfma_f32_16x16x32_bf16 v[20:23], v[198:201], v[182:185], v[20:23]
	v_mfma_f32_16x16x32_bf16 v[16:19], v[206:209], v[182:185], v[16:19]
	v_mfma_f32_16x16x32_bf16 v[4:7], v[198:201], v[190:193], v[4:7]
	v_mfma_f32_16x16x32_bf16 v[0:3], v[206:209], v[190:193], v[0:3]
	v_mfma_f32_16x16x32_bf16 v[52:55], v[202:205], v[170:173], v[52:55]
	v_mfma_f32_16x16x32_bf16 v[48:51], v[210:213], v[170:173], v[48:51]
	v_mfma_f32_16x16x32_bf16 v[36:39], v[202:205], v[178:181], v[36:39]
	v_mfma_f32_16x16x32_bf16 v[32:35], v[210:213], v[178:181], v[32:35]
	v_mfma_f32_16x16x32_bf16 v[20:23], v[202:205], v[186:189], v[20:23]
	v_mfma_f32_16x16x32_bf16 v[16:19], v[210:213], v[186:189], v[16:19]
	s_add_i32 s53, s53, 2
	s_add_u32 s51, s51, 0x100
	s_addc_u32 s52, s52, 0
	s_cmp_gt_u32 s53, 13
	s_mov_b64 s[18:19], s[20:21]
	v_mfma_f32_16x16x32_bf16 v[4:7], v[202:205], v[194:197], v[4:7]
	v_mfma_f32_16x16x32_bf16 v[0:3], v[210:213], v[194:197], v[0:3]
	s_barrier
	s_cbranch_scc0 .LBB0_1026
	v_mul_f32_e32 v142, 0xbfb8aa3b, v124
	v_exp_f32_e32 v142, v142
	v_mul_f32_e32 v143, 0xbfb8aa3b, v125
	v_exp_f32_e32 v143, v143
	s_lshl_b32 s18, s46, 8
	v_add_f32_e32 v142, 1.0, v142
	v_rcp_f32_e32 v150, v142
	v_add_f32_e32 v142, 1.0, v143
	v_rcp_f32_e32 v151, v142
	s_mov_b32 s19, s9
	v_lshl_add_u32 v149, s47, 8, v144
	v_lshl_add_u64 v[142:143], v[132:133], 0, s[18:19]
	v_pk_mul_f32 v[124:125], v[124:125], v[150:151]
	v_mul_f32_e32 v150, 0xbfb8aa3b, v126
	v_mul_f32_e32 v151, 0xbfb8aa3b, v127
	v_exp_f32_e32 v150, v150
	v_exp_f32_e32 v151, v151
	v_pk_mul_f32 v[116:117], v[124:125], v[116:117]
	s_and_b64 vcc, exec, s[4:5]
	v_add_f32_e32 v124, 1.0, v150
	v_add_f32_e32 v125, 1.0, v151
	v_mul_f32_e32 v150, 0xbfb8aa3b, v120
	v_mul_f32_e32 v151, 0xbfb8aa3b, v121
	v_rcp_f32_e32 v124, v124
	v_rcp_f32_e32 v125, v125
	v_exp_f32_e32 v150, v150
	v_exp_f32_e32 v151, v151
	s_mov_b32 s47, s8
	v_pk_mul_f32 v[124:125], v[126:127], v[124:125]
	v_add_f32_e32 v126, 1.0, v150
	v_add_f32_e32 v127, 1.0, v151
	v_mul_f32_e32 v150, 0xbfb8aa3b, v122
	v_mul_f32_e32 v151, 0xbfb8aa3b, v123
	v_exp_f32_e32 v150, v150
	v_exp_f32_e32 v151, v151
	v_rcp_f32_e32 v126, v126
	v_rcp_f32_e32 v127, v127
	v_add_f32_e32 v150, 1.0, v150
	v_add_f32_e32 v151, 1.0, v151
	v_rcp_f32_e32 v150, v150
	v_rcp_f32_e32 v151, v151
	v_pk_mul_f32 v[120:121], v[120:121], v[126:127]
	v_pk_mul_f32 v[118:119], v[124:125], v[118:119]
	v_pk_mul_f32 v[120:121], v[120:121], v[112:113]
	v_pk_mul_f32 v[112:113], v[122:123], v[150:151]
	s_mov_b32 s46, s12
	v_pk_mul_f32 v[122:123], v[112:113], v[114:115]
	v_mul_f32_e32 v115, 0xbfb8aa3b, v108
	v_cvt_pk_bf16_f32 v112, v116, v117
	v_exp_f32_e32 v116, v115
	v_mul_f32_e32 v115, 0xbfb8aa3b, v109
	v_exp_f32_e32 v117, v115
	v_cvt_pk_bf16_f32 v113, v118, v119
	v_cvt_pk_bf16_f32 v114, v120, v121
	v_cvt_pk_bf16_f32 v115, v122, v123
	v_add_f32_e32 v116, 1.0, v116
	v_add_f32_e32 v117, 1.0, v117
	v_mad_i64_i32 v[118:119], s[18:19], v149, s44, v[142:143]
	v_rcp_f32_e32 v116, v116
	v_rcp_f32_e32 v117, v117
	global_store_dwordx4 v[118:119], v[112:115], off
	s_mov_b64 s[20:21], s[16:17]
	v_pk_mul_f32 v[108:109], v[108:109], v[116:117]
	v_mul_f32_e32 v112, 0xbfb8aa3b, v110
	v_mul_f32_e32 v113, 0xbfb8aa3b, v111
	v_exp_f32_e32 v112, v112
	v_exp_f32_e32 v113, v113
	v_pk_mul_f32 v[100:101], v[108:109], v[100:101]
	v_or_b32_e32 v114, 16, v149
	v_add_f32_e32 v108, 1.0, v112
	v_add_f32_e32 v109, 1.0, v113
	v_mul_f32_e32 v112, 0xbfb8aa3b, v104
	v_mul_f32_e32 v113, 0xbfb8aa3b, v105
	v_rcp_f32_e32 v108, v108
	v_rcp_f32_e32 v109, v109
	v_exp_f32_e32 v112, v112
	v_exp_f32_e32 v113, v113
	v_pk_mul_f32 v[108:109], v[110:111], v[108:109]
	v_add_f32_e32 v110, 1.0, v112
	v_add_f32_e32 v111, 1.0, v113
	v_mul_f32_e32 v112, 0xbfb8aa3b, v106
	v_mul_f32_e32 v113, 0xbfb8aa3b, v107
	v_exp_f32_e32 v112, v112
	v_exp_f32_e32 v113, v113
	v_rcp_f32_e32 v110, v110
	v_rcp_f32_e32 v111, v111
; __device__ __forceinline__ void gemm_phase(const bf16_t* __restrict__ A, const bf16_t* __restrict__ Bt, bf16_t* __restrict__ C, int M, int N, int K,
;                                            int ldc, const int EPI, char* smem, const int wid_u) {
;     ...
;             float o[8];
; #pragma unroll
;             for (int n = 0; n < 2; ++n) {
;               const f32x4 a = acc[ai][0][m][n], b = acc[ai][1][m][n];
; #pragma unroll
;               for (int j = 0; j < 4; ++j) o[n * 4 + j] = a[j] * __builtin_amdgcn_rcpf(1.f + __expf(-a[j])) * b[j];
;             }
;             *(uint4*)(C + row * ldc + (bcol >> 1) + wc * 32 + fq * 8) = pack8(o);
	v_add_f32_e32 v112, 1.0, v112
	v_add_f32_e32 v113, 1.0, v113
	v_rcp_f32_e32 v112, v112
	v_rcp_f32_e32 v113, v113
	v_pk_mul_f32 v[104:105], v[104:105], v[110:111]
	v_pk_mul_f32 v[102:103], v[108:109], v[102:103]
	v_pk_mul_f32 v[104:105], v[104:105], v[96:97]
	v_pk_mul_f32 v[96:97], v[106:107], v[112:113]
	s_nop 0
	v_pk_mul_f32 v[106:107], v[96:97], v[98:99]
	v_mul_f32_e32 v99, 0xbfb8aa3b, v92
	v_cvt_pk_bf16_f32 v96, v100, v101
	v_exp_f32_e32 v100, v99
	v_mul_f32_e32 v99, 0xbfb8aa3b, v93
	v_exp_f32_e32 v101, v99
	v_cvt_pk_bf16_f32 v97, v102, v103
	v_cvt_pk_bf16_f32 v98, v104, v105
	v_cvt_pk_bf16_f32 v99, v106, v107
	v_add_f32_e32 v100, 1.0, v100
	v_add_f32_e32 v101, 1.0, v101
	v_mad_i64_i32 v[102:103], s[18:19], v114, s44, v[142:143]
	v_rcp_f32_e32 v100, v100
	v_rcp_f32_e32 v101, v101
	global_store_dwordx4 v[102:103], v[96:99], off
	v_pk_mul_f32 v[92:93], v[92:93], v[100:101]
	s_nop 0
	v_mul_f32_e32 v96, 0xbfb8aa3b, v94
	v_mul_f32_e32 v97, 0xbfb8aa3b, v95
	v_exp_f32_e32 v96, v96
	v_exp_f32_e32 v97, v97
	v_pk_mul_f32 v[84:85], v[92:93], v[84:85]
	v_or_b32_e32 v98, 32, v149
	v_add_f32_e32 v92, 1.0, v96
	v_add_f32_e32 v93, 1.0, v97
	v_mul_f32_e32 v96, 0xbfb8aa3b, v88
	v_mul_f32_e32 v97, 0xbfb8aa3b, v89
	v_rcp_f32_e32 v92, v92
	v_rcp_f32_e32 v93, v93
	v_exp_f32_e32 v96, v96
	v_exp_f32_e32 v97, v97
	v_pk_mul_f32 v[92:93], v[94:95], v[92:93]
	v_add_f32_e32 v94, 1.0, v96
	v_add_f32_e32 v95, 1.0, v97
	v_mul_f32_e32 v96, 0xbfb8aa3b, v90
	v_mul_f32_e32 v97, 0xbfb8aa3b, v91
	v_exp_f32_e32 v96, v96
	v_exp_f32_e32 v97, v97
	v_rcp_f32_e32 v94, v94
	v_rcp_f32_e32 v95, v95
	v_add_f32_e32 v96, 1.0, v96
	v_add_f32_e32 v97, 1.0, v97
	v_rcp_f32_e32 v96, v96
	v_rcp_f32_e32 v97, v97
	v_pk_mul_f32 v[88:89], v[88:89], v[94:95]
	v_pk_mul_f32 v[86:87], v[92:93], v[86:87]
	v_pk_mul_f32 v[88:89], v[88:89], v[80:81]
	v_pk_mul_f32 v[80:81], v[90:91], v[96:97]
	s_nop 0
	v_pk_mul_f32 v[90:91], v[80:81], v[82:83]
	v_mul_f32_e32 v83, 0xbfb8aa3b, v76
	v_cvt_pk_bf16_f32 v80, v84, v85
	v_exp_f32_e32 v84, v83
	v_mul_f32_e32 v83, 0xbfb8aa3b, v77
	v_exp_f32_e32 v85, v83
	v_cvt_pk_bf16_f32 v81, v86, v87
	v_cvt_pk_bf16_f32 v82, v88, v89
	v_cvt_pk_bf16_f32 v83, v90, v91
	v_add_f32_e32 v84, 1.0, v84
	v_add_f32_e32 v85, 1.0, v85
	v_mad_i64_i32 v[86:87], s[18:19], v98, s44, v[142:143]
	v_rcp_f32_e32 v84, v84
	v_rcp_f32_e32 v85, v85
	global_store_dwordx4 v[86:87], v[80:83], off
	v_pk_mul_f32 v[76:77], v[76:77], v[84:85]
	s_nop 0
	v_mul_f32_e32 v80, 0xbfb8aa3b, v78
	v_mul_f32_e32 v81, 0xbfb8aa3b, v79
	v_exp_f32_e32 v80, v80
	v_exp_f32_e32 v81, v81
	v_pk_mul_f32 v[68:69], v[76:77], v[68:69]
	v_or_b32_e32 v82, 48, v149
	v_add_f32_e32 v76, 1.0, v80
	v_add_f32_e32 v77, 1.0, v81
	v_mul_f32_e32 v80, 0xbfb8aa3b, v72
	v_mul_f32_e32 v81, 0xbfb8aa3b, v73
	v_rcp_f32_e32 v76, v76
	v_rcp_f32_e32 v77, v77
	v_exp_f32_e32 v80, v80
	v_exp_f32_e32 v81, v81
	v_pk_mul_f32 v[76:77], v[78:79], v[76:77]
	v_add_f32_e32 v78, 1.0, v80
	v_add_f32_e32 v79, 1.0, v81
	v_mul_f32_e32 v80, 0xbfb8aa3b, v74
	v_mul_f32_e32 v81, 0xbfb8aa3b, v75
	v_exp_f32_e32 v80, v80
	v_exp_f32_e32 v81, v81
	v_rcp_f32_e32 v78, v78
	v_rcp_f32_e32 v79, v79
	v_add_f32_e32 v80, 1.0, v80
	v_add_f32_e32 v81, 1.0, v81
	v_rcp_f32_e32 v80, v80
	v_rcp_f32_e32 v81, v81
	v_pk_mul_f32 v[72:73], v[72:73], v[78:79]
	v_pk_mul_f32 v[70:71], v[76:77], v[70:71]
	v_pk_mul_f32 v[72:73], v[72:73], v[64:65]
	v_pk_mul_f32 v[64:65], v[74:75], v[80:81]
	s_nop 0
	v_pk_mul_f32 v[74:75], v[64:65], v[66:67]
	v_mul_f32_e32 v67, 0xbfb8aa3b, v60
	v_cvt_pk_bf16_f32 v64, v68, v69
	v_exp_f32_e32 v68, v67
	v_mul_f32_e32 v67, 0xbfb8aa3b, v61
	v_exp_f32_e32 v69, v67
	v_cvt_pk_bf16_f32 v65, v70, v71
	v_cvt_pk_bf16_f32 v66, v72, v73
	v_cvt_pk_bf16_f32 v67, v74, v75
	v_add_f32_e32 v68, 1.0, v68
	v_add_f32_e32 v69, 1.0, v69
	v_mad_i64_i32 v[70:71], s[18:19], v82, s44, v[142:143]
	v_rcp_f32_e32 v68, v68
	v_rcp_f32_e32 v69, v69
	global_store_dwordx4 v[70:71], v[64:67], off
	v_pk_mul_f32 v[60:61], v[60:61], v[68:69]
	s_nop 0
	v_mul_f32_e32 v64, 0xbfb8aa3b, v62
	v_mul_f32_e32 v65, 0xbfb8aa3b, v63
	v_exp_f32_e32 v64, v64
	v_exp_f32_e32 v65, v65
	v_pk_mul_f32 v[52:53], v[60:61], v[52:53]
	v_add_u32_e32 v66, 0x80, v149
	v_add_f32_e32 v60, 1.0, v64
	v_add_f32_e32 v61, 1.0, v65
	v_mul_f32_e32 v64, 0xbfb8aa3b, v56
	v_mul_f32_e32 v65, 0xbfb8aa3b, v57
	v_rcp_f32_e32 v60, v60
	v_rcp_f32_e32 v61, v61
	v_exp_f32_e32 v64, v64
	v_exp_f32_e32 v65, v65
	v_pk_mul_f32 v[60:61], v[62:63], v[60:61]
	v_add_f32_e32 v62, 1.0, v64
	v_add_f32_e32 v63, 1.0, v65
	v_mul_f32_e32 v64, 0xbfb8aa3b, v58
	v_mul_f32_e32 v65, 0xbfb8aa3b, v59
	v_exp_f32_e32 v64, v64
	v_exp_f32_e32 v65, v65
	v_rcp_f32_e32 v62, v62
	v_rcp_f32_e32 v63, v63
	v_add_f32_e32 v64, 1.0, v64
	v_add_f32_e32 v65, 1.0, v65
	v_rcp_f32_e32 v64, v64
	v_rcp_f32_e32 v65, v65
	v_pk_mul_f32 v[56:57], v[56:57], v[62:63]
	v_pk_mul_f32 v[54:55], v[60:61], v[54:55]
	v_pk_mul_f32 v[56:57], v[56:57], v[48:49]
	v_pk_mul_f32 v[48:49], v[58:59], v[64:65]
	s_nop 0
; #define WAIT_V(n) asm volatile("s_waitcnt vmcnt(" #n ")" ::: "memory")
; #define BAR __builtin_amdgcn_s_barrier()
; __device__ __forceinline__ void gemm_phase(const bf16_t* __restrict__ A, const bf16_t* __restrict__ Bt, bf16_t* __restrict__ C, int M, int N, int K,
;                                            int ldc, const int EPI, char* smem, const int wid_u) {
;     ...
;             float o[8];
; #pragma unroll
;             for (int n = 0; n < 2; ++n) {
;               const f32x4 a = acc[ai][0][m][n], b = acc[ai][1][m][n];
; #pragma unroll
;               for (int j = 0; j < 4; ++j) o[n * 4 + j] = a[j] * __builtin_amdgcn_rcpf(1.f + __expf(-a[j])) * b[j];
;             }
;             *(uint4*)(C + row * ldc + (bcol >> 1) + wc * 32 + fq * 8) = pack8(o);
;           }
;         }
;     }
;     if (!has_next) break;
; #pragma unroll
;     for (int a = 0; a < 2; ++a)
; #pragma unroll
;       for (int b = 0; b < 2; ++b)
; #pragma unroll
;         for (int m = 0; m < 4; ++m)
; #pragma unroll
;           for (int n = 0; n < 2; ++n) acc[a][b][m][n] = (f32x4){0.f, 0.f, 0.f, 0.f};
;     pm = npm; pn = npn; cA = nA; cB = nB; ++ui;
;   }
;   WAIT_V(0);
;   if (wr == 0) BAR;
	v_pk_mul_f32 v[58:59], v[48:49], v[50:51]
	v_mul_f32_e32 v51, 0xbfb8aa3b, v44
	v_cvt_pk_bf16_f32 v48, v52, v53
	v_exp_f32_e32 v52, v51
	v_mul_f32_e32 v51, 0xbfb8aa3b, v45
	v_exp_f32_e32 v53, v51
	v_cvt_pk_bf16_f32 v49, v54, v55
	v_cvt_pk_bf16_f32 v50, v56, v57
	v_cvt_pk_bf16_f32 v51, v58, v59
	v_add_f32_e32 v52, 1.0, v52
	v_add_f32_e32 v53, 1.0, v53
	v_mad_i64_i32 v[54:55], s[18:19], v66, s44, v[142:143]
	v_rcp_f32_e32 v52, v52
	v_rcp_f32_e32 v53, v53
	global_store_dwordx4 v[54:55], v[48:51], off
	v_pk_mul_f32 v[44:45], v[44:45], v[52:53]
	s_nop 0
	v_mul_f32_e32 v48, 0xbfb8aa3b, v46
	v_mul_f32_e32 v49, 0xbfb8aa3b, v47
	v_exp_f32_e32 v48, v48
	v_exp_f32_e32 v49, v49
	v_pk_mul_f32 v[36:37], v[44:45], v[36:37]
	v_add_u32_e32 v50, 0x90, v149
	v_add_f32_e32 v44, 1.0, v48
	v_add_f32_e32 v45, 1.0, v49
	v_mul_f32_e32 v48, 0xbfb8aa3b, v40
	v_mul_f32_e32 v49, 0xbfb8aa3b, v41
	v_rcp_f32_e32 v44, v44
	v_rcp_f32_e32 v45, v45
	v_exp_f32_e32 v48, v48
	v_exp_f32_e32 v49, v49
	v_pk_mul_f32 v[44:45], v[46:47], v[44:45]
	v_add_f32_e32 v46, 1.0, v48
	v_add_f32_e32 v47, 1.0, v49
	v_mul_f32_e32 v48, 0xbfb8aa3b, v42
	v_mul_f32_e32 v49, 0xbfb8aa3b, v43
	v_exp_f32_e32 v48, v48
	v_exp_f32_e32 v49, v49
	v_rcp_f32_e32 v46, v46
	v_rcp_f32_e32 v47, v47
	v_add_f32_e32 v48, 1.0, v48
	v_add_f32_e32 v49, 1.0, v49
	v_rcp_f32_e32 v48, v48
	v_rcp_f32_e32 v49, v49
	v_pk_mul_f32 v[40:41], v[40:41], v[46:47]
	v_pk_mul_f32 v[38:39], v[44:45], v[38:39]
	v_pk_mul_f32 v[40:41], v[40:41], v[32:33]
	v_pk_mul_f32 v[32:33], v[42:43], v[48:49]
	s_nop 0
	v_pk_mul_f32 v[42:43], v[32:33], v[34:35]
	v_mul_f32_e32 v35, 0xbfb8aa3b, v28
	v_cvt_pk_bf16_f32 v32, v36, v37
	v_exp_f32_e32 v36, v35
	v_mul_f32_e32 v35, 0xbfb8aa3b, v29
	v_exp_f32_e32 v37, v35
	v_cvt_pk_bf16_f32 v33, v38, v39
	v_cvt_pk_bf16_f32 v34, v40, v41
	v_cvt_pk_bf16_f32 v35, v42, v43
	v_add_f32_e32 v36, 1.0, v36
	v_add_f32_e32 v37, 1.0, v37
	v_mad_i64_i32 v[38:39], s[18:19], v50, s44, v[142:143]
	v_rcp_f32_e32 v36, v36
	v_rcp_f32_e32 v37, v37
	global_store_dwordx4 v[38:39], v[32:35], off
	v_pk_mul_f32 v[28:29], v[28:29], v[36:37]
	s_nop 0
	v_mul_f32_e32 v32, 0xbfb8aa3b, v30
	v_mul_f32_e32 v33, 0xbfb8aa3b, v31
	v_exp_f32_e32 v32, v32
	v_exp_f32_e32 v33, v33
	v_pk_mul_f32 v[20:21], v[28:29], v[20:21]
	v_add_u32_e32 v34, 0xa0, v149
	v_add_f32_e32 v28, 1.0, v32
	v_add_f32_e32 v29, 1.0, v33
	v_mul_f32_e32 v32, 0xbfb8aa3b, v24
	v_mul_f32_e32 v33, 0xbfb8aa3b, v25
	v_rcp_f32_e32 v28, v28
	v_rcp_f32_e32 v29, v29
	v_exp_f32_e32 v32, v32
	v_exp_f32_e32 v33, v33
	v_pk_mul_f32 v[28:29], v[30:31], v[28:29]
	v_add_f32_e32 v30, 1.0, v32
	v_add_f32_e32 v31, 1.0, v33
	v_mul_f32_e32 v32, 0xbfb8aa3b, v26
	v_mul_f32_e32 v33, 0xbfb8aa3b, v27
	v_exp_f32_e32 v32, v32
	v_exp_f32_e32 v33, v33
	v_rcp_f32_e32 v30, v30
	v_rcp_f32_e32 v31, v31
	v_add_f32_e32 v32, 1.0, v32
	v_add_f32_e32 v33, 1.0, v33
	v_rcp_f32_e32 v32, v32
	v_rcp_f32_e32 v33, v33
	v_pk_mul_f32 v[24:25], v[24:25], v[30:31]
	v_pk_mul_f32 v[22:23], v[28:29], v[22:23]
	v_pk_mul_f32 v[24:25], v[24:25], v[16:17]
	v_pk_mul_f32 v[16:17], v[26:27], v[32:33]
	s_nop 0
	v_pk_mul_f32 v[26:27], v[16:17], v[18:19]
	v_mul_f32_e32 v19, 0xbfb8aa3b, v12
	v_cvt_pk_bf16_f32 v16, v20, v21
	v_exp_f32_e32 v20, v19
	v_mul_f32_e32 v19, 0xbfb8aa3b, v13
	v_exp_f32_e32 v21, v19
	v_cvt_pk_bf16_f32 v17, v22, v23
	v_cvt_pk_bf16_f32 v18, v24, v25
	v_cvt_pk_bf16_f32 v19, v26, v27
	v_add_f32_e32 v20, 1.0, v20
	v_add_f32_e32 v21, 1.0, v21
	v_mad_i64_i32 v[22:23], s[18:19], v34, s44, v[142:143]
	v_rcp_f32_e32 v20, v20
	v_rcp_f32_e32 v21, v21
	global_store_dwordx4 v[22:23], v[16:19], off
	v_pk_mul_f32 v[12:13], v[12:13], v[20:21]
	s_nop 0
	v_mul_f32_e32 v16, 0xbfb8aa3b, v14
	v_mul_f32_e32 v17, 0xbfb8aa3b, v15
	v_exp_f32_e32 v16, v16
	v_exp_f32_e32 v17, v17
	v_pk_mul_f32 v[4:5], v[12:13], v[4:5]
	v_add_u32_e32 v18, 0xb0, v149
	v_add_f32_e32 v12, 1.0, v16
	v_add_f32_e32 v13, 1.0, v17
	v_mul_f32_e32 v16, 0xbfb8aa3b, v8
	v_mul_f32_e32 v17, 0xbfb8aa3b, v9
	v_rcp_f32_e32 v12, v12
	v_rcp_f32_e32 v13, v13
	v_exp_f32_e32 v16, v16
	v_exp_f32_e32 v17, v17
	v_pk_mul_f32 v[12:13], v[14:15], v[12:13]
	v_add_f32_e32 v14, 1.0, v16
	v_add_f32_e32 v15, 1.0, v17
	v_mul_f32_e32 v16, 0xbfb8aa3b, v10
	v_mul_f32_e32 v17, 0xbfb8aa3b, v11
	v_exp_f32_e32 v16, v16
	v_exp_f32_e32 v17, v17
	v_rcp_f32_e32 v14, v14
	v_rcp_f32_e32 v15, v15
	v_add_f32_e32 v16, 1.0, v16
	v_add_f32_e32 v17, 1.0, v17
	v_rcp_f32_e32 v16, v16
	v_rcp_f32_e32 v17, v17
	v_pk_mul_f32 v[8:9], v[8:9], v[14:15]
	v_pk_mul_f32 v[6:7], v[12:13], v[6:7]
	v_pk_mul_f32 v[8:9], v[8:9], v[0:1]
	v_pk_mul_f32 v[0:1], v[10:11], v[16:17]
	s_nop 0
	v_pk_mul_f32 v[10:11], v[0:1], v[2:3]
	v_cvt_pk_bf16_f32 v0, v4, v5
	v_mad_i64_i32 v[4:5], s[18:19], v18, s44, v[142:143]
	v_cvt_pk_bf16_f32 v1, v6, v7
	v_cvt_pk_bf16_f32 v2, v8, v9
	v_cvt_pk_bf16_f32 v3, v10, v11
	s_mov_b64 s[18:19], s[14:15]
	global_store_dwordx4 v[4:5], v[0:3], off
	s_cbranch_vccz .LBB0_1023
	s_waitcnt vmcnt(0)
	s_cmpk_gt_u32 s26, 0xff
	s_cbranch_scc1 .LBB0_1030
	s_barrier
